# in-proj quarter units also run the lean one-barrier-per-K-tile loop; the |q|,|k| maxima now include the quarter-unit tiles
# baseline (speedup 1.0000x reference)
;     DI void operator()(const f32x4 (&acc)[2][2][4][2], const pg8::Unit& u, int wr, int wc, int fr, int fq) const {
;         const Params& p = *pp;
;         const int colt = u.pn * 256, seg = colt >> 9;
;         const bool isq = (seg == 0) || (seg == 4), isg = (seg == 3) || (seg == 7), iskv = !isq && !isg;
;         const int oi = seg == 1 ? 0 : seg == 2 ? 1 : seg == 5 ? 2 : 3;
; #pragma unroll
;         for (int ai = 0; ai < 2; ++ai)
; #pragma unroll
;             for (int m = 0; m < 4; ++m) {
;                 const int R = u.pm * 256 + ai * 128 + wr * 64 + m * 16 + fr;
;                 float* fo = nullptr;
;                 if (iskv) {
;                     if (R < ROWS_P) { const int b = R / LPAD, t = R - b * LPAD; if (t < LP) fo = p.out + O_PAK + oi * PKV_SZ + ((size_t)b * LP + t) * 512 - seg * 512; }
;                     else fo = p.out + O_SAK + oi * SKV_SZ + (size_t)(R - ROWS_P) * 512 - seg * 512;
;                 }
;                 bf16_t* uo = p.u + (size_t)R * NU;
; #pragma unroll
;                 for (int bj = 0; bj < 2; ++bj) {
;                     const int n = colt + bj * 128 + wc * 32 + 8 * fq;
;                     f32x4 v0 = acc[ai][bj][m][0], v1 = acc[ai][bj][m][1];
;                     if (fo) { *(f32x4*)(fo + n) = v0; *(f32x4*)(fo + n + 4) = v1; }
;                     if (isq) { v0 = v0 * QSCALE; v1 = v1 * QSCALE; }
.LBB0_141:
	s_sub_i32 s1, s0, 8
	s_cmp_lt_u32 s1, 4
	s_cbranch_scc0 .Lnrm_skip
	s_nop 7
	s_nop 7
	v_mbcnt_lo_u32_b32 v186, -1, 0
	v_mbcnt_hi_u32_b32 v186, -1, v186
	v_xor_b32_e32 v187, 16, v186
	v_lshlrev_b32_e32 v187, 2, v187
	v_xor_b32_e32 v188, 32, v186
	v_lshlrev_b32_e32 v188, 2, v188
	v_mul_f32_e32 v190, v122, v122
	v_fmac_f32_e32 v190, v123, v123
	v_fmac_f32_e32 v190, v124, v124
	v_fmac_f32_e32 v190, v125, v125
	v_fmac_f32_e32 v190, v126, v126
	v_fmac_f32_e32 v190, v127, v127
	v_fmac_f32_e32 v190, v128, v128
	v_fmac_f32_e32 v190, v129, v129
	v_mul_f32_e32 v191, v114, v114
	v_fmac_f32_e32 v191, v115, v115
	v_fmac_f32_e32 v191, v116, v116
	v_fmac_f32_e32 v191, v117, v117
	v_fmac_f32_e32 v191, v118, v118
	v_fmac_f32_e32 v191, v119, v119
	v_fmac_f32_e32 v191, v120, v120
	v_fmac_f32_e32 v191, v121, v121
	v_mul_f32_e32 v192, v106, v106
	v_fmac_f32_e32 v192, v107, v107
	v_fmac_f32_e32 v192, v108, v108
	v_fmac_f32_e32 v192, v109, v109
	v_fmac_f32_e32 v192, v110, v110
	v_fmac_f32_e32 v192, v111, v111
	v_fmac_f32_e32 v192, v112, v112
	v_fmac_f32_e32 v192, v113, v113
	v_mul_f32_e32 v193, v98, v98
	v_fmac_f32_e32 v193, v99, v99
	v_fmac_f32_e32 v193, v100, v100
	v_fmac_f32_e32 v193, v101, v101
	v_fmac_f32_e32 v193, v102, v102
	v_fmac_f32_e32 v193, v103, v103
	v_fmac_f32_e32 v193, v104, v104
	v_fmac_f32_e32 v193, v105, v105
	v_mul_f32_e32 v194, v90, v90
	v_fmac_f32_e32 v194, v91, v91
	v_fmac_f32_e32 v194, v92, v92
	v_fmac_f32_e32 v194, v93, v93
	v_fmac_f32_e32 v194, v94, v94
	v_fmac_f32_e32 v194, v95, v95
	v_fmac_f32_e32 v194, v96, v96
	v_fmac_f32_e32 v194, v97, v97
	v_mul_f32_e32 v195, v82, v82
	v_fmac_f32_e32 v195, v83, v83
	v_fmac_f32_e32 v195, v84, v84
	v_fmac_f32_e32 v195, v85, v85
	v_fmac_f32_e32 v195, v86, v86
	v_fmac_f32_e32 v195, v87, v87
	v_fmac_f32_e32 v195, v88, v88
	v_fmac_f32_e32 v195, v89, v89
	v_mul_f32_e32 v196, v74, v74
	v_fmac_f32_e32 v196, v75, v75
	v_fmac_f32_e32 v196, v76, v76
	v_fmac_f32_e32 v196, v77, v77
	v_fmac_f32_e32 v196, v78, v78
	v_fmac_f32_e32 v196, v79, v79
	v_fmac_f32_e32 v196, v80, v80
	v_fmac_f32_e32 v196, v81, v81
	v_mul_f32_e32 v197, v66, v66
	v_fmac_f32_e32 v197, v67, v67
	v_fmac_f32_e32 v197, v68, v68
	v_fmac_f32_e32 v197, v69, v69
	v_fmac_f32_e32 v197, v70, v70
	v_fmac_f32_e32 v197, v71, v71
	v_fmac_f32_e32 v197, v72, v72
	v_fmac_f32_e32 v197, v73, v73
	v_mul_f32_e32 v198, v58, v58
	v_fmac_f32_e32 v198, v59, v59
	v_fmac_f32_e32 v198, v60, v60
	v_fmac_f32_e32 v198, v61, v61
	v_fmac_f32_e32 v198, v62, v62
	v_fmac_f32_e32 v198, v63, v63
	v_fmac_f32_e32 v198, v64, v64
	v_fmac_f32_e32 v198, v65, v65
	v_mul_f32_e32 v199, v50, v50
	v_fmac_f32_e32 v199, v51, v51
	v_fmac_f32_e32 v199, v52, v52
	v_fmac_f32_e32 v199, v53, v53
	v_fmac_f32_e32 v199, v54, v54
	v_fmac_f32_e32 v199, v55, v55
	v_fmac_f32_e32 v199, v56, v56
	v_fmac_f32_e32 v199, v57, v57
	v_mul_f32_e32 v200, v42, v42
	v_fmac_f32_e32 v200, v43, v43
	v_fmac_f32_e32 v200, v44, v44
	v_fmac_f32_e32 v200, v45, v45
	v_fmac_f32_e32 v200, v46, v46
	v_fmac_f32_e32 v200, v47, v47
	v_fmac_f32_e32 v200, v48, v48
	v_fmac_f32_e32 v200, v49, v49
	v_mul_f32_e32 v201, v34, v34
	v_fmac_f32_e32 v201, v35, v35
	v_fmac_f32_e32 v201, v36, v36
	v_fmac_f32_e32 v201, v37, v37
	v_fmac_f32_e32 v201, v38, v38
	v_fmac_f32_e32 v201, v39, v39
	v_fmac_f32_e32 v201, v40, v40
	v_fmac_f32_e32 v201, v41, v41
	v_mul_f32_e32 v202, v26, v26
	v_fmac_f32_e32 v202, v27, v27
	v_fmac_f32_e32 v202, v28, v28
	v_fmac_f32_e32 v202, v29, v29
	v_fmac_f32_e32 v202, v30, v30
	v_fmac_f32_e32 v202, v31, v31
	v_fmac_f32_e32 v202, v32, v32
	v_fmac_f32_e32 v202, v33, v33
	v_mul_f32_e32 v203, v18, v18
	v_fmac_f32_e32 v203, v19, v19
	v_fmac_f32_e32 v203, v20, v20
	v_fmac_f32_e32 v203, v21, v21
	v_fmac_f32_e32 v203, v22, v22
	v_fmac_f32_e32 v203, v23, v23
	v_fmac_f32_e32 v203, v24, v24
	v_fmac_f32_e32 v203, v25, v25
	v_mul_f32_e32 v204, v10, v10
	v_fmac_f32_e32 v204, v11, v11
	v_fmac_f32_e32 v204, v12, v12
	v_fmac_f32_e32 v204, v13, v13
	v_fmac_f32_e32 v204, v14, v14
	v_fmac_f32_e32 v204, v15, v15
	v_fmac_f32_e32 v204, v16, v16
	v_fmac_f32_e32 v204, v17, v17
	v_mul_f32_e32 v205, v2, v2
	v_fmac_f32_e32 v205, v3, v3
	v_fmac_f32_e32 v205, v4, v4
	v_fmac_f32_e32 v205, v5, v5
	v_fmac_f32_e32 v205, v6, v6
	v_fmac_f32_e32 v205, v7, v7
	v_fmac_f32_e32 v205, v8, v8
	v_fmac_f32_e32 v205, v9, v9
	s_and_b64 s[8:9], s[12:13], exec
	s_cselect_b32 s7, 64, 0
	s_lshl_b32 s1, s6, 8
	s_add_i32 s7, s7, s1
	s_add_i32 s8, s7, 0
	s_mul_hi_u32 s9, s8, 0x7e07e07f
	s_lshr_b32 s9, s9, 11
	s_mul_i32 s9, s9, 0x1040
	s_sub_i32 s9, s8, s9
	s_cmp_lt_u32 s9, 0x1010
	s_cselect_b32 s9, 1, 0
	s_cmp_ge_u32 s6, 65
	s_cselect_b32 s9, 1, s9
	s_cmp_lg_u32 s9, 0
	s_cbranch_scc1 .Lnrm_ok_0
	v_mov_b32_e32 v190, 0
	v_mov_b32_e32 v191, 0

; DI unsigned pk2(float a, float b) { f32x2 v = {a, b}; bf16x2v r = __builtin_convertvector(v, bf16x2v); return __builtin_bit_cast(unsigned, r); }
; #define PG8_BAR __builtin_amdgcn_s_barrier()
; template <class Epi, class Sched, bool ALIGN_EPI = false, bool SP2 = false>
; __device__ __forceinline__ void gemm_phase(PG8_LAS unsigned char* lds, const Gemm g, const Sched& S, const Epi& E) {
;     ...
;         if constexpr (ALIGN_EPI) { if (wr == 0) PG8_BAR; }
;         if constexpr (!Epi::AFTER_DRAIN) { E(acc, cur, wr, wc, fr, fq); S.done(cur); }
;         if (!has_next) break;
; #pragma unroll
;         for (int a = 0; a < 2; ++a)
; #pragma unroll
;             for (int b = 0; b < 2; ++b)
; #pragma unroll
;                 for (int m = 0; m < 4; ++m)
; #pragma unroll
;                     for (int n = 0; n < 2; ++n) acc[a][b][m][n] = (f32x4){0.f, 0.f, 0.f, 0.f};
;         cur = nxt; cA = nA; cB = nB; ++ui;
;         if constexpr (ALIGN_EPI) { if (wr == 1) PG8_BAR; }
;     DI void operator()(const f32x4 (&acc)[2][2][4][2], const pg8::Unit& u, int wr, int wc, int fr, int fq) const {
;     ...
;                     *(u32x4*)(uo + n) = (u32x4){pk2(v0[0], v0[1]), pk2(v0[2], v0[3]), pk2(v1[0], v1[1]), pk2(v1[2], v1[3])};
.LBB0_341:
	v_cvt_pk_bf16_f32 v2, v10, v11
	v_cvt_pk_bf16_f32 v3, v12, v13
	v_cvt_pk_bf16_f32 v4, v14, v15
	v_cvt_pk_bf16_f32 v5, v16, v17
	s_andn2_b64 vcc, exec, s[4:5]
	s_mov_b64 s[0:1], -1
	global_store_dwordx4 v[18:19], v[2:5], off offset:256
	s_cbranch_vccnz .LBB0_134
	s_cmp_lg_u32 s101, 15
	s_cbranch_scc1 .LBB0_133
	s_andn2_b64 vcc, exec, s[12:13]
	s_cbranch_vccnz .LBB0_133
	s_barrier
	s_branch .LBB0_133

; #define PG8_STAGE(bufoff, gbase, voff) do { _Pragma("unroll") for (int _i = 0; _i < 2; ++_i) \
;         __builtin_amdgcn_global_load_lds((const unsigned*)((const char*)(gbase) + (voff)[_i]), (PG8_LAS unsigned*)(lds + (bufoff) + ldsw + _i * 8192), 16, 0, 0); } while (0)
; #define PG8_LDA(dst, b, h) do { _Pragma("unroll") for (int m = 0; m < 4; ++m) _Pragma("unroll") for (int k = 0; k < 2; ++k) dst[m][k] = *(const PG8_LAS bf16x8*)(lds + PG8_SA(b, h) + aoff + m * 2048 + k * 1024); } while (0)
; #define PG8_LDB(dst, b, h) do { _Pragma("unroll") for (int n = 0; n < 2; ++n) _Pragma("unroll") for (int k = 0; k < 2; ++k) dst[n][k] = *(const PG8_LAS bf16x8*)(lds + PG8_SB(b, h) + boff + n * 2048 + k * 1024); } while (0)
; template <class Epi, class Sched, bool ALIGN_EPI = false, bool SP2 = false>
; __device__ __forceinline__ void gemm_phase(PG8_LAS unsigned char* lds, const Gemm g, const Sched& S, const Epi& E) {
;     ...
;         for (int t = 0; t < nt; t += 2) {
;             const bool last = (t == nt - 2);
;             const char* a1 = cA + (size_t)(t + 1) * kstep;
;             const char* a2 = last ? nA : cA + (size_t)(t + 2) * kstep; const char* b2 = last ? nB : cB + (size_t)(t + 2) * kstep;
;             const char* a3 = a2 + kstep; const char* b3 = b2 + kstep;
;             if (last && has_next) S.a_ready(nxt);
;             if constexpr (SP2) {
;             PG8_LDB(B0, 0, 0); PG8_LDB(B1, 0, 1); PG8_SCHED; PG8_LDA(At, 0, 0); PG8_STAGE(PG8_SA(1, 1), a1 + hstep, voffA);
;             PG8_WAIT_V(8); PG8_WAIT_L(0); PG8_BAR; PG8_MMA(0, 0, At, B0); PG8_MMA(0, 1, At, B1); PG8_BAR; PG8_SCHED;
;             PG8_LDA(At, 0, 1); PG8_STAGE(PG8_SB(0, 0), b2, voffB); PG8_STAGE(PG8_SB(0, 1), b2 + hstep, voffB); PG8_STAGE(PG8_SA(0, 0), a2, voffA);
;             PG8_WAIT_V(8); PG8_WAIT_L(0); PG8_BAR; PG8_MMA(1, 0, At, B0); PG8_MMA(1, 1, At, B1); PG8_BAR; PG8_SCHED;
;             PG8_LDB(B0, 1, 0); PG8_LDB(B1, 1, 1); PG8_SCHED; PG8_LDA(At, 1, 0); PG8_STAGE(PG8_SA(0, 1), a2 + hstep, voffA);
;             PG8_WAIT_V(8); PG8_WAIT_L(0); PG8_BAR; PG8_MMA(0, 0, At, B0); PG8_MMA(0, 1, At, B1); PG8_BAR; PG8_SCHED;
;             PG8_LDA(At, 1, 1); PG8_STAGE(PG8_SB(1, 0), b3, voffB); PG8_STAGE(PG8_SB(1, 1), b3 + hstep, voffB); PG8_STAGE(PG8_SA(1, 0), a3, voffA);
;             PG8_WAIT_V(8); PG8_WAIT_L(0); PG8_BAR; PG8_MMA(1, 0, At, B0); PG8_MMA(1, 1, At, B1); PG8_BAR; PG8_SCHED;
.Lp1q_tail:
	s_andn2_b64 vcc, exec, s[4:5]
	s_mov_b64 s[0:1], -1
	s_cbranch_vccnz .LBB0_134
	s_andn2_b64 vcc, exec, s[12:13]
	s_cbranch_vccnz .LBB0_133
	s_barrier
	s_branch .LBB0_133
.Lp1q_lean:
	s_bitcmp1_b32 s100, 0
	s_cbranch_scc1 .Lp1q_lean_q0
	s_bitcmp1_b32 s100, 1
	s_cbranch_scc1 .Lp1q_lean_q1
	s_bitcmp1_b32 s100, 2
	s_cbranch_scc1 .Lp1q_lean_q2
	s_branch .Lp1q_lean_q3
.Lp1q_lean_q0:
	s_mov_b32 s34, s6
	s_mov_b32 s35, 0
	s_lshl_b64 s[34:35], s[34:35], 19
	s_add_u32 s34, s34, s66
	s_addc_u32 s35, s35, s67
	s_add_u32 s34, s34, 0x80
	s_addc_u32 s35, s35, 0
	s_mov_b32 s38, s0
	s_mov_b32 s39, 0
	s_lshl_b64 s[38:39], s[38:39], 19
	s_add_u32 s38, s38, s62
	s_addc_u32 s39, s39, s63
	s_add_u32 s38, s38, 0x80
	s_addc_u32 s39, s39, 0
	s_waitcnt vmcnt(0) lgkmcnt(0)
	s_barrier
	s_add_u32 s34, s34, 0x80
	s_addc_u32 s35, s35, 0
	s_add_u32 s38, s38, 0x80
	s_addc_u32 s39, s39, 0
	s_add_i32 m0, s42, 0x4000
	s_nop 0
	global_load_lds_dwordx4 v140, s[34:35]
	s_add_i32 m0, s42, 0x6000
	s_nop 0
	global_load_lds_dwordx4 v144, s[34:35]
	s_add_i32 m0, s42, 0x14000
	s_nop 0
	global_load_lds_dwordx4 v142, s[38:39]
	s_add_i32 m0, s42, 0x16000
	s_nop 0
	global_load_lds_dwordx4 v146, s[38:39]
	s_add_u32 s34, s34, 0x80
	s_addc_u32 s35, s35, 0
	s_add_u32 s38, s38, 0x80
	s_addc_u32 s39, s39, 0
	s_add_i32 m0, s42, 0xc000
	s_nop 0
	global_load_lds_dwordx4 v140, s[34:35]
	s_add_i32 m0, s42, 0xe000
	s_nop 0
	global_load_lds_dwordx4 v144, s[34:35]
	s_add_i32 m0, s42, 0x1c000
	s_nop 0
	global_load_lds_dwordx4 v142, s[38:39]
	s_add_i32 m0, s42, 0x1e000
	s_nop 0
	global_load_lds_dwordx4 v146, s[38:39]
	ds_read_b128 v[130:133], v180
	ds_read_b128 v[134:137], v180 offset:1024
	ds_read_b128 v[158:161], v180 offset:2048
	ds_read_b128 v[186:189], v180 offset:3072
	ds_read_b128 v[206:209], v182
	ds_read_b128 v[210:213], v182 offset:1024
	ds_read_b128 v[214:217], v182 offset:2048
	ds_read_b128 v[218:221], v182 offset:3072
	ds_read_b128 v[222:225], v182 offset:4096
	ds_read_b128 v[226:229], v182 offset:5120
	ds_read_b128 v[230:233], v182 offset:6144
	ds_read_b128 v[234:237], v182 offset:7168
	s_waitcnt lgkmcnt(0)
	v_mfma_f32_16x16x32_bf16 v[126:129], v[130:133], v[206:209], v[126:129]
	v_mfma_f32_16x16x32_bf16 v[122:125], v[158:161], v[206:209], v[122:125]
	v_mfma_f32_16x16x32_bf16 v[110:113], v[130:133], v[214:217], v[110:113]
	v_mfma_f32_16x16x32_bf16 v[106:109], v[158:161], v[214:217], v[106:109]
	v_mfma_f32_16x16x32_bf16 v[94:97], v[130:133], v[222:225], v[94:97]
	v_mfma_f32_16x16x32_bf16 v[90:93], v[158:161], v[222:225], v[90:93]
	v_mfma_f32_16x16x32_bf16 v[78:81], v[130:133], v[230:233], v[78:81]
	v_mfma_f32_16x16x32_bf16 v[74:77], v[158:161], v[230:233], v[74:77]
	v_mfma_f32_16x16x32_bf16 v[126:129], v[134:137], v[210:213], v[126:129]
	v_mfma_f32_16x16x32_bf16 v[122:125], v[186:189], v[210:213], v[122:125]
	v_mfma_f32_16x16x32_bf16 v[110:113], v[134:137], v[218:221], v[110:113]
	v_mfma_f32_16x16x32_bf16 v[106:109], v[186:189], v[218:221], v[106:109]
	v_mfma_f32_16x16x32_bf16 v[94:97], v[134:137], v[226:229], v[94:97]
	v_mfma_f32_16x16x32_bf16 v[90:93], v[186:189], v[226:229], v[90:93]
	v_mfma_f32_16x16x32_bf16 v[78:81], v[134:137], v[234:237], v[78:81]
	v_mfma_f32_16x16x32_bf16 v[74:77], v[186:189], v[234:237], v[74:77]
	s_waitcnt vmcnt(8)
	s_barrier
	ds_read_b128 v[130:133], v183
	ds_read_b128 v[134:137], v183 offset:1024
	ds_read_b128 v[158:161], v183 offset:2048
	ds_read_b128 v[186:189], v183 offset:3072
	ds_read_b128 v[206:209], v182 offset:32768
	ds_read_b128 v[210:213], v182 offset:33792
	ds_read_b128 v[214:217], v182 offset:34816
	ds_read_b128 v[218:221], v182 offset:35840
	ds_read_b128 v[222:225], v182 offset:36864
	ds_read_b128 v[226:229], v182 offset:37888
	ds_read_b128 v[230:233], v182 offset:38912
	ds_read_b128 v[234:237], v182 offset:39936
	s_add_u32 s34, s34, 0x80
	s_addc_u32 s35, s35, 0
	s_add_u32 s38, s38, 0x80
	s_addc_u32 s39, s39, 0
	s_mov_b32 m0, s42
	s_nop 0
	global_load_lds_dwordx4 v140, s[34:35]
	s_add_i32 m0, s42, 0x2000
	s_nop 0
	global_load_lds_dwordx4 v144, s[34:35]
	s_add_i32 m0, s42, 0x10000
	s_nop 0
	global_load_lds_dwordx4 v142, s[38:39]
	s_add_i32 m0, s42, 0x12000
	s_nop 0
	global_load_lds_dwordx4 v146, s[38:39]
	s_waitcnt lgkmcnt(0)
	v_mfma_f32_16x16x32_bf16 v[126:129], v[130:133], v[206:209], v[126:129]
	v_mfma_f32_16x16x32_bf16 v[122:125], v[158:161], v[206:209], v[122:125]
	v_mfma_f32_16x16x32_bf16 v[110:113], v[130:133], v[214:217], v[110:113]
	v_mfma_f32_16x16x32_bf16 v[106:109], v[158:161], v[214:217], v[106:109]
	v_mfma_f32_16x16x32_bf16 v[94:97], v[130:133], v[222:225], v[94:97]
	v_mfma_f32_16x16x32_bf16 v[90:93], v[158:161], v[222:225], v[90:93]
	v_mfma_f32_16x16x32_bf16 v[78:81], v[130:133], v[230:233], v[78:81]
	v_mfma_f32_16x16x32_bf16 v[74:77], v[158:161], v[230:233], v[74:77]
	v_mfma_f32_16x16x32_bf16 v[126:129], v[134:137], v[210:213], v[126:129]
	v_mfma_f32_16x16x32_bf16 v[122:125], v[186:189], v[210:213], v[122:125]
	v_mfma_f32_16x16x32_bf16 v[110:113], v[134:137], v[218:221], v[110:113]
	v_mfma_f32_16x16x32_bf16 v[106:109], v[186:189], v[218:221], v[106:109]
	v_mfma_f32_16x16x32_bf16 v[94:97], v[134:137], v[226:229], v[94:97]
	v_mfma_f32_16x16x32_bf16 v[90:93], v[186:189], v[226:229], v[90:93]
	v_mfma_f32_16x16x32_bf16 v[78:81], v[134:137], v[234:237], v[78:81]
	v_mfma_f32_16x16x32_bf16 v[74:77], v[186:189], v[234:237], v[74:77]
	s_waitcnt vmcnt(8)
	s_barrier
; #define PG8_STAGE(bufoff, gbase, voff) do { _Pragma("unroll") for (int _i = 0; _i < 2; ++_i) \
;         __builtin_amdgcn_global_load_lds((const unsigned*)((const char*)(gbase) + (voff)[_i]), (PG8_LAS unsigned*)(lds + (bufoff) + ldsw + _i * 8192), 16, 0, 0); } while (0)
; #define PG8_LDA(dst, b, h) do { _Pragma("unroll") for (int m = 0; m < 4; ++m) _Pragma("unroll") for (int k = 0; k < 2; ++k) dst[m][k] = *(const PG8_LAS bf16x8*)(lds + PG8_SA(b, h) + aoff + m * 2048 + k * 1024); } while (0)
; #define PG8_LDB(dst, b, h) do { _Pragma("unroll") for (int n = 0; n < 2; ++n) _Pragma("unroll") for (int k = 0; k < 2; ++k) dst[n][k] = *(const PG8_LAS bf16x8*)(lds + PG8_SB(b, h) + boff + n * 2048 + k * 1024); } while (0)
; #define PG8_MMA(ai, bj, At, Bt) do { __builtin_amdgcn_s_setprio(1); _Pragma("unroll") for (int m = 0; m < 4; ++m) _Pragma("unroll") for (int n = 0; n < 2; ++n) _Pragma("unroll") for (int k = 0; k < 2; ++k) \
;         acc[ai][bj][m][n] = __builtin_amdgcn_mfma_f32_16x16x32_bf16(Bt[n][k], At[m][k], acc[ai][bj][m][n], 0, 0, 0); __builtin_amdgcn_s_setprio(0); } while (0)
; #define PG8_WAIT_V(n) asm volatile("s_waitcnt vmcnt(" #n ")" ::: "memory")
; template <class Epi, class Sched, bool ALIGN_EPI = false, bool SP2 = false>
; __device__ __forceinline__ void gemm_phase(PG8_LAS unsigned char* lds, const Gemm g, const Sched& S, const Epi& E) {
;     ...
;             PG8_LDB(B0, 0, 0); PG8_LDB(B1, 0, 1); PG8_SCHED; PG8_LDA(At, 0, 0); PG8_STAGE(PG8_SA(1, 1), a1 + hstep, voffA);
;             PG8_WAIT_V(8); PG8_WAIT_L(0); PG8_BAR; PG8_MMA(0, 0, At, B0); PG8_MMA(0, 1, At, B1); PG8_BAR; PG8_SCHED;
;             PG8_LDA(At, 0, 1); PG8_STAGE(PG8_SB(0, 0), b2, voffB); PG8_STAGE(PG8_SB(0, 1), b2 + hstep, voffB); PG8_STAGE(PG8_SA(0, 0), a2, voffA);
;             PG8_WAIT_V(8); PG8_WAIT_L(0); PG8_BAR; PG8_MMA(1, 0, At, B0); PG8_MMA(1, 1, At, B1); PG8_BAR; PG8_SCHED;
;             PG8_LDB(B0, 1, 0); PG8_LDB(B1, 1, 1); PG8_SCHED; PG8_LDA(At, 1, 0); PG8_STAGE(PG8_SA(0, 1), a2 + hstep, voffA);
;             PG8_WAIT_V(8); PG8_WAIT_L(0); PG8_BAR; PG8_MMA(0, 0, At, B0); PG8_MMA(0, 1, At, B1); PG8_BAR; PG8_SCHED;
;             PG8_LDA(At, 1, 1); PG8_STAGE(PG8_SB(1, 0), b3, voffB); PG8_STAGE(PG8_SB(1, 1), b3 + hstep, voffB); PG8_STAGE(PG8_SA(1, 0), a3, voffA);
;             PG8_WAIT_V(8); PG8_WAIT_L(0); PG8_BAR; PG8_MMA(1, 0, At, B0); PG8_MMA(1, 1, At, B1); PG8_BAR; PG8_SCHED;
	ds_read_b128 v[130:133], v181
	ds_read_b128 v[134:137], v181 offset:1024
	ds_read_b128 v[158:161], v181 offset:2048
	ds_read_b128 v[186:189], v181 offset:3072
	ds_read_b128 v[206:209], v182 offset:16384
	ds_read_b128 v[210:213], v182 offset:17408
	ds_read_b128 v[214:217], v182 offset:18432
	ds_read_b128 v[218:221], v182 offset:19456
	ds_read_b128 v[222:225], v182 offset:20480
	ds_read_b128 v[226:229], v182 offset:21504
	ds_read_b128 v[230:233], v182 offset:22528
	ds_read_b128 v[234:237], v182 offset:23552
	s_add_u32 s34, s34, 0x80
	s_addc_u32 s35, s35, 0
	s_add_u32 s38, s38, 0x80
	s_addc_u32 s39, s39, 0
	s_add_i32 m0, s42, 0x8000
	s_nop 0
	global_load_lds_dwordx4 v140, s[34:35]
	s_add_i32 m0, s42, 0xa000
	s_nop 0
	global_load_lds_dwordx4 v144, s[34:35]
	s_add_i32 m0, s42, 0x18000
	s_nop 0
	global_load_lds_dwordx4 v142, s[38:39]
	s_add_i32 m0, s42, 0x1a000
	s_nop 0
	global_load_lds_dwordx4 v146, s[38:39]
	s_waitcnt lgkmcnt(0)
	v_mfma_f32_16x16x32_bf16 v[126:129], v[130:133], v[206:209], v[126:129]
	v_mfma_f32_16x16x32_bf16 v[122:125], v[158:161], v[206:209], v[122:125]
	v_mfma_f32_16x16x32_bf16 v[110:113], v[130:133], v[214:217], v[110:113]
	v_mfma_f32_16x16x32_bf16 v[106:109], v[158:161], v[214:217], v[106:109]
	v_mfma_f32_16x16x32_bf16 v[94:97], v[130:133], v[222:225], v[94:97]
	v_mfma_f32_16x16x32_bf16 v[90:93], v[158:161], v[222:225], v[90:93]
	v_mfma_f32_16x16x32_bf16 v[78:81], v[130:133], v[230:233], v[78:81]
	v_mfma_f32_16x16x32_bf16 v[74:77], v[158:161], v[230:233], v[74:77]
	v_mfma_f32_16x16x32_bf16 v[126:129], v[134:137], v[210:213], v[126:129]
	v_mfma_f32_16x16x32_bf16 v[122:125], v[186:189], v[210:213], v[122:125]
	v_mfma_f32_16x16x32_bf16 v[110:113], v[134:137], v[218:221], v[110:113]
	v_mfma_f32_16x16x32_bf16 v[106:109], v[186:189], v[218:221], v[106:109]
	v_mfma_f32_16x16x32_bf16 v[94:97], v[134:137], v[226:229], v[94:97]
	v_mfma_f32_16x16x32_bf16 v[90:93], v[186:189], v[226:229], v[90:93]
	v_mfma_f32_16x16x32_bf16 v[78:81], v[134:137], v[234:237], v[78:81]
	v_mfma_f32_16x16x32_bf16 v[74:77], v[186:189], v[234:237], v[74:77]
	s_waitcnt vmcnt(8)
	s_barrier
	ds_read_b128 v[130:133], v184
	ds_read_b128 v[134:137], v184 offset:1024
	ds_read_b128 v[158:161], v184 offset:2048
	ds_read_b128 v[186:189], v184 offset:3072
	ds_read_b128 v[206:209], v182 offset:49152
	ds_read_b128 v[210:213], v182 offset:50176
	ds_read_b128 v[214:217], v182 offset:51200
	ds_read_b128 v[218:221], v182 offset:52224
	ds_read_b128 v[222:225], v182 offset:53248
	ds_read_b128 v[226:229], v182 offset:54272
	ds_read_b128 v[230:233], v182 offset:55296
	ds_read_b128 v[234:237], v182 offset:56320
	s_add_u32 s34, s34, 0x80
	s_addc_u32 s35, s35, 0
	s_add_u32 s38, s38, 0x80
	s_addc_u32 s39, s39, 0
	s_add_i32 m0, s42, 0x4000
	s_nop 0
	global_load_lds_dwordx4 v140, s[34:35]
	s_add_i32 m0, s42, 0x6000
	s_nop 0
	global_load_lds_dwordx4 v144, s[34:35]
	s_add_i32 m0, s42, 0x14000
	s_nop 0
	global_load_lds_dwordx4 v142, s[38:39]
	s_add_i32 m0, s42, 0x16000
	s_nop 0
	global_load_lds_dwordx4 v146, s[38:39]
	s_waitcnt lgkmcnt(0)
	v_mfma_f32_16x16x32_bf16 v[126:129], v[130:133], v[206:209], v[126:129]
	v_mfma_f32_16x16x32_bf16 v[122:125], v[158:161], v[206:209], v[122:125]
	v_mfma_f32_16x16x32_bf16 v[110:113], v[130:133], v[214:217], v[110:113]
	v_mfma_f32_16x16x32_bf16 v[106:109], v[158:161], v[214:217], v[106:109]
	v_mfma_f32_16x16x32_bf16 v[94:97], v[130:133], v[222:225], v[94:97]
	v_mfma_f32_16x16x32_bf16 v[90:93], v[158:161], v[222:225], v[90:93]
	v_mfma_f32_16x16x32_bf16 v[78:81], v[130:133], v[230:233], v[78:81]
	v_mfma_f32_16x16x32_bf16 v[74:77], v[158:161], v[230:233], v[74:77]
	v_mfma_f32_16x16x32_bf16 v[126:129], v[134:137], v[210:213], v[126:129]
	v_mfma_f32_16x16x32_bf16 v[122:125], v[186:189], v[210:213], v[122:125]
	v_mfma_f32_16x16x32_bf16 v[110:113], v[134:137], v[218:221], v[110:113]
	v_mfma_f32_16x16x32_bf16 v[106:109], v[186:189], v[218:221], v[106:109]
	v_mfma_f32_16x16x32_bf16 v[94:97], v[134:137], v[226:229], v[94:97]
	v_mfma_f32_16x16x32_bf16 v[90:93], v[186:189], v[226:229], v[90:93]
	v_mfma_f32_16x16x32_bf16 v[78:81], v[134:137], v[234:237], v[78:81]
	v_mfma_f32_16x16x32_bf16 v[74:77], v[186:189], v[234:237], v[74:77]
	s_waitcnt vmcnt(8)
	s_barrier
	ds_read_b128 v[130:133], v180
	ds_read_b128 v[134:137], v180 offset:1024
	ds_read_b128 v[158:161], v180 offset:2048
	ds_read_b128 v[186:189], v180 offset:3072
	ds_read_b128 v[206:209], v182
	ds_read_b128 v[210:213], v182 offset:1024
	ds_read_b128 v[214:217], v182 offset:2048
	ds_read_b128 v[218:221], v182 offset:3072
	ds_read_b128 v[222:225], v182 offset:4096
	ds_read_b128 v[226:229], v182 offset:5120
	ds_read_b128 v[230:233], v182 offset:6144
	ds_read_b128 v[234:237], v182 offset:7168
	s_add_u32 s34, s34, 0x80
	s_addc_u32 s35, s35, 0
	s_add_u32 s38, s38, 0x80
	s_addc_u32 s39, s39, 0
	s_add_i32 m0, s42, 0xc000
	s_nop 0
	global_load_lds_dwordx4 v140, s[34:35]
	s_add_i32 m0, s42, 0xe000
	s_nop 0
	global_load_lds_dwordx4 v144, s[34:35]
	s_add_i32 m0, s42, 0x1c000
	s_nop 0
	global_load_lds_dwordx4 v142, s[38:39]
	s_add_i32 m0, s42, 0x1e000
	s_nop 0
	global_load_lds_dwordx4 v146, s[38:39]
	s_waitcnt lgkmcnt(0)
	v_mfma_f32_16x16x32_bf16 v[126:129], v[130:133], v[206:209], v[126:129]
	v_mfma_f32_16x16x32_bf16 v[122:125], v[158:161], v[206:209], v[122:125]
	v_mfma_f32_16x16x32_bf16 v[110:113], v[130:133], v[214:217], v[110:113]
	v_mfma_f32_16x16x32_bf16 v[106:109], v[158:161], v[214:217], v[106:109]
	v_mfma_f32_16x16x32_bf16 v[94:97], v[130:133], v[222:225], v[94:97]
	v_mfma_f32_16x16x32_bf16 v[90:93], v[158:161], v[222:225], v[90:93]
	v_mfma_f32_16x16x32_bf16 v[78:81], v[130:133], v[230:233], v[78:81]
	v_mfma_f32_16x16x32_bf16 v[74:77], v[158:161], v[230:233], v[74:77]
	v_mfma_f32_16x16x32_bf16 v[126:129], v[134:137], v[210:213], v[126:129]
	v_mfma_f32_16x16x32_bf16 v[122:125], v[186:189], v[210:213], v[122:125]
	v_mfma_f32_16x16x32_bf16 v[110:113], v[134:137], v[218:221], v[110:113]
	v_mfma_f32_16x16x32_bf16 v[106:109], v[186:189], v[218:221], v[106:109]
	v_mfma_f32_16x16x32_bf16 v[94:97], v[134:137], v[226:229], v[94:97]
	v_mfma_f32_16x16x32_bf16 v[90:93], v[186:189], v[226:229], v[90:93]
	v_mfma_f32_16x16x32_bf16 v[78:81], v[134:137], v[234:237], v[78:81]
	v_mfma_f32_16x16x32_bf16 v[74:77], v[186:189], v[234:237], v[74:77]
	s_waitcnt vmcnt(8)
	s_barrier
; #define PG8_STAGE(bufoff, gbase, voff) do { _Pragma("unroll") for (int _i = 0; _i < 2; ++_i) \
;         __builtin_amdgcn_global_load_lds((const unsigned*)((const char*)(gbase) + (voff)[_i]), (PG8_LAS unsigned*)(lds + (bufoff) + ldsw + _i * 8192), 16, 0, 0); } while (0)
; #define PG8_LDA(dst, b, h) do { _Pragma("unroll") for (int m = 0; m < 4; ++m) _Pragma("unroll") for (int k = 0; k < 2; ++k) dst[m][k] = *(const PG8_LAS bf16x8*)(lds + PG8_SA(b, h) + aoff + m * 2048 + k * 1024); } while (0)
; #define PG8_LDB(dst, b, h) do { _Pragma("unroll") for (int n = 0; n < 2; ++n) _Pragma("unroll") for (int k = 0; k < 2; ++k) dst[n][k] = *(const PG8_LAS bf16x8*)(lds + PG8_SB(b, h) + boff + n * 2048 + k * 1024); } while (0)
; #define PG8_MMA(ai, bj, At, Bt) do { __builtin_amdgcn_s_setprio(1); _Pragma("unroll") for (int m = 0; m < 4; ++m) _Pragma("unroll") for (int n = 0; n < 2; ++n) _Pragma("unroll") for (int k = 0; k < 2; ++k) \
;         acc[ai][bj][m][n] = __builtin_amdgcn_mfma_f32_16x16x32_bf16(Bt[n][k], At[m][k], acc[ai][bj][m][n], 0, 0, 0); __builtin_amdgcn_s_setprio(0); } while (0)
; #define PG8_WAIT_V(n) asm volatile("s_waitcnt vmcnt(" #n ")" ::: "memory")
; template <class Epi, class Sched, bool ALIGN_EPI = false, bool SP2 = false>
; __device__ __forceinline__ void gemm_phase(PG8_LAS unsigned char* lds, const Gemm g, const Sched& S, const Epi& E) {
;     ...
;             PG8_LDB(B0, 0, 0); PG8_LDB(B1, 0, 1); PG8_SCHED; PG8_LDA(At, 0, 0); PG8_STAGE(PG8_SA(1, 1), a1 + hstep, voffA);
;             PG8_WAIT_V(8); PG8_WAIT_L(0); PG8_BAR; PG8_MMA(0, 0, At, B0); PG8_MMA(0, 1, At, B1); PG8_BAR; PG8_SCHED;
;             PG8_LDA(At, 0, 1); PG8_STAGE(PG8_SB(0, 0), b2, voffB); PG8_STAGE(PG8_SB(0, 1), b2 + hstep, voffB); PG8_STAGE(PG8_SA(0, 0), a2, voffA);
;             PG8_WAIT_V(8); PG8_WAIT_L(0); PG8_BAR; PG8_MMA(1, 0, At, B0); PG8_MMA(1, 1, At, B1); PG8_BAR; PG8_SCHED;
;             PG8_LDB(B0, 1, 0); PG8_LDB(B1, 1, 1); PG8_SCHED; PG8_LDA(At, 1, 0); PG8_STAGE(PG8_SA(0, 1), a2 + hstep, voffA);
;             PG8_WAIT_V(8); PG8_WAIT_L(0); PG8_BAR; PG8_MMA(0, 0, At, B0); PG8_MMA(0, 1, At, B1); PG8_BAR; PG8_SCHED;
;             PG8_LDA(At, 1, 1); PG8_STAGE(PG8_SB(1, 0), b3, voffB); PG8_STAGE(PG8_SB(1, 1), b3 + hstep, voffB); PG8_STAGE(PG8_SA(1, 0), a3, voffA);
;             PG8_WAIT_V(8); PG8_WAIT_L(0); PG8_BAR; PG8_MMA(1, 0, At, B0); PG8_MMA(1, 1, At, B1); PG8_BAR; PG8_SCHED;
	ds_read_b128 v[130:133], v183
	ds_read_b128 v[134:137], v183 offset:1024
	ds_read_b128 v[158:161], v183 offset:2048
	ds_read_b128 v[186:189], v183 offset:3072
	ds_read_b128 v[206:209], v182 offset:32768
	ds_read_b128 v[210:213], v182 offset:33792
	ds_read_b128 v[214:217], v182 offset:34816
	ds_read_b128 v[218:221], v182 offset:35840
	ds_read_b128 v[222:225], v182 offset:36864
	ds_read_b128 v[226:229], v182 offset:37888
	ds_read_b128 v[230:233], v182 offset:38912
	ds_read_b128 v[234:237], v182 offset:39936
	s_add_u32 s34, s34, 0x80
	s_addc_u32 s35, s35, 0
	s_add_u32 s38, s38, 0x80
	s_addc_u32 s39, s39, 0
	s_mov_b32 m0, s42
	s_nop 0
	global_load_lds_dwordx4 v140, s[34:35]
	s_add_i32 m0, s42, 0x2000
	s_nop 0
	global_load_lds_dwordx4 v144, s[34:35]
	s_add_i32 m0, s42, 0x10000
	s_nop 0
	global_load_lds_dwordx4 v142, s[38:39]
	s_add_i32 m0, s42, 0x12000
	s_nop 0
	global_load_lds_dwordx4 v146, s[38:39]
	s_waitcnt lgkmcnt(0)
	v_mfma_f32_16x16x32_bf16 v[126:129], v[130:133], v[206:209], v[126:129]
	v_mfma_f32_16x16x32_bf16 v[122:125], v[158:161], v[206:209], v[122:125]
	v_mfma_f32_16x16x32_bf16 v[110:113], v[130:133], v[214:217], v[110:113]
	v_mfma_f32_16x16x32_bf16 v[106:109], v[158:161], v[214:217], v[106:109]
	v_mfma_f32_16x16x32_bf16 v[94:97], v[130:133], v[222:225], v[94:97]
	v_mfma_f32_16x16x32_bf16 v[90:93], v[158:161], v[222:225], v[90:93]
	v_mfma_f32_16x16x32_bf16 v[78:81], v[130:133], v[230:233], v[78:81]
	v_mfma_f32_16x16x32_bf16 v[74:77], v[158:161], v[230:233], v[74:77]
	v_mfma_f32_16x16x32_bf16 v[126:129], v[134:137], v[210:213], v[126:129]
	v_mfma_f32_16x16x32_bf16 v[122:125], v[186:189], v[210:213], v[122:125]
	v_mfma_f32_16x16x32_bf16 v[110:113], v[134:137], v[218:221], v[110:113]
	v_mfma_f32_16x16x32_bf16 v[106:109], v[186:189], v[218:221], v[106:109]
	v_mfma_f32_16x16x32_bf16 v[94:97], v[134:137], v[226:229], v[94:97]
	v_mfma_f32_16x16x32_bf16 v[90:93], v[186:189], v[226:229], v[90:93]
	v_mfma_f32_16x16x32_bf16 v[78:81], v[134:137], v[234:237], v[78:81]
	v_mfma_f32_16x16x32_bf16 v[74:77], v[186:189], v[234:237], v[74:77]
	s_waitcnt vmcnt(8)
	s_barrier
	ds_read_b128 v[130:133], v181
	ds_read_b128 v[134:137], v181 offset:1024
	ds_read_b128 v[158:161], v181 offset:2048
	ds_read_b128 v[186:189], v181 offset:3072
	ds_read_b128 v[206:209], v182 offset:16384
	ds_read_b128 v[210:213], v182 offset:17408
	ds_read_b128 v[214:217], v182 offset:18432
	ds_read_b128 v[218:221], v182 offset:19456
	ds_read_b128 v[222:225], v182 offset:20480
	ds_read_b128 v[226:229], v182 offset:21504
	ds_read_b128 v[230:233], v182 offset:22528
	ds_read_b128 v[234:237], v182 offset:23552
	s_add_u32 s34, s34, 0x80
	s_addc_u32 s35, s35, 0
	s_add_u32 s38, s38, 0x80
	s_addc_u32 s39, s39, 0
	s_add_i32 m0, s42, 0x8000
	s_nop 0
	global_load_lds_dwordx4 v140, s[34:35]
	s_add_i32 m0, s42, 0xa000
	s_nop 0
	global_load_lds_dwordx4 v144, s[34:35]
	s_add_i32 m0, s42, 0x18000
	s_nop 0
	global_load_lds_dwordx4 v142, s[38:39]
	s_add_i32 m0, s42, 0x1a000
	s_nop 0
	global_load_lds_dwordx4 v146, s[38:39]
	s_waitcnt lgkmcnt(0)
	v_mfma_f32_16x16x32_bf16 v[126:129], v[130:133], v[206:209], v[126:129]
	v_mfma_f32_16x16x32_bf16 v[122:125], v[158:161], v[206:209], v[122:125]
	v_mfma_f32_16x16x32_bf16 v[110:113], v[130:133], v[214:217], v[110:113]
	v_mfma_f32_16x16x32_bf16 v[106:109], v[158:161], v[214:217], v[106:109]
	v_mfma_f32_16x16x32_bf16 v[94:97], v[130:133], v[222:225], v[94:97]
	v_mfma_f32_16x16x32_bf16 v[90:93], v[158:161], v[222:225], v[90:93]
	v_mfma_f32_16x16x32_bf16 v[78:81], v[130:133], v[230:233], v[78:81]
	v_mfma_f32_16x16x32_bf16 v[74:77], v[158:161], v[230:233], v[74:77]
	v_mfma_f32_16x16x32_bf16 v[126:129], v[134:137], v[210:213], v[126:129]
	v_mfma_f32_16x16x32_bf16 v[122:125], v[186:189], v[210:213], v[122:125]
	v_mfma_f32_16x16x32_bf16 v[110:113], v[134:137], v[218:221], v[110:113]
	v_mfma_f32_16x16x32_bf16 v[106:109], v[186:189], v[218:221], v[106:109]
	v_mfma_f32_16x16x32_bf16 v[94:97], v[134:137], v[226:229], v[94:97]
	v_mfma_f32_16x16x32_bf16 v[90:93], v[186:189], v[226:229], v[90:93]
	v_mfma_f32_16x16x32_bf16 v[78:81], v[134:137], v[234:237], v[78:81]
	v_mfma_f32_16x16x32_bf16 v[74:77], v[186:189], v[234:237], v[74:77]
	s_waitcnt vmcnt(8)
	s_barrier
	ds_read_b128 v[130:133], v184
	ds_read_b128 v[134:137], v184 offset:1024
	ds_read_b128 v[158:161], v184 offset:2048
	ds_read_b128 v[186:189], v184 offset:3072
	ds_read_b128 v[206:209], v182 offset:49152
	ds_read_b128 v[210:213], v182 offset:50176
	ds_read_b128 v[214:217], v182 offset:51200
	ds_read_b128 v[218:221], v182 offset:52224
	ds_read_b128 v[222:225], v182 offset:53248
	ds_read_b128 v[226:229], v182 offset:54272
	ds_read_b128 v[230:233], v182 offset:55296
	ds_read_b128 v[234:237], v182 offset:56320
	s_add_u32 s34, s34, 0x80
	s_addc_u32 s35, s35, 0
	s_add_u32 s38, s38, 0x80
	s_addc_u32 s39, s39, 0
	s_add_i32 m0, s42, 0x4000
	s_nop 0
	global_load_lds_dwordx4 v140, s[34:35]
	s_add_i32 m0, s42, 0x6000
	s_nop 0
	global_load_lds_dwordx4 v144, s[34:35]
	s_add_i32 m0, s42, 0x14000
	s_nop 0
	global_load_lds_dwordx4 v142, s[38:39]
	s_add_i32 m0, s42, 0x16000
	s_nop 0
	global_load_lds_dwordx4 v146, s[38:39]
	s_waitcnt lgkmcnt(0)
	v_mfma_f32_16x16x32_bf16 v[126:129], v[130:133], v[206:209], v[126:129]
	v_mfma_f32_16x16x32_bf16 v[122:125], v[158:161], v[206:209], v[122:125]
	v_mfma_f32_16x16x32_bf16 v[110:113], v[130:133], v[214:217], v[110:113]
	v_mfma_f32_16x16x32_bf16 v[106:109], v[158:161], v[214:217], v[106:109]
	v_mfma_f32_16x16x32_bf16 v[94:97], v[130:133], v[222:225], v[94:97]
	v_mfma_f32_16x16x32_bf16 v[90:93], v[158:161], v[222:225], v[90:93]
	v_mfma_f32_16x16x32_bf16 v[78:81], v[130:133], v[230:233], v[78:81]
	v_mfma_f32_16x16x32_bf16 v[74:77], v[158:161], v[230:233], v[74:77]
	v_mfma_f32_16x16x32_bf16 v[126:129], v[134:137], v[210:213], v[126:129]
	v_mfma_f32_16x16x32_bf16 v[122:125], v[186:189], v[210:213], v[122:125]
	v_mfma_f32_16x16x32_bf16 v[110:113], v[134:137], v[218:221], v[110:113]
	v_mfma_f32_16x16x32_bf16 v[106:109], v[186:189], v[218:221], v[106:109]
	v_mfma_f32_16x16x32_bf16 v[94:97], v[134:137], v[226:229], v[94:97]
	v_mfma_f32_16x16x32_bf16 v[90:93], v[186:189], v[226:229], v[90:93]
	v_mfma_f32_16x16x32_bf16 v[78:81], v[134:137], v[234:237], v[78:81]
	v_mfma_f32_16x16x32_bf16 v[74:77], v[186:189], v[234:237], v[74:77]
	s_waitcnt vmcnt(8)
	s_barrier
; #define PG8_STAGE(bufoff, gbase, voff) do { _Pragma("unroll") for (int _i = 0; _i < 2; ++_i) \
;         __builtin_amdgcn_global_load_lds((const unsigned*)((const char*)(gbase) + (voff)[_i]), (PG8_LAS unsigned*)(lds + (bufoff) + ldsw + _i * 8192), 16, 0, 0); } while (0)
; #define PG8_LDA(dst, b, h) do { _Pragma("unroll") for (int m = 0; m < 4; ++m) _Pragma("unroll") for (int k = 0; k < 2; ++k) dst[m][k] = *(const PG8_LAS bf16x8*)(lds + PG8_SA(b, h) + aoff + m * 2048 + k * 1024); } while (0)
; #define PG8_LDB(dst, b, h) do { _Pragma("unroll") for (int n = 0; n < 2; ++n) _Pragma("unroll") for (int k = 0; k < 2; ++k) dst[n][k] = *(const PG8_LAS bf16x8*)(lds + PG8_SB(b, h) + boff + n * 2048 + k * 1024); } while (0)
; #define PG8_MMA(ai, bj, At, Bt) do { __builtin_amdgcn_s_setprio(1); _Pragma("unroll") for (int m = 0; m < 4; ++m) _Pragma("unroll") for (int n = 0; n < 2; ++n) _Pragma("unroll") for (int k = 0; k < 2; ++k) \
;         acc[ai][bj][m][n] = __builtin_amdgcn_mfma_f32_16x16x32_bf16(Bt[n][k], At[m][k], acc[ai][bj][m][n], 0, 0, 0); __builtin_amdgcn_s_setprio(0); } while (0)
; #define PG8_WAIT_V(n) asm volatile("s_waitcnt vmcnt(" #n ")" ::: "memory")
; template <class Epi, class Sched, bool ALIGN_EPI = false, bool SP2 = false>
; __device__ __forceinline__ void gemm_phase(PG8_LAS unsigned char* lds, const Gemm g, const Sched& S, const Epi& E) {
;     ...
;             PG8_LDB(B0, 0, 0); PG8_LDB(B1, 0, 1); PG8_SCHED; PG8_LDA(At, 0, 0); PG8_STAGE(PG8_SA(1, 1), a1 + hstep, voffA);
;             PG8_WAIT_V(8); PG8_WAIT_L(0); PG8_BAR; PG8_MMA(0, 0, At, B0); PG8_MMA(0, 1, At, B1); PG8_BAR; PG8_SCHED;
;             PG8_LDA(At, 0, 1); PG8_STAGE(PG8_SB(0, 0), b2, voffB); PG8_STAGE(PG8_SB(0, 1), b2 + hstep, voffB); PG8_STAGE(PG8_SA(0, 0), a2, voffA);
;             PG8_WAIT_V(8); PG8_WAIT_L(0); PG8_BAR; PG8_MMA(1, 0, At, B0); PG8_MMA(1, 1, At, B1); PG8_BAR; PG8_SCHED;
;             PG8_LDB(B0, 1, 0); PG8_LDB(B1, 1, 1); PG8_SCHED; PG8_LDA(At, 1, 0); PG8_STAGE(PG8_SA(0, 1), a2 + hstep, voffA);
;             PG8_WAIT_V(8); PG8_WAIT_L(0); PG8_BAR; PG8_MMA(0, 0, At, B0); PG8_MMA(0, 1, At, B1); PG8_BAR; PG8_SCHED;
;             PG8_LDA(At, 1, 1); PG8_STAGE(PG8_SB(1, 0), b3, voffB); PG8_STAGE(PG8_SB(1, 1), b3 + hstep, voffB); PG8_STAGE(PG8_SA(1, 0), a3, voffA);
;             PG8_WAIT_V(8); PG8_WAIT_L(0); PG8_BAR; PG8_MMA(1, 0, At, B0); PG8_MMA(1, 1, At, B1); PG8_BAR; PG8_SCHED;
	ds_read_b128 v[130:133], v180
	ds_read_b128 v[134:137], v180 offset:1024
	ds_read_b128 v[158:161], v180 offset:2048
	ds_read_b128 v[186:189], v180 offset:3072
	ds_read_b128 v[206:209], v182
	ds_read_b128 v[210:213], v182 offset:1024
	ds_read_b128 v[214:217], v182 offset:2048
	ds_read_b128 v[218:221], v182 offset:3072
	ds_read_b128 v[222:225], v182 offset:4096
	ds_read_b128 v[226:229], v182 offset:5120
	ds_read_b128 v[230:233], v182 offset:6144
	ds_read_b128 v[234:237], v182 offset:7168
	s_add_u32 s34, s34, 0x80
	s_addc_u32 s35, s35, 0
	s_add_u32 s38, s38, 0x80
	s_addc_u32 s39, s39, 0
	s_add_i32 m0, s42, 0xc000
	s_nop 0
	global_load_lds_dwordx4 v140, s[34:35]
	s_add_i32 m0, s42, 0xe000
	s_nop 0
	global_load_lds_dwordx4 v144, s[34:35]
	s_add_i32 m0, s42, 0x1c000
	s_nop 0
	global_load_lds_dwordx4 v142, s[38:39]
	s_add_i32 m0, s42, 0x1e000
	s_nop 0
	global_load_lds_dwordx4 v146, s[38:39]
	s_waitcnt lgkmcnt(0)
	v_mfma_f32_16x16x32_bf16 v[126:129], v[130:133], v[206:209], v[126:129]
	v_mfma_f32_16x16x32_bf16 v[122:125], v[158:161], v[206:209], v[122:125]
	v_mfma_f32_16x16x32_bf16 v[110:113], v[130:133], v[214:217], v[110:113]
	v_mfma_f32_16x16x32_bf16 v[106:109], v[158:161], v[214:217], v[106:109]
	v_mfma_f32_16x16x32_bf16 v[94:97], v[130:133], v[222:225], v[94:97]
	v_mfma_f32_16x16x32_bf16 v[90:93], v[158:161], v[222:225], v[90:93]
	v_mfma_f32_16x16x32_bf16 v[78:81], v[130:133], v[230:233], v[78:81]
	v_mfma_f32_16x16x32_bf16 v[74:77], v[158:161], v[230:233], v[74:77]
	v_mfma_f32_16x16x32_bf16 v[126:129], v[134:137], v[210:213], v[126:129]
	v_mfma_f32_16x16x32_bf16 v[122:125], v[186:189], v[210:213], v[122:125]
	v_mfma_f32_16x16x32_bf16 v[110:113], v[134:137], v[218:221], v[110:113]
	v_mfma_f32_16x16x32_bf16 v[106:109], v[186:189], v[218:221], v[106:109]
	v_mfma_f32_16x16x32_bf16 v[94:97], v[134:137], v[226:229], v[94:97]
	v_mfma_f32_16x16x32_bf16 v[90:93], v[186:189], v[226:229], v[90:93]
	v_mfma_f32_16x16x32_bf16 v[78:81], v[134:137], v[234:237], v[78:81]
	v_mfma_f32_16x16x32_bf16 v[74:77], v[186:189], v[234:237], v[74:77]
	s_waitcnt vmcnt(8)
	s_barrier
	ds_read_b128 v[130:133], v183
	ds_read_b128 v[134:137], v183 offset:1024
	ds_read_b128 v[158:161], v183 offset:2048
	ds_read_b128 v[186:189], v183 offset:3072
	ds_read_b128 v[206:209], v182 offset:32768
	ds_read_b128 v[210:213], v182 offset:33792
	ds_read_b128 v[214:217], v182 offset:34816
	ds_read_b128 v[218:221], v182 offset:35840
	ds_read_b128 v[222:225], v182 offset:36864
	ds_read_b128 v[226:229], v182 offset:37888
	ds_read_b128 v[230:233], v182 offset:38912
	ds_read_b128 v[234:237], v182 offset:39936
	s_add_u32 s34, s34, 0x80
	s_addc_u32 s35, s35, 0
	s_add_u32 s38, s38, 0x80
	s_addc_u32 s39, s39, 0
	s_mov_b32 m0, s42
	s_nop 0
	global_load_lds_dwordx4 v140, s[34:35]
	s_add_i32 m0, s42, 0x2000
	s_nop 0
	global_load_lds_dwordx4 v144, s[34:35]
	s_add_i32 m0, s42, 0x10000
	s_nop 0
	global_load_lds_dwordx4 v142, s[38:39]
	s_add_i32 m0, s42, 0x12000
	s_nop 0
	global_load_lds_dwordx4 v146, s[38:39]
	s_waitcnt lgkmcnt(0)
	v_mfma_f32_16x16x32_bf16 v[126:129], v[130:133], v[206:209], v[126:129]
	v_mfma_f32_16x16x32_bf16 v[122:125], v[158:161], v[206:209], v[122:125]
	v_mfma_f32_16x16x32_bf16 v[110:113], v[130:133], v[214:217], v[110:113]
	v_mfma_f32_16x16x32_bf16 v[106:109], v[158:161], v[214:217], v[106:109]
	v_mfma_f32_16x16x32_bf16 v[94:97], v[130:133], v[222:225], v[94:97]
	v_mfma_f32_16x16x32_bf16 v[90:93], v[158:161], v[222:225], v[90:93]
	v_mfma_f32_16x16x32_bf16 v[78:81], v[130:133], v[230:233], v[78:81]
	v_mfma_f32_16x16x32_bf16 v[74:77], v[158:161], v[230:233], v[74:77]
	v_mfma_f32_16x16x32_bf16 v[126:129], v[134:137], v[210:213], v[126:129]
	v_mfma_f32_16x16x32_bf16 v[122:125], v[186:189], v[210:213], v[122:125]
	v_mfma_f32_16x16x32_bf16 v[110:113], v[134:137], v[218:221], v[110:113]
	v_mfma_f32_16x16x32_bf16 v[106:109], v[186:189], v[218:221], v[106:109]
	v_mfma_f32_16x16x32_bf16 v[94:97], v[134:137], v[226:229], v[94:97]
	v_mfma_f32_16x16x32_bf16 v[90:93], v[186:189], v[226:229], v[90:93]
	v_mfma_f32_16x16x32_bf16 v[78:81], v[134:137], v[234:237], v[78:81]
	v_mfma_f32_16x16x32_bf16 v[74:77], v[186:189], v[234:237], v[74:77]
	s_waitcnt vmcnt(8)
	s_barrier
	ds_read_b128 v[130:133], v181
	ds_read_b128 v[134:137], v181 offset:1024
	ds_read_b128 v[158:161], v181 offset:2048
	ds_read_b128 v[186:189], v181 offset:3072
	ds_read_b128 v[206:209], v182 offset:16384
	ds_read_b128 v[210:213], v182 offset:17408
	ds_read_b128 v[214:217], v182 offset:18432
	ds_read_b128 v[218:221], v182 offset:19456
	ds_read_b128 v[222:225], v182 offset:20480
	ds_read_b128 v[226:229], v182 offset:21504
	ds_read_b128 v[230:233], v182 offset:22528
	ds_read_b128 v[234:237], v182 offset:23552
	s_add_u32 s34, s34, 0x80
	s_addc_u32 s35, s35, 0
	s_add_u32 s38, s38, 0x80
	s_addc_u32 s39, s39, 0
	s_add_i32 m0, s42, 0x8000
	s_nop 0
	global_load_lds_dwordx4 v140, s[34:35]
	s_add_i32 m0, s42, 0xa000
	s_nop 0
	global_load_lds_dwordx4 v144, s[34:35]
	s_add_i32 m0, s42, 0x18000
	s_nop 0
	global_load_lds_dwordx4 v142, s[38:39]
	s_add_i32 m0, s42, 0x1a000
	s_nop 0
	global_load_lds_dwordx4 v146, s[38:39]
	s_waitcnt lgkmcnt(0)
	v_mfma_f32_16x16x32_bf16 v[126:129], v[130:133], v[206:209], v[126:129]
	v_mfma_f32_16x16x32_bf16 v[122:125], v[158:161], v[206:209], v[122:125]
	v_mfma_f32_16x16x32_bf16 v[110:113], v[130:133], v[214:217], v[110:113]
	v_mfma_f32_16x16x32_bf16 v[106:109], v[158:161], v[214:217], v[106:109]
	v_mfma_f32_16x16x32_bf16 v[94:97], v[130:133], v[222:225], v[94:97]
	v_mfma_f32_16x16x32_bf16 v[90:93], v[158:161], v[222:225], v[90:93]
	v_mfma_f32_16x16x32_bf16 v[78:81], v[130:133], v[230:233], v[78:81]
	v_mfma_f32_16x16x32_bf16 v[74:77], v[158:161], v[230:233], v[74:77]
	v_mfma_f32_16x16x32_bf16 v[126:129], v[134:137], v[210:213], v[126:129]
	v_mfma_f32_16x16x32_bf16 v[122:125], v[186:189], v[210:213], v[122:125]
	v_mfma_f32_16x16x32_bf16 v[110:113], v[134:137], v[218:221], v[110:113]
	v_mfma_f32_16x16x32_bf16 v[106:109], v[186:189], v[218:221], v[106:109]
	v_mfma_f32_16x16x32_bf16 v[94:97], v[134:137], v[226:229], v[94:97]
	v_mfma_f32_16x16x32_bf16 v[90:93], v[186:189], v[226:229], v[90:93]
	v_mfma_f32_16x16x32_bf16 v[78:81], v[134:137], v[234:237], v[78:81]
	v_mfma_f32_16x16x32_bf16 v[74:77], v[186:189], v[234:237], v[74:77]
	s_waitcnt vmcnt(8)
	s_barrier
; #define PG8_STAGE(bufoff, gbase, voff) do { _Pragma("unroll") for (int _i = 0; _i < 2; ++_i) \
;         __builtin_amdgcn_global_load_lds((const unsigned*)((const char*)(gbase) + (voff)[_i]), (PG8_LAS unsigned*)(lds + (bufoff) + ldsw + _i * 8192), 16, 0, 0); } while (0)
; #define PG8_LDA(dst, b, h) do { _Pragma("unroll") for (int m = 0; m < 4; ++m) _Pragma("unroll") for (int k = 0; k < 2; ++k) dst[m][k] = *(const PG8_LAS bf16x8*)(lds + PG8_SA(b, h) + aoff + m * 2048 + k * 1024); } while (0)
; #define PG8_LDB(dst, b, h) do { _Pragma("unroll") for (int n = 0; n < 2; ++n) _Pragma("unroll") for (int k = 0; k < 2; ++k) dst[n][k] = *(const PG8_LAS bf16x8*)(lds + PG8_SB(b, h) + boff + n * 2048 + k * 1024); } while (0)
; #define PG8_MMA(ai, bj, At, Bt) do { __builtin_amdgcn_s_setprio(1); _Pragma("unroll") for (int m = 0; m < 4; ++m) _Pragma("unroll") for (int n = 0; n < 2; ++n) _Pragma("unroll") for (int k = 0; k < 2; ++k) \
;         acc[ai][bj][m][n] = __builtin_amdgcn_mfma_f32_16x16x32_bf16(Bt[n][k], At[m][k], acc[ai][bj][m][n], 0, 0, 0); __builtin_amdgcn_s_setprio(0); } while (0)
; #define PG8_WAIT_V(n) asm volatile("s_waitcnt vmcnt(" #n ")" ::: "memory")
; template <class Epi, class Sched, bool ALIGN_EPI = false, bool SP2 = false>
; __device__ __forceinline__ void gemm_phase(PG8_LAS unsigned char* lds, const Gemm g, const Sched& S, const Epi& E) {
;     ...
;             PG8_LDB(B0, 0, 0); PG8_LDB(B1, 0, 1); PG8_SCHED; PG8_LDA(At, 0, 0); PG8_STAGE(PG8_SA(1, 1), a1 + hstep, voffA);
;             PG8_WAIT_V(8); PG8_WAIT_L(0); PG8_BAR; PG8_MMA(0, 0, At, B0); PG8_MMA(0, 1, At, B1); PG8_BAR; PG8_SCHED;
;             PG8_LDA(At, 0, 1); PG8_STAGE(PG8_SB(0, 0), b2, voffB); PG8_STAGE(PG8_SB(0, 1), b2 + hstep, voffB); PG8_STAGE(PG8_SA(0, 0), a2, voffA);
;             PG8_WAIT_V(8); PG8_WAIT_L(0); PG8_BAR; PG8_MMA(1, 0, At, B0); PG8_MMA(1, 1, At, B1); PG8_BAR; PG8_SCHED;
;             PG8_LDB(B0, 1, 0); PG8_LDB(B1, 1, 1); PG8_SCHED; PG8_LDA(At, 1, 0); PG8_STAGE(PG8_SA(0, 1), a2 + hstep, voffA);
;             PG8_WAIT_V(8); PG8_WAIT_L(0); PG8_BAR; PG8_MMA(0, 0, At, B0); PG8_MMA(0, 1, At, B1); PG8_BAR; PG8_SCHED;
;             PG8_LDA(At, 1, 1); PG8_STAGE(PG8_SB(1, 0), b3, voffB); PG8_STAGE(PG8_SB(1, 1), b3 + hstep, voffB); PG8_STAGE(PG8_SA(1, 0), a3, voffA);
;             PG8_WAIT_V(8); PG8_WAIT_L(0); PG8_BAR; PG8_MMA(1, 0, At, B0); PG8_MMA(1, 1, At, B1); PG8_BAR; PG8_SCHED;
	ds_read_b128 v[130:133], v184
	ds_read_b128 v[134:137], v184 offset:1024
	ds_read_b128 v[158:161], v184 offset:2048
	ds_read_b128 v[186:189], v184 offset:3072
	ds_read_b128 v[206:209], v182 offset:49152
	ds_read_b128 v[210:213], v182 offset:50176
	ds_read_b128 v[214:217], v182 offset:51200
	ds_read_b128 v[218:221], v182 offset:52224
	ds_read_b128 v[222:225], v182 offset:53248
	ds_read_b128 v[226:229], v182 offset:54272
	ds_read_b128 v[230:233], v182 offset:55296
	ds_read_b128 v[234:237], v182 offset:56320
	s_add_u32 s34, s34, 0x80
	s_addc_u32 s35, s35, 0
	s_add_u32 s38, s38, 0x80
	s_addc_u32 s39, s39, 0
	s_add_i32 m0, s42, 0x4000
	s_nop 0
	global_load_lds_dwordx4 v140, s[34:35]
	s_add_i32 m0, s42, 0x6000
	s_nop 0
	global_load_lds_dwordx4 v144, s[34:35]
	s_add_i32 m0, s42, 0x14000
	s_nop 0
	global_load_lds_dwordx4 v142, s[38:39]
	s_add_i32 m0, s42, 0x16000
	s_nop 0
	global_load_lds_dwordx4 v146, s[38:39]
	s_waitcnt lgkmcnt(0)
	v_mfma_f32_16x16x32_bf16 v[126:129], v[130:133], v[206:209], v[126:129]
	v_mfma_f32_16x16x32_bf16 v[122:125], v[158:161], v[206:209], v[122:125]
	v_mfma_f32_16x16x32_bf16 v[110:113], v[130:133], v[214:217], v[110:113]
	v_mfma_f32_16x16x32_bf16 v[106:109], v[158:161], v[214:217], v[106:109]
	v_mfma_f32_16x16x32_bf16 v[94:97], v[130:133], v[222:225], v[94:97]
	v_mfma_f32_16x16x32_bf16 v[90:93], v[158:161], v[222:225], v[90:93]
	v_mfma_f32_16x16x32_bf16 v[78:81], v[130:133], v[230:233], v[78:81]
	v_mfma_f32_16x16x32_bf16 v[74:77], v[158:161], v[230:233], v[74:77]
	v_mfma_f32_16x16x32_bf16 v[126:129], v[134:137], v[210:213], v[126:129]
	v_mfma_f32_16x16x32_bf16 v[122:125], v[186:189], v[210:213], v[122:125]
	v_mfma_f32_16x16x32_bf16 v[110:113], v[134:137], v[218:221], v[110:113]
	v_mfma_f32_16x16x32_bf16 v[106:109], v[186:189], v[218:221], v[106:109]
	v_mfma_f32_16x16x32_bf16 v[94:97], v[134:137], v[226:229], v[94:97]
	v_mfma_f32_16x16x32_bf16 v[90:93], v[186:189], v[226:229], v[90:93]
	v_mfma_f32_16x16x32_bf16 v[78:81], v[134:137], v[234:237], v[78:81]
	v_mfma_f32_16x16x32_bf16 v[74:77], v[186:189], v[234:237], v[74:77]
	s_waitcnt vmcnt(8)
	s_barrier
	ds_read_b128 v[130:133], v180
	ds_read_b128 v[134:137], v180 offset:1024
	ds_read_b128 v[158:161], v180 offset:2048
	ds_read_b128 v[186:189], v180 offset:3072
	ds_read_b128 v[206:209], v182
	ds_read_b128 v[210:213], v182 offset:1024
	ds_read_b128 v[214:217], v182 offset:2048
	ds_read_b128 v[218:221], v182 offset:3072
	ds_read_b128 v[222:225], v182 offset:4096
	ds_read_b128 v[226:229], v182 offset:5120
	ds_read_b128 v[230:233], v182 offset:6144
	ds_read_b128 v[234:237], v182 offset:7168
	s_add_u32 s34, s34, 0x80
	s_addc_u32 s35, s35, 0
	s_add_u32 s38, s38, 0x80
	s_addc_u32 s39, s39, 0
	s_add_i32 m0, s42, 0xc000
	s_nop 0
	global_load_lds_dwordx4 v140, s[34:35]
	s_add_i32 m0, s42, 0xe000
	s_nop 0
	global_load_lds_dwordx4 v144, s[34:35]
	s_add_i32 m0, s42, 0x1c000
	s_nop 0
	global_load_lds_dwordx4 v142, s[38:39]
	s_add_i32 m0, s42, 0x1e000
	s_nop 0
	global_load_lds_dwordx4 v146, s[38:39]
	s_waitcnt lgkmcnt(0)
	v_mfma_f32_16x16x32_bf16 v[126:129], v[130:133], v[206:209], v[126:129]
	v_mfma_f32_16x16x32_bf16 v[122:125], v[158:161], v[206:209], v[122:125]
	v_mfma_f32_16x16x32_bf16 v[110:113], v[130:133], v[214:217], v[110:113]
	v_mfma_f32_16x16x32_bf16 v[106:109], v[158:161], v[214:217], v[106:109]
	v_mfma_f32_16x16x32_bf16 v[94:97], v[130:133], v[222:225], v[94:97]
	v_mfma_f32_16x16x32_bf16 v[90:93], v[158:161], v[222:225], v[90:93]
	v_mfma_f32_16x16x32_bf16 v[78:81], v[130:133], v[230:233], v[78:81]
	v_mfma_f32_16x16x32_bf16 v[74:77], v[158:161], v[230:233], v[74:77]
	v_mfma_f32_16x16x32_bf16 v[126:129], v[134:137], v[210:213], v[126:129]
	v_mfma_f32_16x16x32_bf16 v[122:125], v[186:189], v[210:213], v[122:125]
	v_mfma_f32_16x16x32_bf16 v[110:113], v[134:137], v[218:221], v[110:113]
	v_mfma_f32_16x16x32_bf16 v[106:109], v[186:189], v[218:221], v[106:109]
	v_mfma_f32_16x16x32_bf16 v[94:97], v[134:137], v[226:229], v[94:97]
	v_mfma_f32_16x16x32_bf16 v[90:93], v[186:189], v[226:229], v[90:93]
	v_mfma_f32_16x16x32_bf16 v[78:81], v[134:137], v[234:237], v[78:81]
	v_mfma_f32_16x16x32_bf16 v[74:77], v[186:189], v[234:237], v[74:77]
	s_waitcnt vmcnt(8)
	s_barrier
	ds_read_b128 v[130:133], v183
	ds_read_b128 v[134:137], v183 offset:1024
	ds_read_b128 v[158:161], v183 offset:2048
	ds_read_b128 v[186:189], v183 offset:3072
	ds_read_b128 v[206:209], v182 offset:32768
	ds_read_b128 v[210:213], v182 offset:33792
	ds_read_b128 v[214:217], v182 offset:34816
	ds_read_b128 v[218:221], v182 offset:35840
	ds_read_b128 v[222:225], v182 offset:36864
	ds_read_b128 v[226:229], v182 offset:37888
	ds_read_b128 v[230:233], v182 offset:38912
	ds_read_b128 v[234:237], v182 offset:39936
	s_waitcnt lgkmcnt(0)
	v_mfma_f32_16x16x32_bf16 v[126:129], v[130:133], v[206:209], v[126:129]
	v_mfma_f32_16x16x32_bf16 v[122:125], v[158:161], v[206:209], v[122:125]
	v_mfma_f32_16x16x32_bf16 v[110:113], v[130:133], v[214:217], v[110:113]
	v_mfma_f32_16x16x32_bf16 v[106:109], v[158:161], v[214:217], v[106:109]
	v_mfma_f32_16x16x32_bf16 v[94:97], v[130:133], v[222:225], v[94:97]
	v_mfma_f32_16x16x32_bf16 v[90:93], v[158:161], v[222:225], v[90:93]
	v_mfma_f32_16x16x32_bf16 v[78:81], v[130:133], v[230:233], v[78:81]
	v_mfma_f32_16x16x32_bf16 v[74:77], v[158:161], v[230:233], v[74:77]
	v_mfma_f32_16x16x32_bf16 v[126:129], v[134:137], v[210:213], v[126:129]
	v_mfma_f32_16x16x32_bf16 v[122:125], v[186:189], v[210:213], v[122:125]
	v_mfma_f32_16x16x32_bf16 v[110:113], v[134:137], v[218:221], v[110:113]
	v_mfma_f32_16x16x32_bf16 v[106:109], v[186:189], v[218:221], v[106:109]
	v_mfma_f32_16x16x32_bf16 v[94:97], v[134:137], v[226:229], v[94:97]
	v_mfma_f32_16x16x32_bf16 v[90:93], v[186:189], v[226:229], v[90:93]
	v_mfma_f32_16x16x32_bf16 v[78:81], v[134:137], v[234:237], v[78:81]
	v_mfma_f32_16x16x32_bf16 v[74:77], v[186:189], v[234:237], v[74:77]
	s_waitcnt vmcnt(4)
	s_barrier
; #define PG8_STAGE(bufoff, gbase, voff) do { _Pragma("unroll") for (int _i = 0; _i < 2; ++_i) \
;         __builtin_amdgcn_global_load_lds((const unsigned*)((const char*)(gbase) + (voff)[_i]), (PG8_LAS unsigned*)(lds + (bufoff) + ldsw + _i * 8192), 16, 0, 0); } while (0)
; #define PG8_LDA(dst, b, h) do { _Pragma("unroll") for (int m = 0; m < 4; ++m) _Pragma("unroll") for (int k = 0; k < 2; ++k) dst[m][k] = *(const PG8_LAS bf16x8*)(lds + PG8_SA(b, h) + aoff + m * 2048 + k * 1024); } while (0)
; #define PG8_LDB(dst, b, h) do { _Pragma("unroll") for (int n = 0; n < 2; ++n) _Pragma("unroll") for (int k = 0; k < 2; ++k) dst[n][k] = *(const PG8_LAS bf16x8*)(lds + PG8_SB(b, h) + boff + n * 2048 + k * 1024); } while (0)
; #define PG8_MMA(ai, bj, At, Bt) do { __builtin_amdgcn_s_setprio(1); _Pragma("unroll") for (int m = 0; m < 4; ++m) _Pragma("unroll") for (int n = 0; n < 2; ++n) _Pragma("unroll") for (int k = 0; k < 2; ++k) \
;         acc[ai][bj][m][n] = __builtin_amdgcn_mfma_f32_16x16x32_bf16(Bt[n][k], At[m][k], acc[ai][bj][m][n], 0, 0, 0); __builtin_amdgcn_s_setprio(0); } while (0)
; #define PG8_WAIT_V(n) asm volatile("s_waitcnt vmcnt(" #n ")" ::: "memory")
; template <class Epi, class Sched, bool ALIGN_EPI = false, bool SP2 = false>
; __device__ __forceinline__ void gemm_phase(PG8_LAS unsigned char* lds, const Gemm g, const Sched& S, const Epi& E) {
;     ...
;             PG8_LDB(B0, 0, 0); PG8_LDB(B1, 0, 1); PG8_SCHED; PG8_LDA(At, 0, 0); PG8_STAGE(PG8_SA(1, 1), a1 + hstep, voffA);
;             PG8_WAIT_V(8); PG8_WAIT_L(0); PG8_BAR; PG8_MMA(0, 0, At, B0); PG8_MMA(0, 1, At, B1); PG8_BAR; PG8_SCHED;
;             PG8_LDA(At, 0, 1); PG8_STAGE(PG8_SB(0, 0), b2, voffB); PG8_STAGE(PG8_SB(0, 1), b2 + hstep, voffB); PG8_STAGE(PG8_SA(0, 0), a2, voffA);
;             PG8_WAIT_V(8); PG8_WAIT_L(0); PG8_BAR; PG8_MMA(1, 0, At, B0); PG8_MMA(1, 1, At, B1); PG8_BAR; PG8_SCHED;
;             PG8_LDB(B0, 1, 0); PG8_LDB(B1, 1, 1); PG8_SCHED; PG8_LDA(At, 1, 0); PG8_STAGE(PG8_SA(0, 1), a2 + hstep, voffA);
;             PG8_WAIT_V(8); PG8_WAIT_L(0); PG8_BAR; PG8_MMA(0, 0, At, B0); PG8_MMA(0, 1, At, B1); PG8_BAR; PG8_SCHED;
;             PG8_LDA(At, 1, 1); PG8_STAGE(PG8_SB(1, 0), b3, voffB); PG8_STAGE(PG8_SB(1, 1), b3 + hstep, voffB); PG8_STAGE(PG8_SA(1, 0), a3, voffA);
;             PG8_WAIT_V(8); PG8_WAIT_L(0); PG8_BAR; PG8_MMA(1, 0, At, B0); PG8_MMA(1, 1, At, B1); PG8_BAR; PG8_SCHED;
	ds_read_b128 v[130:133], v181
	ds_read_b128 v[134:137], v181 offset:1024
	ds_read_b128 v[158:161], v181 offset:2048
	ds_read_b128 v[186:189], v181 offset:3072
	ds_read_b128 v[206:209], v182 offset:16384
	ds_read_b128 v[210:213], v182 offset:17408
	ds_read_b128 v[214:217], v182 offset:18432
	ds_read_b128 v[218:221], v182 offset:19456
	ds_read_b128 v[222:225], v182 offset:20480
	ds_read_b128 v[226:229], v182 offset:21504
	ds_read_b128 v[230:233], v182 offset:22528
	ds_read_b128 v[234:237], v182 offset:23552
	s_waitcnt lgkmcnt(0)
	v_mfma_f32_16x16x32_bf16 v[126:129], v[130:133], v[206:209], v[126:129]
	v_mfma_f32_16x16x32_bf16 v[122:125], v[158:161], v[206:209], v[122:125]
	v_mfma_f32_16x16x32_bf16 v[110:113], v[130:133], v[214:217], v[110:113]
	v_mfma_f32_16x16x32_bf16 v[106:109], v[158:161], v[214:217], v[106:109]
	v_mfma_f32_16x16x32_bf16 v[94:97], v[130:133], v[222:225], v[94:97]
	v_mfma_f32_16x16x32_bf16 v[90:93], v[158:161], v[222:225], v[90:93]
	v_mfma_f32_16x16x32_bf16 v[78:81], v[130:133], v[230:233], v[78:81]
	v_mfma_f32_16x16x32_bf16 v[74:77], v[158:161], v[230:233], v[74:77]
	v_mfma_f32_16x16x32_bf16 v[126:129], v[134:137], v[210:213], v[126:129]
	v_mfma_f32_16x16x32_bf16 v[122:125], v[186:189], v[210:213], v[122:125]
	v_mfma_f32_16x16x32_bf16 v[110:113], v[134:137], v[218:221], v[110:113]
	v_mfma_f32_16x16x32_bf16 v[106:109], v[186:189], v[218:221], v[106:109]
	v_mfma_f32_16x16x32_bf16 v[94:97], v[134:137], v[226:229], v[94:97]
	v_mfma_f32_16x16x32_bf16 v[90:93], v[186:189], v[226:229], v[90:93]
	v_mfma_f32_16x16x32_bf16 v[78:81], v[134:137], v[234:237], v[78:81]
	v_mfma_f32_16x16x32_bf16 v[74:77], v[186:189], v[234:237], v[74:77]
	s_waitcnt vmcnt(0)
	s_barrier
	ds_read_b128 v[130:133], v184
	ds_read_b128 v[134:137], v184 offset:1024
	ds_read_b128 v[158:161], v184 offset:2048
	ds_read_b128 v[186:189], v184 offset:3072
	ds_read_b128 v[206:209], v182 offset:49152
	ds_read_b128 v[210:213], v182 offset:50176
	ds_read_b128 v[214:217], v182 offset:51200
	ds_read_b128 v[218:221], v182 offset:52224
	ds_read_b128 v[222:225], v182 offset:53248
	ds_read_b128 v[226:229], v182 offset:54272
	ds_read_b128 v[230:233], v182 offset:55296
	ds_read_b128 v[234:237], v182 offset:56320
	s_waitcnt lgkmcnt(0)
	v_mfma_f32_16x16x32_bf16 v[126:129], v[130:133], v[206:209], v[126:129]
	v_mfma_f32_16x16x32_bf16 v[122:125], v[158:161], v[206:209], v[122:125]
	v_mfma_f32_16x16x32_bf16 v[110:113], v[130:133], v[214:217], v[110:113]
	v_mfma_f32_16x16x32_bf16 v[106:109], v[158:161], v[214:217], v[106:109]
	v_mfma_f32_16x16x32_bf16 v[94:97], v[130:133], v[222:225], v[94:97]
	v_mfma_f32_16x16x32_bf16 v[90:93], v[158:161], v[222:225], v[90:93]
	v_mfma_f32_16x16x32_bf16 v[78:81], v[130:133], v[230:233], v[78:81]
	v_mfma_f32_16x16x32_bf16 v[74:77], v[158:161], v[230:233], v[74:77]
	v_mfma_f32_16x16x32_bf16 v[126:129], v[134:137], v[210:213], v[126:129]
	v_mfma_f32_16x16x32_bf16 v[122:125], v[186:189], v[210:213], v[122:125]
	v_mfma_f32_16x16x32_bf16 v[110:113], v[134:137], v[218:221], v[110:113]
	v_mfma_f32_16x16x32_bf16 v[106:109], v[186:189], v[218:221], v[106:109]
	v_mfma_f32_16x16x32_bf16 v[94:97], v[134:137], v[226:229], v[94:97]
	v_mfma_f32_16x16x32_bf16 v[90:93], v[186:189], v[226:229], v[90:93]
	v_mfma_f32_16x16x32_bf16 v[78:81], v[134:137], v[234:237], v[78:81]
	v_mfma_f32_16x16x32_bf16 v[74:77], v[186:189], v[234:237], v[74:77]
	s_branch .LBB0_141
.Lp1q_lean_q1:
	s_mov_b32 s34, s6
	s_mov_b32 s35, 0
	s_lshl_b64 s[34:35], s[34:35], 19
	s_add_u32 s34, s34, s66
	s_addc_u32 s35, s35, s67
	s_add_u32 s34, s34, 0x80
	s_addc_u32 s35, s35, 0
	s_mov_b32 s38, s0
	s_mov_b32 s39, 0
	s_lshl_b64 s[38:39], s[38:39], 19
	s_add_u32 s38, s38, s62
	s_addc_u32 s39, s39, s63
	s_add_u32 s38, s38, 0x80
	s_addc_u32 s39, s39, 0
	s_add_u32 s38, s38, 0x40000
	s_addc_u32 s39, s39, 0
	s_waitcnt vmcnt(0) lgkmcnt(0)
	s_barrier
	s_add_u32 s34, s34, 0x80
	s_addc_u32 s35, s35, 0
	s_add_u32 s38, s38, 0x80
	s_addc_u32 s39, s39, 0
	s_add_i32 m0, s42, 0x4000
	s_nop 0
	global_load_lds_dwordx4 v140, s[34:35]
	s_add_i32 m0, s42, 0x6000
	s_nop 0
	global_load_lds_dwordx4 v144, s[34:35]
	s_add_i32 m0, s42, 0x10000
	s_nop 0
	global_load_lds_dwordx4 v142, s[38:39]
	s_add_i32 m0, s42, 0x12000
	s_nop 0
	global_load_lds_dwordx4 v146, s[38:39]
	s_add_u32 s34, s34, 0x80
	s_addc_u32 s35, s35, 0
	s_add_u32 s38, s38, 0x80
	s_addc_u32 s39, s39, 0
	s_add_i32 m0, s42, 0xc000
	s_nop 0
	global_load_lds_dwordx4 v140, s[34:35]
	s_add_i32 m0, s42, 0xe000
	s_nop 0
	global_load_lds_dwordx4 v144, s[34:35]
	s_add_i32 m0, s42, 0x18000
	s_nop 0
	global_load_lds_dwordx4 v142, s[38:39]
	s_add_i32 m0, s42, 0x1a000
	s_nop 0
	global_load_lds_dwordx4 v146, s[38:39]
	ds_read_b128 v[190:193], v181
	ds_read_b128 v[194:197], v181 offset:1024
	ds_read_b128 v[198:201], v181 offset:2048
	ds_read_b128 v[202:205], v181 offset:3072
	ds_read_b128 v[206:209], v182
	ds_read_b128 v[210:213], v182 offset:1024
	ds_read_b128 v[214:217], v182 offset:2048
	ds_read_b128 v[218:221], v182 offset:3072
	ds_read_b128 v[222:225], v182 offset:4096
	ds_read_b128 v[226:229], v182 offset:5120
	ds_read_b128 v[230:233], v182 offset:6144
	ds_read_b128 v[234:237], v182 offset:7168
	s_waitcnt lgkmcnt(0)
	v_mfma_f32_16x16x32_bf16 v[118:121], v[190:193], v[206:209], v[118:121]
	v_mfma_f32_16x16x32_bf16 v[114:117], v[198:201], v[206:209], v[114:117]
	v_mfma_f32_16x16x32_bf16 v[102:105], v[190:193], v[214:217], v[102:105]
	v_mfma_f32_16x16x32_bf16 v[98:101], v[198:201], v[214:217], v[98:101]
	v_mfma_f32_16x16x32_bf16 v[86:89], v[190:193], v[222:225], v[86:89]
	v_mfma_f32_16x16x32_bf16 v[82:85], v[198:201], v[222:225], v[82:85]
	v_mfma_f32_16x16x32_bf16 v[70:73], v[190:193], v[230:233], v[70:73]
	v_mfma_f32_16x16x32_bf16 v[66:69], v[198:201], v[230:233], v[66:69]
	v_mfma_f32_16x16x32_bf16 v[118:121], v[194:197], v[210:213], v[118:121]
	v_mfma_f32_16x16x32_bf16 v[114:117], v[202:205], v[210:213], v[114:117]
	v_mfma_f32_16x16x32_bf16 v[102:105], v[194:197], v[218:221], v[102:105]
	v_mfma_f32_16x16x32_bf16 v[98:101], v[202:205], v[218:221], v[98:101]
	v_mfma_f32_16x16x32_bf16 v[86:89], v[194:197], v[226:229], v[86:89]
	v_mfma_f32_16x16x32_bf16 v[82:85], v[202:205], v[226:229], v[82:85]
	v_mfma_f32_16x16x32_bf16 v[70:73], v[194:197], v[234:237], v[70:73]
	v_mfma_f32_16x16x32_bf16 v[66:69], v[202:205], v[234:237], v[66:69]
	s_waitcnt vmcnt(8)
	s_barrier
; #define PG8_STAGE(bufoff, gbase, voff) do { _Pragma("unroll") for (int _i = 0; _i < 2; ++_i) \
;         __builtin_amdgcn_global_load_lds((const unsigned*)((const char*)(gbase) + (voff)[_i]), (PG8_LAS unsigned*)(lds + (bufoff) + ldsw + _i * 8192), 16, 0, 0); } while (0)
; #define PG8_LDA(dst, b, h) do { _Pragma("unroll") for (int m = 0; m < 4; ++m) _Pragma("unroll") for (int k = 0; k < 2; ++k) dst[m][k] = *(const PG8_LAS bf16x8*)(lds + PG8_SA(b, h) + aoff + m * 2048 + k * 1024); } while (0)
; #define PG8_LDB(dst, b, h) do { _Pragma("unroll") for (int n = 0; n < 2; ++n) _Pragma("unroll") for (int k = 0; k < 2; ++k) dst[n][k] = *(const PG8_LAS bf16x8*)(lds + PG8_SB(b, h) + boff + n * 2048 + k * 1024); } while (0)
; #define PG8_MMA(ai, bj, At, Bt) do { __builtin_amdgcn_s_setprio(1); _Pragma("unroll") for (int m = 0; m < 4; ++m) _Pragma("unroll") for (int n = 0; n < 2; ++n) _Pragma("unroll") for (int k = 0; k < 2; ++k) \
;         acc[ai][bj][m][n] = __builtin_amdgcn_mfma_f32_16x16x32_bf16(Bt[n][k], At[m][k], acc[ai][bj][m][n], 0, 0, 0); __builtin_amdgcn_s_setprio(0); } while (0)
; #define PG8_WAIT_V(n) asm volatile("s_waitcnt vmcnt(" #n ")" ::: "memory")
; template <class Epi, class Sched, bool ALIGN_EPI = false, bool SP2 = false>
; __device__ __forceinline__ void gemm_phase(PG8_LAS unsigned char* lds, const Gemm g, const Sched& S, const Epi& E) {
;     ...
;             PG8_LDB(B0, 0, 0); PG8_LDB(B1, 0, 1); PG8_SCHED; PG8_LDA(At, 0, 0); PG8_STAGE(PG8_SA(1, 1), a1 + hstep, voffA);
;             PG8_WAIT_V(8); PG8_WAIT_L(0); PG8_BAR; PG8_MMA(0, 0, At, B0); PG8_MMA(0, 1, At, B1); PG8_BAR; PG8_SCHED;
;             PG8_LDA(At, 0, 1); PG8_STAGE(PG8_SB(0, 0), b2, voffB); PG8_STAGE(PG8_SB(0, 1), b2 + hstep, voffB); PG8_STAGE(PG8_SA(0, 0), a2, voffA);
;             PG8_WAIT_V(8); PG8_WAIT_L(0); PG8_BAR; PG8_MMA(1, 0, At, B0); PG8_MMA(1, 1, At, B1); PG8_BAR; PG8_SCHED;
;             PG8_LDB(B0, 1, 0); PG8_LDB(B1, 1, 1); PG8_SCHED; PG8_LDA(At, 1, 0); PG8_STAGE(PG8_SA(0, 1), a2 + hstep, voffA);
;             PG8_WAIT_V(8); PG8_WAIT_L(0); PG8_BAR; PG8_MMA(0, 0, At, B0); PG8_MMA(0, 1, At, B1); PG8_BAR; PG8_SCHED;
;             PG8_LDA(At, 1, 1); PG8_STAGE(PG8_SB(1, 0), b3, voffB); PG8_STAGE(PG8_SB(1, 1), b3 + hstep, voffB); PG8_STAGE(PG8_SA(1, 0), a3, voffA);
;             PG8_WAIT_V(8); PG8_WAIT_L(0); PG8_BAR; PG8_MMA(1, 0, At, B0); PG8_MMA(1, 1, At, B1); PG8_BAR; PG8_SCHED;
	ds_read_b128 v[190:193], v184
	ds_read_b128 v[194:197], v184 offset:1024
	ds_read_b128 v[198:201], v184 offset:2048
	ds_read_b128 v[202:205], v184 offset:3072
	ds_read_b128 v[206:209], v182 offset:32768
	ds_read_b128 v[210:213], v182 offset:33792
	ds_read_b128 v[214:217], v182 offset:34816
	ds_read_b128 v[218:221], v182 offset:35840
	ds_read_b128 v[222:225], v182 offset:36864
	ds_read_b128 v[226:229], v182 offset:37888
	ds_read_b128 v[230:233], v182 offset:38912
	ds_read_b128 v[234:237], v182 offset:39936
	s_add_u32 s34, s34, 0x80
	s_addc_u32 s35, s35, 0
	s_add_u32 s38, s38, 0x80
	s_addc_u32 s39, s39, 0
	s_mov_b32 m0, s42
	s_nop 0
	global_load_lds_dwordx4 v140, s[34:35]
	s_add_i32 m0, s42, 0x2000
	s_nop 0
	global_load_lds_dwordx4 v144, s[34:35]
	s_add_i32 m0, s42, 0x14000
	s_nop 0
	global_load_lds_dwordx4 v142, s[38:39]
	s_add_i32 m0, s42, 0x16000
	s_nop 0
	global_load_lds_dwordx4 v146, s[38:39]
	s_waitcnt lgkmcnt(0)
	v_mfma_f32_16x16x32_bf16 v[118:121], v[190:193], v[206:209], v[118:121]
	v_mfma_f32_16x16x32_bf16 v[114:117], v[198:201], v[206:209], v[114:117]
	v_mfma_f32_16x16x32_bf16 v[102:105], v[190:193], v[214:217], v[102:105]
	v_mfma_f32_16x16x32_bf16 v[98:101], v[198:201], v[214:217], v[98:101]
	v_mfma_f32_16x16x32_bf16 v[86:89], v[190:193], v[222:225], v[86:89]
	v_mfma_f32_16x16x32_bf16 v[82:85], v[198:201], v[222:225], v[82:85]
	v_mfma_f32_16x16x32_bf16 v[70:73], v[190:193], v[230:233], v[70:73]
	v_mfma_f32_16x16x32_bf16 v[66:69], v[198:201], v[230:233], v[66:69]
	v_mfma_f32_16x16x32_bf16 v[118:121], v[194:197], v[210:213], v[118:121]
	v_mfma_f32_16x16x32_bf16 v[114:117], v[202:205], v[210:213], v[114:117]
	v_mfma_f32_16x16x32_bf16 v[102:105], v[194:197], v[218:221], v[102:105]
	v_mfma_f32_16x16x32_bf16 v[98:101], v[202:205], v[218:221], v[98:101]
	v_mfma_f32_16x16x32_bf16 v[86:89], v[194:197], v[226:229], v[86:89]
	v_mfma_f32_16x16x32_bf16 v[82:85], v[202:205], v[226:229], v[82:85]
	v_mfma_f32_16x16x32_bf16 v[70:73], v[194:197], v[234:237], v[70:73]
	v_mfma_f32_16x16x32_bf16 v[66:69], v[202:205], v[234:237], v[66:69]
	s_waitcnt vmcnt(8)
	s_barrier
	ds_read_b128 v[190:193], v180
	ds_read_b128 v[194:197], v180 offset:1024
	ds_read_b128 v[198:201], v180 offset:2048
	ds_read_b128 v[202:205], v180 offset:3072
	ds_read_b128 v[206:209], v182 offset:16384
	ds_read_b128 v[210:213], v182 offset:17408
	ds_read_b128 v[214:217], v182 offset:18432
	ds_read_b128 v[218:221], v182 offset:19456
	ds_read_b128 v[222:225], v182 offset:20480
	ds_read_b128 v[226:229], v182 offset:21504
	ds_read_b128 v[230:233], v182 offset:22528
	ds_read_b128 v[234:237], v182 offset:23552
	s_add_u32 s34, s34, 0x80
	s_addc_u32 s35, s35, 0
	s_add_u32 s38, s38, 0x80
	s_addc_u32 s39, s39, 0
	s_add_i32 m0, s42, 0x8000
	s_nop 0
	global_load_lds_dwordx4 v140, s[34:35]
	s_add_i32 m0, s42, 0xa000
	s_nop 0
	global_load_lds_dwordx4 v144, s[34:35]
	s_add_i32 m0, s42, 0x1c000
	s_nop 0
	global_load_lds_dwordx4 v142, s[38:39]
	s_add_i32 m0, s42, 0x1e000
	s_nop 0
	global_load_lds_dwordx4 v146, s[38:39]
	s_waitcnt lgkmcnt(0)
	v_mfma_f32_16x16x32_bf16 v[118:121], v[190:193], v[206:209], v[118:121]
	v_mfma_f32_16x16x32_bf16 v[114:117], v[198:201], v[206:209], v[114:117]
	v_mfma_f32_16x16x32_bf16 v[102:105], v[190:193], v[214:217], v[102:105]
	v_mfma_f32_16x16x32_bf16 v[98:101], v[198:201], v[214:217], v[98:101]
	v_mfma_f32_16x16x32_bf16 v[86:89], v[190:193], v[222:225], v[86:89]
	v_mfma_f32_16x16x32_bf16 v[82:85], v[198:201], v[222:225], v[82:85]
	v_mfma_f32_16x16x32_bf16 v[70:73], v[190:193], v[230:233], v[70:73]
	v_mfma_f32_16x16x32_bf16 v[66:69], v[198:201], v[230:233], v[66:69]
	v_mfma_f32_16x16x32_bf16 v[118:121], v[194:197], v[210:213], v[118:121]
	v_mfma_f32_16x16x32_bf16 v[114:117], v[202:205], v[210:213], v[114:117]
	v_mfma_f32_16x16x32_bf16 v[102:105], v[194:197], v[218:221], v[102:105]
	v_mfma_f32_16x16x32_bf16 v[98:101], v[202:205], v[218:221], v[98:101]
	v_mfma_f32_16x16x32_bf16 v[86:89], v[194:197], v[226:229], v[86:89]
	v_mfma_f32_16x16x32_bf16 v[82:85], v[202:205], v[226:229], v[82:85]
	v_mfma_f32_16x16x32_bf16 v[70:73], v[194:197], v[234:237], v[70:73]
	v_mfma_f32_16x16x32_bf16 v[66:69], v[202:205], v[234:237], v[66:69]
	s_waitcnt vmcnt(8)
	s_barrier
	ds_read_b128 v[190:193], v183
	ds_read_b128 v[194:197], v183 offset:1024
	ds_read_b128 v[198:201], v183 offset:2048
	ds_read_b128 v[202:205], v183 offset:3072
	ds_read_b128 v[206:209], v182 offset:49152
	ds_read_b128 v[210:213], v182 offset:50176
	ds_read_b128 v[214:217], v182 offset:51200
	ds_read_b128 v[218:221], v182 offset:52224
	ds_read_b128 v[222:225], v182 offset:53248
	ds_read_b128 v[226:229], v182 offset:54272
	ds_read_b128 v[230:233], v182 offset:55296
	ds_read_b128 v[234:237], v182 offset:56320
	s_add_u32 s34, s34, 0x80
	s_addc_u32 s35, s35, 0
	s_add_u32 s38, s38, 0x80
	s_addc_u32 s39, s39, 0
	s_add_i32 m0, s42, 0x4000
	s_nop 0
	global_load_lds_dwordx4 v140, s[34:35]
	s_add_i32 m0, s42, 0x6000
	s_nop 0
	global_load_lds_dwordx4 v144, s[34:35]
	s_add_i32 m0, s42, 0x10000
	s_nop 0
	global_load_lds_dwordx4 v142, s[38:39]
	s_add_i32 m0, s42, 0x12000
	s_nop 0
	global_load_lds_dwordx4 v146, s[38:39]
	s_waitcnt lgkmcnt(0)
	v_mfma_f32_16x16x32_bf16 v[118:121], v[190:193], v[206:209], v[118:121]
	v_mfma_f32_16x16x32_bf16 v[114:117], v[198:201], v[206:209], v[114:117]
	v_mfma_f32_16x16x32_bf16 v[102:105], v[190:193], v[214:217], v[102:105]
	v_mfma_f32_16x16x32_bf16 v[98:101], v[198:201], v[214:217], v[98:101]
	v_mfma_f32_16x16x32_bf16 v[86:89], v[190:193], v[222:225], v[86:89]
	v_mfma_f32_16x16x32_bf16 v[82:85], v[198:201], v[222:225], v[82:85]
	v_mfma_f32_16x16x32_bf16 v[70:73], v[190:193], v[230:233], v[70:73]
	v_mfma_f32_16x16x32_bf16 v[66:69], v[198:201], v[230:233], v[66:69]
	v_mfma_f32_16x16x32_bf16 v[118:121], v[194:197], v[210:213], v[118:121]
	v_mfma_f32_16x16x32_bf16 v[114:117], v[202:205], v[210:213], v[114:117]
	v_mfma_f32_16x16x32_bf16 v[102:105], v[194:197], v[218:221], v[102:105]
	v_mfma_f32_16x16x32_bf16 v[98:101], v[202:205], v[218:221], v[98:101]
	v_mfma_f32_16x16x32_bf16 v[86:89], v[194:197], v[226:229], v[86:89]
	v_mfma_f32_16x16x32_bf16 v[82:85], v[202:205], v[226:229], v[82:85]
	v_mfma_f32_16x16x32_bf16 v[70:73], v[194:197], v[234:237], v[70:73]
	v_mfma_f32_16x16x32_bf16 v[66:69], v[202:205], v[234:237], v[66:69]
	s_waitcnt vmcnt(8)
	s_barrier
; #define PG8_STAGE(bufoff, gbase, voff) do { _Pragma("unroll") for (int _i = 0; _i < 2; ++_i) \
;         __builtin_amdgcn_global_load_lds((const unsigned*)((const char*)(gbase) + (voff)[_i]), (PG8_LAS unsigned*)(lds + (bufoff) + ldsw + _i * 8192), 16, 0, 0); } while (0)
; #define PG8_LDA(dst, b, h) do { _Pragma("unroll") for (int m = 0; m < 4; ++m) _Pragma("unroll") for (int k = 0; k < 2; ++k) dst[m][k] = *(const PG8_LAS bf16x8*)(lds + PG8_SA(b, h) + aoff + m * 2048 + k * 1024); } while (0)
; #define PG8_LDB(dst, b, h) do { _Pragma("unroll") for (int n = 0; n < 2; ++n) _Pragma("unroll") for (int k = 0; k < 2; ++k) dst[n][k] = *(const PG8_LAS bf16x8*)(lds + PG8_SB(b, h) + boff + n * 2048 + k * 1024); } while (0)
; #define PG8_MMA(ai, bj, At, Bt) do { __builtin_amdgcn_s_setprio(1); _Pragma("unroll") for (int m = 0; m < 4; ++m) _Pragma("unroll") for (int n = 0; n < 2; ++n) _Pragma("unroll") for (int k = 0; k < 2; ++k) \
;         acc[ai][bj][m][n] = __builtin_amdgcn_mfma_f32_16x16x32_bf16(Bt[n][k], At[m][k], acc[ai][bj][m][n], 0, 0, 0); __builtin_amdgcn_s_setprio(0); } while (0)
; #define PG8_WAIT_V(n) asm volatile("s_waitcnt vmcnt(" #n ")" ::: "memory")
; template <class Epi, class Sched, bool ALIGN_EPI = false, bool SP2 = false>
; __device__ __forceinline__ void gemm_phase(PG8_LAS unsigned char* lds, const Gemm g, const Sched& S, const Epi& E) {
;     ...
;             PG8_LDB(B0, 0, 0); PG8_LDB(B1, 0, 1); PG8_SCHED; PG8_LDA(At, 0, 0); PG8_STAGE(PG8_SA(1, 1), a1 + hstep, voffA);
;             PG8_WAIT_V(8); PG8_WAIT_L(0); PG8_BAR; PG8_MMA(0, 0, At, B0); PG8_MMA(0, 1, At, B1); PG8_BAR; PG8_SCHED;
;             PG8_LDA(At, 0, 1); PG8_STAGE(PG8_SB(0, 0), b2, voffB); PG8_STAGE(PG8_SB(0, 1), b2 + hstep, voffB); PG8_STAGE(PG8_SA(0, 0), a2, voffA);
;             PG8_WAIT_V(8); PG8_WAIT_L(0); PG8_BAR; PG8_MMA(1, 0, At, B0); PG8_MMA(1, 1, At, B1); PG8_BAR; PG8_SCHED;
;             PG8_LDB(B0, 1, 0); PG8_LDB(B1, 1, 1); PG8_SCHED; PG8_LDA(At, 1, 0); PG8_STAGE(PG8_SA(0, 1), a2 + hstep, voffA);
;             PG8_WAIT_V(8); PG8_WAIT_L(0); PG8_BAR; PG8_MMA(0, 0, At, B0); PG8_MMA(0, 1, At, B1); PG8_BAR; PG8_SCHED;
;             PG8_LDA(At, 1, 1); PG8_STAGE(PG8_SB(1, 0), b3, voffB); PG8_STAGE(PG8_SB(1, 1), b3 + hstep, voffB); PG8_STAGE(PG8_SA(1, 0), a3, voffA);
;             PG8_WAIT_V(8); PG8_WAIT_L(0); PG8_BAR; PG8_MMA(1, 0, At, B0); PG8_MMA(1, 1, At, B1); PG8_BAR; PG8_SCHED;
	ds_read_b128 v[190:193], v181
	ds_read_b128 v[194:197], v181 offset:1024
	ds_read_b128 v[198:201], v181 offset:2048
	ds_read_b128 v[202:205], v181 offset:3072
	ds_read_b128 v[206:209], v182
	ds_read_b128 v[210:213], v182 offset:1024
	ds_read_b128 v[214:217], v182 offset:2048
	ds_read_b128 v[218:221], v182 offset:3072
	ds_read_b128 v[222:225], v182 offset:4096
	ds_read_b128 v[226:229], v182 offset:5120
	ds_read_b128 v[230:233], v182 offset:6144
	ds_read_b128 v[234:237], v182 offset:7168
	s_add_u32 s34, s34, 0x80
	s_addc_u32 s35, s35, 0
	s_add_u32 s38, s38, 0x80
	s_addc_u32 s39, s39, 0
	s_add_i32 m0, s42, 0xc000
	s_nop 0
	global_load_lds_dwordx4 v140, s[34:35]
	s_add_i32 m0, s42, 0xe000
	s_nop 0
	global_load_lds_dwordx4 v144, s[34:35]
	s_add_i32 m0, s42, 0x18000
	s_nop 0
	global_load_lds_dwordx4 v142, s[38:39]
	s_add_i32 m0, s42, 0x1a000
	s_nop 0
	global_load_lds_dwordx4 v146, s[38:39]
	s_waitcnt lgkmcnt(0)
	v_mfma_f32_16x16x32_bf16 v[118:121], v[190:193], v[206:209], v[118:121]
	v_mfma_f32_16x16x32_bf16 v[114:117], v[198:201], v[206:209], v[114:117]
	v_mfma_f32_16x16x32_bf16 v[102:105], v[190:193], v[214:217], v[102:105]
	v_mfma_f32_16x16x32_bf16 v[98:101], v[198:201], v[214:217], v[98:101]
	v_mfma_f32_16x16x32_bf16 v[86:89], v[190:193], v[222:225], v[86:89]
	v_mfma_f32_16x16x32_bf16 v[82:85], v[198:201], v[222:225], v[82:85]
	v_mfma_f32_16x16x32_bf16 v[70:73], v[190:193], v[230:233], v[70:73]
	v_mfma_f32_16x16x32_bf16 v[66:69], v[198:201], v[230:233], v[66:69]
	v_mfma_f32_16x16x32_bf16 v[118:121], v[194:197], v[210:213], v[118:121]
	v_mfma_f32_16x16x32_bf16 v[114:117], v[202:205], v[210:213], v[114:117]
	v_mfma_f32_16x16x32_bf16 v[102:105], v[194:197], v[218:221], v[102:105]
	v_mfma_f32_16x16x32_bf16 v[98:101], v[202:205], v[218:221], v[98:101]
	v_mfma_f32_16x16x32_bf16 v[86:89], v[194:197], v[226:229], v[86:89]
	v_mfma_f32_16x16x32_bf16 v[82:85], v[202:205], v[226:229], v[82:85]
	v_mfma_f32_16x16x32_bf16 v[70:73], v[194:197], v[234:237], v[70:73]
	v_mfma_f32_16x16x32_bf16 v[66:69], v[202:205], v[234:237], v[66:69]
	s_waitcnt vmcnt(8)
	s_barrier
	ds_read_b128 v[190:193], v184
	ds_read_b128 v[194:197], v184 offset:1024
	ds_read_b128 v[198:201], v184 offset:2048
	ds_read_b128 v[202:205], v184 offset:3072
	ds_read_b128 v[206:209], v182 offset:32768
	ds_read_b128 v[210:213], v182 offset:33792
	ds_read_b128 v[214:217], v182 offset:34816
	ds_read_b128 v[218:221], v182 offset:35840
	ds_read_b128 v[222:225], v182 offset:36864
	ds_read_b128 v[226:229], v182 offset:37888
	ds_read_b128 v[230:233], v182 offset:38912
	ds_read_b128 v[234:237], v182 offset:39936
	s_add_u32 s34, s34, 0x80
	s_addc_u32 s35, s35, 0
	s_add_u32 s38, s38, 0x80
	s_addc_u32 s39, s39, 0
	s_mov_b32 m0, s42
	s_nop 0
	global_load_lds_dwordx4 v140, s[34:35]
	s_add_i32 m0, s42, 0x2000
	s_nop 0
	global_load_lds_dwordx4 v144, s[34:35]
	s_add_i32 m0, s42, 0x14000
	s_nop 0
	global_load_lds_dwordx4 v142, s[38:39]
	s_add_i32 m0, s42, 0x16000
	s_nop 0
	global_load_lds_dwordx4 v146, s[38:39]
	s_waitcnt lgkmcnt(0)
	v_mfma_f32_16x16x32_bf16 v[118:121], v[190:193], v[206:209], v[118:121]
	v_mfma_f32_16x16x32_bf16 v[114:117], v[198:201], v[206:209], v[114:117]
	v_mfma_f32_16x16x32_bf16 v[102:105], v[190:193], v[214:217], v[102:105]
	v_mfma_f32_16x16x32_bf16 v[98:101], v[198:201], v[214:217], v[98:101]
	v_mfma_f32_16x16x32_bf16 v[86:89], v[190:193], v[222:225], v[86:89]
	v_mfma_f32_16x16x32_bf16 v[82:85], v[198:201], v[222:225], v[82:85]
	v_mfma_f32_16x16x32_bf16 v[70:73], v[190:193], v[230:233], v[70:73]
	v_mfma_f32_16x16x32_bf16 v[66:69], v[198:201], v[230:233], v[66:69]
	v_mfma_f32_16x16x32_bf16 v[118:121], v[194:197], v[210:213], v[118:121]
	v_mfma_f32_16x16x32_bf16 v[114:117], v[202:205], v[210:213], v[114:117]
	v_mfma_f32_16x16x32_bf16 v[102:105], v[194:197], v[218:221], v[102:105]
	v_mfma_f32_16x16x32_bf16 v[98:101], v[202:205], v[218:221], v[98:101]
	v_mfma_f32_16x16x32_bf16 v[86:89], v[194:197], v[226:229], v[86:89]
	v_mfma_f32_16x16x32_bf16 v[82:85], v[202:205], v[226:229], v[82:85]
	v_mfma_f32_16x16x32_bf16 v[70:73], v[194:197], v[234:237], v[70:73]
	v_mfma_f32_16x16x32_bf16 v[66:69], v[202:205], v[234:237], v[66:69]
	s_waitcnt vmcnt(8)
	s_barrier
	ds_read_b128 v[190:193], v180
	ds_read_b128 v[194:197], v180 offset:1024
	ds_read_b128 v[198:201], v180 offset:2048
	ds_read_b128 v[202:205], v180 offset:3072
	ds_read_b128 v[206:209], v182 offset:16384
	ds_read_b128 v[210:213], v182 offset:17408
	ds_read_b128 v[214:217], v182 offset:18432
	ds_read_b128 v[218:221], v182 offset:19456
	ds_read_b128 v[222:225], v182 offset:20480
	ds_read_b128 v[226:229], v182 offset:21504
	ds_read_b128 v[230:233], v182 offset:22528
	ds_read_b128 v[234:237], v182 offset:23552
	s_add_u32 s34, s34, 0x80
	s_addc_u32 s35, s35, 0
	s_add_u32 s38, s38, 0x80
	s_addc_u32 s39, s39, 0
	s_add_i32 m0, s42, 0x8000
	s_nop 0
	global_load_lds_dwordx4 v140, s[34:35]
	s_add_i32 m0, s42, 0xa000
	s_nop 0
	global_load_lds_dwordx4 v144, s[34:35]
	s_add_i32 m0, s42, 0x1c000
	s_nop 0
	global_load_lds_dwordx4 v142, s[38:39]
	s_add_i32 m0, s42, 0x1e000
	s_nop 0
	global_load_lds_dwordx4 v146, s[38:39]
	s_waitcnt lgkmcnt(0)
	v_mfma_f32_16x16x32_bf16 v[118:121], v[190:193], v[206:209], v[118:121]
	v_mfma_f32_16x16x32_bf16 v[114:117], v[198:201], v[206:209], v[114:117]
	v_mfma_f32_16x16x32_bf16 v[102:105], v[190:193], v[214:217], v[102:105]
	v_mfma_f32_16x16x32_bf16 v[98:101], v[198:201], v[214:217], v[98:101]
	v_mfma_f32_16x16x32_bf16 v[86:89], v[190:193], v[222:225], v[86:89]
	v_mfma_f32_16x16x32_bf16 v[82:85], v[198:201], v[222:225], v[82:85]
	v_mfma_f32_16x16x32_bf16 v[70:73], v[190:193], v[230:233], v[70:73]
	v_mfma_f32_16x16x32_bf16 v[66:69], v[198:201], v[230:233], v[66:69]
	v_mfma_f32_16x16x32_bf16 v[118:121], v[194:197], v[210:213], v[118:121]
	v_mfma_f32_16x16x32_bf16 v[114:117], v[202:205], v[210:213], v[114:117]
	v_mfma_f32_16x16x32_bf16 v[102:105], v[194:197], v[218:221], v[102:105]
	v_mfma_f32_16x16x32_bf16 v[98:101], v[202:205], v[218:221], v[98:101]
	v_mfma_f32_16x16x32_bf16 v[86:89], v[194:197], v[226:229], v[86:89]
	v_mfma_f32_16x16x32_bf16 v[82:85], v[202:205], v[226:229], v[82:85]
	v_mfma_f32_16x16x32_bf16 v[70:73], v[194:197], v[234:237], v[70:73]
	v_mfma_f32_16x16x32_bf16 v[66:69], v[202:205], v[234:237], v[66:69]
	s_waitcnt vmcnt(8)
	s_barrier
; #define PG8_STAGE(bufoff, gbase, voff) do { _Pragma("unroll") for (int _i = 0; _i < 2; ++_i) \
;         __builtin_amdgcn_global_load_lds((const unsigned*)((const char*)(gbase) + (voff)[_i]), (PG8_LAS unsigned*)(lds + (bufoff) + ldsw + _i * 8192), 16, 0, 0); } while (0)
; #define PG8_LDA(dst, b, h) do { _Pragma("unroll") for (int m = 0; m < 4; ++m) _Pragma("unroll") for (int k = 0; k < 2; ++k) dst[m][k] = *(const PG8_LAS bf16x8*)(lds + PG8_SA(b, h) + aoff + m * 2048 + k * 1024); } while (0)
; #define PG8_LDB(dst, b, h) do { _Pragma("unroll") for (int n = 0; n < 2; ++n) _Pragma("unroll") for (int k = 0; k < 2; ++k) dst[n][k] = *(const PG8_LAS bf16x8*)(lds + PG8_SB(b, h) + boff + n * 2048 + k * 1024); } while (0)
; #define PG8_MMA(ai, bj, At, Bt) do { __builtin_amdgcn_s_setprio(1); _Pragma("unroll") for (int m = 0; m < 4; ++m) _Pragma("unroll") for (int n = 0; n < 2; ++n) _Pragma("unroll") for (int k = 0; k < 2; ++k) \
;         acc[ai][bj][m][n] = __builtin_amdgcn_mfma_f32_16x16x32_bf16(Bt[n][k], At[m][k], acc[ai][bj][m][n], 0, 0, 0); __builtin_amdgcn_s_setprio(0); } while (0)
; #define PG8_WAIT_V(n) asm volatile("s_waitcnt vmcnt(" #n ")" ::: "memory")
; template <class Epi, class Sched, bool ALIGN_EPI = false, bool SP2 = false>
; __device__ __forceinline__ void gemm_phase(PG8_LAS unsigned char* lds, const Gemm g, const Sched& S, const Epi& E) {
;     ...
;             PG8_LDB(B0, 0, 0); PG8_LDB(B1, 0, 1); PG8_SCHED; PG8_LDA(At, 0, 0); PG8_STAGE(PG8_SA(1, 1), a1 + hstep, voffA);
;             PG8_WAIT_V(8); PG8_WAIT_L(0); PG8_BAR; PG8_MMA(0, 0, At, B0); PG8_MMA(0, 1, At, B1); PG8_BAR; PG8_SCHED;
;             PG8_LDA(At, 0, 1); PG8_STAGE(PG8_SB(0, 0), b2, voffB); PG8_STAGE(PG8_SB(0, 1), b2 + hstep, voffB); PG8_STAGE(PG8_SA(0, 0), a2, voffA);
;             PG8_WAIT_V(8); PG8_WAIT_L(0); PG8_BAR; PG8_MMA(1, 0, At, B0); PG8_MMA(1, 1, At, B1); PG8_BAR; PG8_SCHED;
;             PG8_LDB(B0, 1, 0); PG8_LDB(B1, 1, 1); PG8_SCHED; PG8_LDA(At, 1, 0); PG8_STAGE(PG8_SA(0, 1), a2 + hstep, voffA);
;             PG8_WAIT_V(8); PG8_WAIT_L(0); PG8_BAR; PG8_MMA(0, 0, At, B0); PG8_MMA(0, 1, At, B1); PG8_BAR; PG8_SCHED;
;             PG8_LDA(At, 1, 1); PG8_STAGE(PG8_SB(1, 0), b3, voffB); PG8_STAGE(PG8_SB(1, 1), b3 + hstep, voffB); PG8_STAGE(PG8_SA(1, 0), a3, voffA);
;             PG8_WAIT_V(8); PG8_WAIT_L(0); PG8_BAR; PG8_MMA(1, 0, At, B0); PG8_MMA(1, 1, At, B1); PG8_BAR; PG8_SCHED;
	ds_read_b128 v[190:193], v183
	ds_read_b128 v[194:197], v183 offset:1024
	ds_read_b128 v[198:201], v183 offset:2048
	ds_read_b128 v[202:205], v183 offset:3072
	ds_read_b128 v[206:209], v182 offset:49152
	ds_read_b128 v[210:213], v182 offset:50176
	ds_read_b128 v[214:217], v182 offset:51200
	ds_read_b128 v[218:221], v182 offset:52224
	ds_read_b128 v[222:225], v182 offset:53248
	ds_read_b128 v[226:229], v182 offset:54272
	ds_read_b128 v[230:233], v182 offset:55296
	ds_read_b128 v[234:237], v182 offset:56320
	s_add_u32 s34, s34, 0x80
	s_addc_u32 s35, s35, 0
	s_add_u32 s38, s38, 0x80
	s_addc_u32 s39, s39, 0
	s_add_i32 m0, s42, 0x4000
	s_nop 0
	global_load_lds_dwordx4 v140, s[34:35]
	s_add_i32 m0, s42, 0x6000
	s_nop 0
	global_load_lds_dwordx4 v144, s[34:35]
	s_add_i32 m0, s42, 0x10000
	s_nop 0
	global_load_lds_dwordx4 v142, s[38:39]
	s_add_i32 m0, s42, 0x12000
	s_nop 0
	global_load_lds_dwordx4 v146, s[38:39]
	s_waitcnt lgkmcnt(0)
	v_mfma_f32_16x16x32_bf16 v[118:121], v[190:193], v[206:209], v[118:121]
	v_mfma_f32_16x16x32_bf16 v[114:117], v[198:201], v[206:209], v[114:117]
	v_mfma_f32_16x16x32_bf16 v[102:105], v[190:193], v[214:217], v[102:105]
	v_mfma_f32_16x16x32_bf16 v[98:101], v[198:201], v[214:217], v[98:101]
	v_mfma_f32_16x16x32_bf16 v[86:89], v[190:193], v[222:225], v[86:89]
	v_mfma_f32_16x16x32_bf16 v[82:85], v[198:201], v[222:225], v[82:85]
	v_mfma_f32_16x16x32_bf16 v[70:73], v[190:193], v[230:233], v[70:73]
	v_mfma_f32_16x16x32_bf16 v[66:69], v[198:201], v[230:233], v[66:69]
	v_mfma_f32_16x16x32_bf16 v[118:121], v[194:197], v[210:213], v[118:121]
	v_mfma_f32_16x16x32_bf16 v[114:117], v[202:205], v[210:213], v[114:117]
	v_mfma_f32_16x16x32_bf16 v[102:105], v[194:197], v[218:221], v[102:105]
	v_mfma_f32_16x16x32_bf16 v[98:101], v[202:205], v[218:221], v[98:101]
	v_mfma_f32_16x16x32_bf16 v[86:89], v[194:197], v[226:229], v[86:89]
	v_mfma_f32_16x16x32_bf16 v[82:85], v[202:205], v[226:229], v[82:85]
	v_mfma_f32_16x16x32_bf16 v[70:73], v[194:197], v[234:237], v[70:73]
	v_mfma_f32_16x16x32_bf16 v[66:69], v[202:205], v[234:237], v[66:69]
	s_waitcnt vmcnt(8)
	s_barrier
	ds_read_b128 v[190:193], v181
	ds_read_b128 v[194:197], v181 offset:1024
	ds_read_b128 v[198:201], v181 offset:2048
	ds_read_b128 v[202:205], v181 offset:3072
	ds_read_b128 v[206:209], v182
	ds_read_b128 v[210:213], v182 offset:1024
	ds_read_b128 v[214:217], v182 offset:2048
	ds_read_b128 v[218:221], v182 offset:3072
	ds_read_b128 v[222:225], v182 offset:4096
	ds_read_b128 v[226:229], v182 offset:5120
	ds_read_b128 v[230:233], v182 offset:6144
	ds_read_b128 v[234:237], v182 offset:7168
	s_add_u32 s34, s34, 0x80
	s_addc_u32 s35, s35, 0
	s_add_u32 s38, s38, 0x80
	s_addc_u32 s39, s39, 0
	s_add_i32 m0, s42, 0xc000
	s_nop 0
	global_load_lds_dwordx4 v140, s[34:35]
	s_add_i32 m0, s42, 0xe000
	s_nop 0
	global_load_lds_dwordx4 v144, s[34:35]
	s_add_i32 m0, s42, 0x18000
	s_nop 0
	global_load_lds_dwordx4 v142, s[38:39]
	s_add_i32 m0, s42, 0x1a000
	s_nop 0
	global_load_lds_dwordx4 v146, s[38:39]
	s_waitcnt lgkmcnt(0)
	v_mfma_f32_16x16x32_bf16 v[118:121], v[190:193], v[206:209], v[118:121]
	v_mfma_f32_16x16x32_bf16 v[114:117], v[198:201], v[206:209], v[114:117]
	v_mfma_f32_16x16x32_bf16 v[102:105], v[190:193], v[214:217], v[102:105]
	v_mfma_f32_16x16x32_bf16 v[98:101], v[198:201], v[214:217], v[98:101]
	v_mfma_f32_16x16x32_bf16 v[86:89], v[190:193], v[222:225], v[86:89]
	v_mfma_f32_16x16x32_bf16 v[82:85], v[198:201], v[222:225], v[82:85]
	v_mfma_f32_16x16x32_bf16 v[70:73], v[190:193], v[230:233], v[70:73]
	v_mfma_f32_16x16x32_bf16 v[66:69], v[198:201], v[230:233], v[66:69]
	v_mfma_f32_16x16x32_bf16 v[118:121], v[194:197], v[210:213], v[118:121]
	v_mfma_f32_16x16x32_bf16 v[114:117], v[202:205], v[210:213], v[114:117]
	v_mfma_f32_16x16x32_bf16 v[102:105], v[194:197], v[218:221], v[102:105]
	v_mfma_f32_16x16x32_bf16 v[98:101], v[202:205], v[218:221], v[98:101]
	v_mfma_f32_16x16x32_bf16 v[86:89], v[194:197], v[226:229], v[86:89]
	v_mfma_f32_16x16x32_bf16 v[82:85], v[202:205], v[226:229], v[82:85]
	v_mfma_f32_16x16x32_bf16 v[70:73], v[194:197], v[234:237], v[70:73]
	v_mfma_f32_16x16x32_bf16 v[66:69], v[202:205], v[234:237], v[66:69]
	s_waitcnt vmcnt(8)
	s_barrier
	ds_read_b128 v[190:193], v184
	ds_read_b128 v[194:197], v184 offset:1024
	ds_read_b128 v[198:201], v184 offset:2048
	ds_read_b128 v[202:205], v184 offset:3072
	ds_read_b128 v[206:209], v182 offset:32768
	ds_read_b128 v[210:213], v182 offset:33792
	ds_read_b128 v[214:217], v182 offset:34816
	ds_read_b128 v[218:221], v182 offset:35840
	ds_read_b128 v[222:225], v182 offset:36864
	ds_read_b128 v[226:229], v182 offset:37888
	ds_read_b128 v[230:233], v182 offset:38912
	ds_read_b128 v[234:237], v182 offset:39936
	s_add_u32 s34, s34, 0x80
	s_addc_u32 s35, s35, 0
	s_add_u32 s38, s38, 0x80
	s_addc_u32 s39, s39, 0
	s_mov_b32 m0, s42
	s_nop 0
	global_load_lds_dwordx4 v140, s[34:35]
	s_add_i32 m0, s42, 0x2000
	s_nop 0
	global_load_lds_dwordx4 v144, s[34:35]
	s_add_i32 m0, s42, 0x14000
	s_nop 0
	global_load_lds_dwordx4 v142, s[38:39]
	s_add_i32 m0, s42, 0x16000
	s_nop 0
	global_load_lds_dwordx4 v146, s[38:39]
	s_waitcnt lgkmcnt(0)
	v_mfma_f32_16x16x32_bf16 v[118:121], v[190:193], v[206:209], v[118:121]
	v_mfma_f32_16x16x32_bf16 v[114:117], v[198:201], v[206:209], v[114:117]
	v_mfma_f32_16x16x32_bf16 v[102:105], v[190:193], v[214:217], v[102:105]
	v_mfma_f32_16x16x32_bf16 v[98:101], v[198:201], v[214:217], v[98:101]
	v_mfma_f32_16x16x32_bf16 v[86:89], v[190:193], v[222:225], v[86:89]
	v_mfma_f32_16x16x32_bf16 v[82:85], v[198:201], v[222:225], v[82:85]
	v_mfma_f32_16x16x32_bf16 v[70:73], v[190:193], v[230:233], v[70:73]
	v_mfma_f32_16x16x32_bf16 v[66:69], v[198:201], v[230:233], v[66:69]
	v_mfma_f32_16x16x32_bf16 v[118:121], v[194:197], v[210:213], v[118:121]
	v_mfma_f32_16x16x32_bf16 v[114:117], v[202:205], v[210:213], v[114:117]
	v_mfma_f32_16x16x32_bf16 v[102:105], v[194:197], v[218:221], v[102:105]
	v_mfma_f32_16x16x32_bf16 v[98:101], v[202:205], v[218:221], v[98:101]
	v_mfma_f32_16x16x32_bf16 v[86:89], v[194:197], v[226:229], v[86:89]
	v_mfma_f32_16x16x32_bf16 v[82:85], v[202:205], v[226:229], v[82:85]
	v_mfma_f32_16x16x32_bf16 v[70:73], v[194:197], v[234:237], v[70:73]
	v_mfma_f32_16x16x32_bf16 v[66:69], v[202:205], v[234:237], v[66:69]
	s_waitcnt vmcnt(8)
	s_barrier
; #define PG8_STAGE(bufoff, gbase, voff) do { _Pragma("unroll") for (int _i = 0; _i < 2; ++_i) \
;         __builtin_amdgcn_global_load_lds((const unsigned*)((const char*)(gbase) + (voff)[_i]), (PG8_LAS unsigned*)(lds + (bufoff) + ldsw + _i * 8192), 16, 0, 0); } while (0)
; #define PG8_LDA(dst, b, h) do { _Pragma("unroll") for (int m = 0; m < 4; ++m) _Pragma("unroll") for (int k = 0; k < 2; ++k) dst[m][k] = *(const PG8_LAS bf16x8*)(lds + PG8_SA(b, h) + aoff + m * 2048 + k * 1024); } while (0)
; #define PG8_LDB(dst, b, h) do { _Pragma("unroll") for (int n = 0; n < 2; ++n) _Pragma("unroll") for (int k = 0; k < 2; ++k) dst[n][k] = *(const PG8_LAS bf16x8*)(lds + PG8_SB(b, h) + boff + n * 2048 + k * 1024); } while (0)
; #define PG8_MMA(ai, bj, At, Bt) do { __builtin_amdgcn_s_setprio(1); _Pragma("unroll") for (int m = 0; m < 4; ++m) _Pragma("unroll") for (int n = 0; n < 2; ++n) _Pragma("unroll") for (int k = 0; k < 2; ++k) \
;         acc[ai][bj][m][n] = __builtin_amdgcn_mfma_f32_16x16x32_bf16(Bt[n][k], At[m][k], acc[ai][bj][m][n], 0, 0, 0); __builtin_amdgcn_s_setprio(0); } while (0)
; #define PG8_WAIT_V(n) asm volatile("s_waitcnt vmcnt(" #n ")" ::: "memory")
; template <class Epi, class Sched, bool ALIGN_EPI = false, bool SP2 = false>
; __device__ __forceinline__ void gemm_phase(PG8_LAS unsigned char* lds, const Gemm g, const Sched& S, const Epi& E) {
;     ...
;             PG8_LDB(B0, 0, 0); PG8_LDB(B1, 0, 1); PG8_SCHED; PG8_LDA(At, 0, 0); PG8_STAGE(PG8_SA(1, 1), a1 + hstep, voffA);
;             PG8_WAIT_V(8); PG8_WAIT_L(0); PG8_BAR; PG8_MMA(0, 0, At, B0); PG8_MMA(0, 1, At, B1); PG8_BAR; PG8_SCHED;
;             PG8_LDA(At, 0, 1); PG8_STAGE(PG8_SB(0, 0), b2, voffB); PG8_STAGE(PG8_SB(0, 1), b2 + hstep, voffB); PG8_STAGE(PG8_SA(0, 0), a2, voffA);
;             PG8_WAIT_V(8); PG8_WAIT_L(0); PG8_BAR; PG8_MMA(1, 0, At, B0); PG8_MMA(1, 1, At, B1); PG8_BAR; PG8_SCHED;
;             PG8_LDB(B0, 1, 0); PG8_LDB(B1, 1, 1); PG8_SCHED; PG8_LDA(At, 1, 0); PG8_STAGE(PG8_SA(0, 1), a2 + hstep, voffA);
;             PG8_WAIT_V(8); PG8_WAIT_L(0); PG8_BAR; PG8_MMA(0, 0, At, B0); PG8_MMA(0, 1, At, B1); PG8_BAR; PG8_SCHED;
;             PG8_LDA(At, 1, 1); PG8_STAGE(PG8_SB(1, 0), b3, voffB); PG8_STAGE(PG8_SB(1, 1), b3 + hstep, voffB); PG8_STAGE(PG8_SA(1, 0), a3, voffA);
;             PG8_WAIT_V(8); PG8_WAIT_L(0); PG8_BAR; PG8_MMA(1, 0, At, B0); PG8_MMA(1, 1, At, B1); PG8_BAR; PG8_SCHED;
	ds_read_b128 v[190:193], v180
	ds_read_b128 v[194:197], v180 offset:1024
	ds_read_b128 v[198:201], v180 offset:2048
	ds_read_b128 v[202:205], v180 offset:3072
	ds_read_b128 v[206:209], v182 offset:16384
	ds_read_b128 v[210:213], v182 offset:17408
	ds_read_b128 v[214:217], v182 offset:18432
	ds_read_b128 v[218:221], v182 offset:19456
	ds_read_b128 v[222:225], v182 offset:20480
	ds_read_b128 v[226:229], v182 offset:21504
	ds_read_b128 v[230:233], v182 offset:22528
	ds_read_b128 v[234:237], v182 offset:23552
	s_add_u32 s34, s34, 0x80
	s_addc_u32 s35, s35, 0
	s_add_u32 s38, s38, 0x80
	s_addc_u32 s39, s39, 0
	s_add_i32 m0, s42, 0x8000
	s_nop 0
	global_load_lds_dwordx4 v140, s[34:35]
	s_add_i32 m0, s42, 0xa000
	s_nop 0
	global_load_lds_dwordx4 v144, s[34:35]
	s_add_i32 m0, s42, 0x1c000
	s_nop 0
	global_load_lds_dwordx4 v142, s[38:39]
	s_add_i32 m0, s42, 0x1e000
	s_nop 0
	global_load_lds_dwordx4 v146, s[38:39]
	s_waitcnt lgkmcnt(0)
	v_mfma_f32_16x16x32_bf16 v[118:121], v[190:193], v[206:209], v[118:121]
	v_mfma_f32_16x16x32_bf16 v[114:117], v[198:201], v[206:209], v[114:117]
	v_mfma_f32_16x16x32_bf16 v[102:105], v[190:193], v[214:217], v[102:105]
	v_mfma_f32_16x16x32_bf16 v[98:101], v[198:201], v[214:217], v[98:101]
	v_mfma_f32_16x16x32_bf16 v[86:89], v[190:193], v[222:225], v[86:89]
	v_mfma_f32_16x16x32_bf16 v[82:85], v[198:201], v[222:225], v[82:85]
	v_mfma_f32_16x16x32_bf16 v[70:73], v[190:193], v[230:233], v[70:73]
	v_mfma_f32_16x16x32_bf16 v[66:69], v[198:201], v[230:233], v[66:69]
	v_mfma_f32_16x16x32_bf16 v[118:121], v[194:197], v[210:213], v[118:121]
	v_mfma_f32_16x16x32_bf16 v[114:117], v[202:205], v[210:213], v[114:117]
	v_mfma_f32_16x16x32_bf16 v[102:105], v[194:197], v[218:221], v[102:105]
	v_mfma_f32_16x16x32_bf16 v[98:101], v[202:205], v[218:221], v[98:101]
	v_mfma_f32_16x16x32_bf16 v[86:89], v[194:197], v[226:229], v[86:89]
	v_mfma_f32_16x16x32_bf16 v[82:85], v[202:205], v[226:229], v[82:85]
	v_mfma_f32_16x16x32_bf16 v[70:73], v[194:197], v[234:237], v[70:73]
	v_mfma_f32_16x16x32_bf16 v[66:69], v[202:205], v[234:237], v[66:69]
	s_waitcnt vmcnt(8)
	s_barrier
	ds_read_b128 v[190:193], v183
	ds_read_b128 v[194:197], v183 offset:1024
	ds_read_b128 v[198:201], v183 offset:2048
	ds_read_b128 v[202:205], v183 offset:3072
	ds_read_b128 v[206:209], v182 offset:49152
	ds_read_b128 v[210:213], v182 offset:50176
	ds_read_b128 v[214:217], v182 offset:51200
	ds_read_b128 v[218:221], v182 offset:52224
	ds_read_b128 v[222:225], v182 offset:53248
	ds_read_b128 v[226:229], v182 offset:54272
	ds_read_b128 v[230:233], v182 offset:55296
	ds_read_b128 v[234:237], v182 offset:56320
	s_add_u32 s34, s34, 0x80
	s_addc_u32 s35, s35, 0
	s_add_u32 s38, s38, 0x80
	s_addc_u32 s39, s39, 0
	s_add_i32 m0, s42, 0x4000
	s_nop 0
	global_load_lds_dwordx4 v140, s[34:35]
	s_add_i32 m0, s42, 0x6000
	s_nop 0
	global_load_lds_dwordx4 v144, s[34:35]
	s_add_i32 m0, s42, 0x10000
	s_nop 0
	global_load_lds_dwordx4 v142, s[38:39]
	s_add_i32 m0, s42, 0x12000
	s_nop 0
	global_load_lds_dwordx4 v146, s[38:39]
	s_waitcnt lgkmcnt(0)
	v_mfma_f32_16x16x32_bf16 v[118:121], v[190:193], v[206:209], v[118:121]
	v_mfma_f32_16x16x32_bf16 v[114:117], v[198:201], v[206:209], v[114:117]
	v_mfma_f32_16x16x32_bf16 v[102:105], v[190:193], v[214:217], v[102:105]
	v_mfma_f32_16x16x32_bf16 v[98:101], v[198:201], v[214:217], v[98:101]
	v_mfma_f32_16x16x32_bf16 v[86:89], v[190:193], v[222:225], v[86:89]
	v_mfma_f32_16x16x32_bf16 v[82:85], v[198:201], v[222:225], v[82:85]
	v_mfma_f32_16x16x32_bf16 v[70:73], v[190:193], v[230:233], v[70:73]
	v_mfma_f32_16x16x32_bf16 v[66:69], v[198:201], v[230:233], v[66:69]
	v_mfma_f32_16x16x32_bf16 v[118:121], v[194:197], v[210:213], v[118:121]
	v_mfma_f32_16x16x32_bf16 v[114:117], v[202:205], v[210:213], v[114:117]
	v_mfma_f32_16x16x32_bf16 v[102:105], v[194:197], v[218:221], v[102:105]
	v_mfma_f32_16x16x32_bf16 v[98:101], v[202:205], v[218:221], v[98:101]
	v_mfma_f32_16x16x32_bf16 v[86:89], v[194:197], v[226:229], v[86:89]
	v_mfma_f32_16x16x32_bf16 v[82:85], v[202:205], v[226:229], v[82:85]
	v_mfma_f32_16x16x32_bf16 v[70:73], v[194:197], v[234:237], v[70:73]
	v_mfma_f32_16x16x32_bf16 v[66:69], v[202:205], v[234:237], v[66:69]
	s_waitcnt vmcnt(8)
	s_barrier
	ds_read_b128 v[190:193], v181
	ds_read_b128 v[194:197], v181 offset:1024
	ds_read_b128 v[198:201], v181 offset:2048
	ds_read_b128 v[202:205], v181 offset:3072
	ds_read_b128 v[206:209], v182
	ds_read_b128 v[210:213], v182 offset:1024
	ds_read_b128 v[214:217], v182 offset:2048
	ds_read_b128 v[218:221], v182 offset:3072
	ds_read_b128 v[222:225], v182 offset:4096
	ds_read_b128 v[226:229], v182 offset:5120
	ds_read_b128 v[230:233], v182 offset:6144
	ds_read_b128 v[234:237], v182 offset:7168
	s_add_u32 s34, s34, 0x80
	s_addc_u32 s35, s35, 0
	s_add_u32 s38, s38, 0x80
	s_addc_u32 s39, s39, 0
	s_add_i32 m0, s42, 0xc000
	s_nop 0
	global_load_lds_dwordx4 v140, s[34:35]
	s_add_i32 m0, s42, 0xe000
	s_nop 0
	global_load_lds_dwordx4 v144, s[34:35]
	s_add_i32 m0, s42, 0x18000
	s_nop 0
	global_load_lds_dwordx4 v142, s[38:39]
	s_add_i32 m0, s42, 0x1a000
	s_nop 0
	global_load_lds_dwordx4 v146, s[38:39]
	s_waitcnt lgkmcnt(0)
	v_mfma_f32_16x16x32_bf16 v[118:121], v[190:193], v[206:209], v[118:121]
	v_mfma_f32_16x16x32_bf16 v[114:117], v[198:201], v[206:209], v[114:117]
	v_mfma_f32_16x16x32_bf16 v[102:105], v[190:193], v[214:217], v[102:105]
	v_mfma_f32_16x16x32_bf16 v[98:101], v[198:201], v[214:217], v[98:101]
	v_mfma_f32_16x16x32_bf16 v[86:89], v[190:193], v[222:225], v[86:89]
	v_mfma_f32_16x16x32_bf16 v[82:85], v[198:201], v[222:225], v[82:85]
	v_mfma_f32_16x16x32_bf16 v[70:73], v[190:193], v[230:233], v[70:73]
	v_mfma_f32_16x16x32_bf16 v[66:69], v[198:201], v[230:233], v[66:69]
	v_mfma_f32_16x16x32_bf16 v[118:121], v[194:197], v[210:213], v[118:121]
	v_mfma_f32_16x16x32_bf16 v[114:117], v[202:205], v[210:213], v[114:117]
	v_mfma_f32_16x16x32_bf16 v[102:105], v[194:197], v[218:221], v[102:105]
	v_mfma_f32_16x16x32_bf16 v[98:101], v[202:205], v[218:221], v[98:101]
	v_mfma_f32_16x16x32_bf16 v[86:89], v[194:197], v[226:229], v[86:89]
	v_mfma_f32_16x16x32_bf16 v[82:85], v[202:205], v[226:229], v[82:85]
	v_mfma_f32_16x16x32_bf16 v[70:73], v[194:197], v[234:237], v[70:73]
	v_mfma_f32_16x16x32_bf16 v[66:69], v[202:205], v[234:237], v[66:69]
	s_waitcnt vmcnt(8)
	s_barrier
; #define PG8_STAGE(bufoff, gbase, voff) do { _Pragma("unroll") for (int _i = 0; _i < 2; ++_i) \
;         __builtin_amdgcn_global_load_lds((const unsigned*)((const char*)(gbase) + (voff)[_i]), (PG8_LAS unsigned*)(lds + (bufoff) + ldsw + _i * 8192), 16, 0, 0); } while (0)
; #define PG8_LDA(dst, b, h) do { _Pragma("unroll") for (int m = 0; m < 4; ++m) _Pragma("unroll") for (int k = 0; k < 2; ++k) dst[m][k] = *(const PG8_LAS bf16x8*)(lds + PG8_SA(b, h) + aoff + m * 2048 + k * 1024); } while (0)
; #define PG8_LDB(dst, b, h) do { _Pragma("unroll") for (int n = 0; n < 2; ++n) _Pragma("unroll") for (int k = 0; k < 2; ++k) dst[n][k] = *(const PG8_LAS bf16x8*)(lds + PG8_SB(b, h) + boff + n * 2048 + k * 1024); } while (0)
; #define PG8_MMA(ai, bj, At, Bt) do { __builtin_amdgcn_s_setprio(1); _Pragma("unroll") for (int m = 0; m < 4; ++m) _Pragma("unroll") for (int n = 0; n < 2; ++n) _Pragma("unroll") for (int k = 0; k < 2; ++k) \
;         acc[ai][bj][m][n] = __builtin_amdgcn_mfma_f32_16x16x32_bf16(Bt[n][k], At[m][k], acc[ai][bj][m][n], 0, 0, 0); __builtin_amdgcn_s_setprio(0); } while (0)
; #define PG8_WAIT_V(n) asm volatile("s_waitcnt vmcnt(" #n ")" ::: "memory")
; template <class Epi, class Sched, bool ALIGN_EPI = false, bool SP2 = false>
; __device__ __forceinline__ void gemm_phase(PG8_LAS unsigned char* lds, const Gemm g, const Sched& S, const Epi& E) {
;     ...
;             PG8_LDB(B0, 0, 0); PG8_LDB(B1, 0, 1); PG8_SCHED; PG8_LDA(At, 0, 0); PG8_STAGE(PG8_SA(1, 1), a1 + hstep, voffA);
;             PG8_WAIT_V(8); PG8_WAIT_L(0); PG8_BAR; PG8_MMA(0, 0, At, B0); PG8_MMA(0, 1, At, B1); PG8_BAR; PG8_SCHED;
;             PG8_LDA(At, 0, 1); PG8_STAGE(PG8_SB(0, 0), b2, voffB); PG8_STAGE(PG8_SB(0, 1), b2 + hstep, voffB); PG8_STAGE(PG8_SA(0, 0), a2, voffA);
;             PG8_WAIT_V(8); PG8_WAIT_L(0); PG8_BAR; PG8_MMA(1, 0, At, B0); PG8_MMA(1, 1, At, B1); PG8_BAR; PG8_SCHED;
;             PG8_LDB(B0, 1, 0); PG8_LDB(B1, 1, 1); PG8_SCHED; PG8_LDA(At, 1, 0); PG8_STAGE(PG8_SA(0, 1), a2 + hstep, voffA);
;             PG8_WAIT_V(8); PG8_WAIT_L(0); PG8_BAR; PG8_MMA(0, 0, At, B0); PG8_MMA(0, 1, At, B1); PG8_BAR; PG8_SCHED;
;             PG8_LDA(At, 1, 1); PG8_STAGE(PG8_SB(1, 0), b3, voffB); PG8_STAGE(PG8_SB(1, 1), b3 + hstep, voffB); PG8_STAGE(PG8_SA(1, 0), a3, voffA);
;             PG8_WAIT_V(8); PG8_WAIT_L(0); PG8_BAR; PG8_MMA(1, 0, At, B0); PG8_MMA(1, 1, At, B1); PG8_BAR; PG8_SCHED;
	ds_read_b128 v[190:193], v184
	ds_read_b128 v[194:197], v184 offset:1024
	ds_read_b128 v[198:201], v184 offset:2048
	ds_read_b128 v[202:205], v184 offset:3072
	ds_read_b128 v[206:209], v182 offset:32768
	ds_read_b128 v[210:213], v182 offset:33792
	ds_read_b128 v[214:217], v182 offset:34816
	ds_read_b128 v[218:221], v182 offset:35840
	ds_read_b128 v[222:225], v182 offset:36864
	ds_read_b128 v[226:229], v182 offset:37888
	ds_read_b128 v[230:233], v182 offset:38912
	ds_read_b128 v[234:237], v182 offset:39936
	s_waitcnt lgkmcnt(0)
	v_mfma_f32_16x16x32_bf16 v[118:121], v[190:193], v[206:209], v[118:121]
	v_mfma_f32_16x16x32_bf16 v[114:117], v[198:201], v[206:209], v[114:117]
	v_mfma_f32_16x16x32_bf16 v[102:105], v[190:193], v[214:217], v[102:105]
	v_mfma_f32_16x16x32_bf16 v[98:101], v[198:201], v[214:217], v[98:101]
	v_mfma_f32_16x16x32_bf16 v[86:89], v[190:193], v[222:225], v[86:89]
	v_mfma_f32_16x16x32_bf16 v[82:85], v[198:201], v[222:225], v[82:85]
	v_mfma_f32_16x16x32_bf16 v[70:73], v[190:193], v[230:233], v[70:73]
	v_mfma_f32_16x16x32_bf16 v[66:69], v[198:201], v[230:233], v[66:69]
	v_mfma_f32_16x16x32_bf16 v[118:121], v[194:197], v[210:213], v[118:121]
	v_mfma_f32_16x16x32_bf16 v[114:117], v[202:205], v[210:213], v[114:117]
	v_mfma_f32_16x16x32_bf16 v[102:105], v[194:197], v[218:221], v[102:105]
	v_mfma_f32_16x16x32_bf16 v[98:101], v[202:205], v[218:221], v[98:101]
	v_mfma_f32_16x16x32_bf16 v[86:89], v[194:197], v[226:229], v[86:89]
	v_mfma_f32_16x16x32_bf16 v[82:85], v[202:205], v[226:229], v[82:85]
	v_mfma_f32_16x16x32_bf16 v[70:73], v[194:197], v[234:237], v[70:73]
	v_mfma_f32_16x16x32_bf16 v[66:69], v[202:205], v[234:237], v[66:69]
	s_waitcnt vmcnt(4)
	s_barrier
	ds_read_b128 v[190:193], v180
	ds_read_b128 v[194:197], v180 offset:1024
	ds_read_b128 v[198:201], v180 offset:2048
	ds_read_b128 v[202:205], v180 offset:3072
	ds_read_b128 v[206:209], v182 offset:16384
	ds_read_b128 v[210:213], v182 offset:17408
	ds_read_b128 v[214:217], v182 offset:18432
	ds_read_b128 v[218:221], v182 offset:19456
	ds_read_b128 v[222:225], v182 offset:20480
	ds_read_b128 v[226:229], v182 offset:21504
	ds_read_b128 v[230:233], v182 offset:22528
	ds_read_b128 v[234:237], v182 offset:23552
	s_waitcnt lgkmcnt(0)
	v_mfma_f32_16x16x32_bf16 v[118:121], v[190:193], v[206:209], v[118:121]
	v_mfma_f32_16x16x32_bf16 v[114:117], v[198:201], v[206:209], v[114:117]
	v_mfma_f32_16x16x32_bf16 v[102:105], v[190:193], v[214:217], v[102:105]
	v_mfma_f32_16x16x32_bf16 v[98:101], v[198:201], v[214:217], v[98:101]
	v_mfma_f32_16x16x32_bf16 v[86:89], v[190:193], v[222:225], v[86:89]
	v_mfma_f32_16x16x32_bf16 v[82:85], v[198:201], v[222:225], v[82:85]
	v_mfma_f32_16x16x32_bf16 v[70:73], v[190:193], v[230:233], v[70:73]
	v_mfma_f32_16x16x32_bf16 v[66:69], v[198:201], v[230:233], v[66:69]
	v_mfma_f32_16x16x32_bf16 v[118:121], v[194:197], v[210:213], v[118:121]
	v_mfma_f32_16x16x32_bf16 v[114:117], v[202:205], v[210:213], v[114:117]
	v_mfma_f32_16x16x32_bf16 v[102:105], v[194:197], v[218:221], v[102:105]
	v_mfma_f32_16x16x32_bf16 v[98:101], v[202:205], v[218:221], v[98:101]
	v_mfma_f32_16x16x32_bf16 v[86:89], v[194:197], v[226:229], v[86:89]
	v_mfma_f32_16x16x32_bf16 v[82:85], v[202:205], v[226:229], v[82:85]
	v_mfma_f32_16x16x32_bf16 v[70:73], v[194:197], v[234:237], v[70:73]
	v_mfma_f32_16x16x32_bf16 v[66:69], v[202:205], v[234:237], v[66:69]
	s_waitcnt vmcnt(0)
	s_barrier
	ds_read_b128 v[190:193], v183
	ds_read_b128 v[194:197], v183 offset:1024
	ds_read_b128 v[198:201], v183 offset:2048
	ds_read_b128 v[202:205], v183 offset:3072
	ds_read_b128 v[206:209], v182 offset:49152
	ds_read_b128 v[210:213], v182 offset:50176
	ds_read_b128 v[214:217], v182 offset:51200
	ds_read_b128 v[218:221], v182 offset:52224
	ds_read_b128 v[222:225], v182 offset:53248
	ds_read_b128 v[226:229], v182 offset:54272
	ds_read_b128 v[230:233], v182 offset:55296
	ds_read_b128 v[234:237], v182 offset:56320
	s_waitcnt lgkmcnt(0)
	v_mfma_f32_16x16x32_bf16 v[118:121], v[190:193], v[206:209], v[118:121]
	v_mfma_f32_16x16x32_bf16 v[114:117], v[198:201], v[206:209], v[114:117]
	v_mfma_f32_16x16x32_bf16 v[102:105], v[190:193], v[214:217], v[102:105]
	v_mfma_f32_16x16x32_bf16 v[98:101], v[198:201], v[214:217], v[98:101]
	v_mfma_f32_16x16x32_bf16 v[86:89], v[190:193], v[222:225], v[86:89]
	v_mfma_f32_16x16x32_bf16 v[82:85], v[198:201], v[222:225], v[82:85]
	v_mfma_f32_16x16x32_bf16 v[70:73], v[190:193], v[230:233], v[70:73]
	v_mfma_f32_16x16x32_bf16 v[66:69], v[198:201], v[230:233], v[66:69]
	v_mfma_f32_16x16x32_bf16 v[118:121], v[194:197], v[210:213], v[118:121]
	v_mfma_f32_16x16x32_bf16 v[114:117], v[202:205], v[210:213], v[114:117]
	v_mfma_f32_16x16x32_bf16 v[102:105], v[194:197], v[218:221], v[102:105]
	v_mfma_f32_16x16x32_bf16 v[98:101], v[202:205], v[218:221], v[98:101]
	v_mfma_f32_16x16x32_bf16 v[86:89], v[194:197], v[226:229], v[86:89]
	v_mfma_f32_16x16x32_bf16 v[82:85], v[202:205], v[226:229], v[82:85]
	v_mfma_f32_16x16x32_bf16 v[70:73], v[194:197], v[234:237], v[70:73]
	v_mfma_f32_16x16x32_bf16 v[66:69], v[202:205], v[234:237], v[66:69]
	s_branch .LBB0_141
; #define PG8_STAGE(bufoff, gbase, voff) do { _Pragma("unroll") for (int _i = 0; _i < 2; ++_i) \
;         __builtin_amdgcn_global_load_lds((const unsigned*)((const char*)(gbase) + (voff)[_i]), (PG8_LAS unsigned*)(lds + (bufoff) + ldsw + _i * 8192), 16, 0, 0); } while (0)
; #define PG8_LDA(dst, b, h) do { _Pragma("unroll") for (int m = 0; m < 4; ++m) _Pragma("unroll") for (int k = 0; k < 2; ++k) dst[m][k] = *(const PG8_LAS bf16x8*)(lds + PG8_SA(b, h) + aoff + m * 2048 + k * 1024); } while (0)
; #define PG8_LDB(dst, b, h) do { _Pragma("unroll") for (int n = 0; n < 2; ++n) _Pragma("unroll") for (int k = 0; k < 2; ++k) dst[n][k] = *(const PG8_LAS bf16x8*)(lds + PG8_SB(b, h) + boff + n * 2048 + k * 1024); } while (0)
; template <class Epi, class Sched, bool ALIGN_EPI = false, bool SP2 = false>
; __device__ __forceinline__ void gemm_phase(PG8_LAS unsigned char* lds, const Gemm g, const Sched& S, const Epi& E) {
;     ...
;         for (int t = 0; t < nt; t += 2) {
;             const bool last = (t == nt - 2);
;             const char* a1 = cA + (size_t)(t + 1) * kstep;
;             const char* a2 = last ? nA : cA + (size_t)(t + 2) * kstep; const char* b2 = last ? nB : cB + (size_t)(t + 2) * kstep;
;             const char* a3 = a2 + kstep; const char* b3 = b2 + kstep;
;             if (last && has_next) S.a_ready(nxt);
;             if constexpr (SP2) {
;             PG8_LDB(B0, 0, 0); PG8_LDB(B1, 0, 1); PG8_SCHED; PG8_LDA(At, 0, 0); PG8_STAGE(PG8_SA(1, 1), a1 + hstep, voffA);
;             PG8_WAIT_V(8); PG8_WAIT_L(0); PG8_BAR; PG8_MMA(0, 0, At, B0); PG8_MMA(0, 1, At, B1); PG8_BAR; PG8_SCHED;
;             PG8_LDA(At, 0, 1); PG8_STAGE(PG8_SB(0, 0), b2, voffB); PG8_STAGE(PG8_SB(0, 1), b2 + hstep, voffB); PG8_STAGE(PG8_SA(0, 0), a2, voffA);
;             PG8_WAIT_V(8); PG8_WAIT_L(0); PG8_BAR; PG8_MMA(1, 0, At, B0); PG8_MMA(1, 1, At, B1); PG8_BAR; PG8_SCHED;
;             PG8_LDB(B0, 1, 0); PG8_LDB(B1, 1, 1); PG8_SCHED; PG8_LDA(At, 1, 0); PG8_STAGE(PG8_SA(0, 1), a2 + hstep, voffA);
;             PG8_WAIT_V(8); PG8_WAIT_L(0); PG8_BAR; PG8_MMA(0, 0, At, B0); PG8_MMA(0, 1, At, B1); PG8_BAR; PG8_SCHED;
;             PG8_LDA(At, 1, 1); PG8_STAGE(PG8_SB(1, 0), b3, voffB); PG8_STAGE(PG8_SB(1, 1), b3 + hstep, voffB); PG8_STAGE(PG8_SA(1, 0), a3, voffA);
;             PG8_WAIT_V(8); PG8_WAIT_L(0); PG8_BAR; PG8_MMA(1, 0, At, B0); PG8_MMA(1, 1, At, B1); PG8_BAR; PG8_SCHED;
.Lp1q_lean_q2:
	s_mov_b32 s34, s6
	s_mov_b32 s35, 0
	s_lshl_b64 s[34:35], s[34:35], 19
	s_add_u32 s34, s34, s66
	s_addc_u32 s35, s35, s67
	s_add_u32 s34, s34, 0x80
	s_addc_u32 s35, s35, 0
	s_add_u32 s34, s34, 0x40000
	s_addc_u32 s35, s35, 0
	s_mov_b32 s38, s0
	s_mov_b32 s39, 0
	s_lshl_b64 s[38:39], s[38:39], 19
	s_add_u32 s38, s38, s62
	s_addc_u32 s39, s39, s63
	s_add_u32 s38, s38, 0x80
	s_addc_u32 s39, s39, 0
	s_waitcnt vmcnt(0) lgkmcnt(0)
	s_barrier
	s_add_i32 m0, s42, 0xc000
	s_nop 0
	global_load_lds_dwordx4 v140, s[34:35]
	s_add_i32 m0, s42, 0xe000
	s_nop 0
	global_load_lds_dwordx4 v144, s[34:35]
	s_add_u32 s34, s34, 0x80
	s_addc_u32 s35, s35, 0
	s_add_u32 s38, s38, 0x80
	s_addc_u32 s39, s39, 0
	s_mov_b32 m0, s42
	s_nop 0
	global_load_lds_dwordx4 v140, s[34:35]
	s_add_i32 m0, s42, 0x2000
	s_nop 0
	global_load_lds_dwordx4 v144, s[34:35]
	s_add_i32 m0, s42, 0x14000
	s_nop 0
	global_load_lds_dwordx4 v142, s[38:39]
	s_add_i32 m0, s42, 0x16000
	s_nop 0
	global_load_lds_dwordx4 v146, s[38:39]
	s_add_u32 s34, s34, 0x80
	s_addc_u32 s35, s35, 0
	s_add_u32 s38, s38, 0x80
	s_addc_u32 s39, s39, 0
	s_add_i32 m0, s42, 0x8000
	s_nop 0
	global_load_lds_dwordx4 v140, s[34:35]
	s_add_i32 m0, s42, 0xa000
	s_nop 0
	global_load_lds_dwordx4 v144, s[34:35]
	s_add_i32 m0, s42, 0x1c000
	s_nop 0
	global_load_lds_dwordx4 v142, s[38:39]
	s_add_i32 m0, s42, 0x1e000
	s_nop 0
	global_load_lds_dwordx4 v146, s[38:39]
	ds_read_b128 v[130:133], v180
	ds_read_b128 v[134:137], v180 offset:1024
	ds_read_b128 v[158:161], v180 offset:2048
	ds_read_b128 v[186:189], v180 offset:3072
	ds_read_b128 v[206:209], v182 offset:16384
	ds_read_b128 v[210:213], v182 offset:17408
	ds_read_b128 v[214:217], v182 offset:18432
	ds_read_b128 v[218:221], v182 offset:19456
	ds_read_b128 v[222:225], v182 offset:20480
	ds_read_b128 v[226:229], v182 offset:21504
	ds_read_b128 v[230:233], v182 offset:22528
	ds_read_b128 v[234:237], v182 offset:23552
	s_waitcnt lgkmcnt(0)
	v_mfma_f32_16x16x32_bf16 v[62:65], v[130:133], v[206:209], v[62:65]
	v_mfma_f32_16x16x32_bf16 v[58:61], v[158:161], v[206:209], v[58:61]
	v_mfma_f32_16x16x32_bf16 v[46:49], v[130:133], v[214:217], v[46:49]
	v_mfma_f32_16x16x32_bf16 v[42:45], v[158:161], v[214:217], v[42:45]
	v_mfma_f32_16x16x32_bf16 v[30:33], v[130:133], v[222:225], v[30:33]
	v_mfma_f32_16x16x32_bf16 v[26:29], v[158:161], v[222:225], v[26:29]
	v_mfma_f32_16x16x32_bf16 v[14:17], v[130:133], v[230:233], v[14:17]
	v_mfma_f32_16x16x32_bf16 v[10:13], v[158:161], v[230:233], v[10:13]
	v_mfma_f32_16x16x32_bf16 v[62:65], v[134:137], v[210:213], v[62:65]
	v_mfma_f32_16x16x32_bf16 v[58:61], v[186:189], v[210:213], v[58:61]
	v_mfma_f32_16x16x32_bf16 v[46:49], v[134:137], v[218:221], v[46:49]
	v_mfma_f32_16x16x32_bf16 v[42:45], v[186:189], v[218:221], v[42:45]
	v_mfma_f32_16x16x32_bf16 v[30:33], v[134:137], v[226:229], v[30:33]
	v_mfma_f32_16x16x32_bf16 v[26:29], v[186:189], v[226:229], v[26:29]
	v_mfma_f32_16x16x32_bf16 v[14:17], v[134:137], v[234:237], v[14:17]
	v_mfma_f32_16x16x32_bf16 v[10:13], v[186:189], v[234:237], v[10:13]
	s_waitcnt vmcnt(8)
	s_barrier
	ds_read_b128 v[130:133], v183
	ds_read_b128 v[134:137], v183 offset:1024
	ds_read_b128 v[158:161], v183 offset:2048
	ds_read_b128 v[186:189], v183 offset:3072
	ds_read_b128 v[206:209], v182 offset:49152
	ds_read_b128 v[210:213], v182 offset:50176
	ds_read_b128 v[214:217], v182 offset:51200
	ds_read_b128 v[218:221], v182 offset:52224
	ds_read_b128 v[222:225], v182 offset:53248
	ds_read_b128 v[226:229], v182 offset:54272
	ds_read_b128 v[230:233], v182 offset:55296
	ds_read_b128 v[234:237], v182 offset:56320
	s_add_u32 s34, s34, 0x80
	s_addc_u32 s35, s35, 0
	s_add_u32 s38, s38, 0x80
	s_addc_u32 s39, s39, 0
	s_add_i32 m0, s42, 0x4000
	s_nop 0
	global_load_lds_dwordx4 v140, s[34:35]
	s_add_i32 m0, s42, 0x6000
	s_nop 0
	global_load_lds_dwordx4 v144, s[34:35]
	s_add_i32 m0, s42, 0x10000
	s_nop 0
	global_load_lds_dwordx4 v142, s[38:39]
	s_add_i32 m0, s42, 0x12000
	s_nop 0
	global_load_lds_dwordx4 v146, s[38:39]
	s_waitcnt lgkmcnt(0)
	v_mfma_f32_16x16x32_bf16 v[62:65], v[130:133], v[206:209], v[62:65]
	v_mfma_f32_16x16x32_bf16 v[58:61], v[158:161], v[206:209], v[58:61]
	v_mfma_f32_16x16x32_bf16 v[46:49], v[130:133], v[214:217], v[46:49]
	v_mfma_f32_16x16x32_bf16 v[42:45], v[158:161], v[214:217], v[42:45]
	v_mfma_f32_16x16x32_bf16 v[30:33], v[130:133], v[222:225], v[30:33]
	v_mfma_f32_16x16x32_bf16 v[26:29], v[158:161], v[222:225], v[26:29]
	v_mfma_f32_16x16x32_bf16 v[14:17], v[130:133], v[230:233], v[14:17]
	v_mfma_f32_16x16x32_bf16 v[10:13], v[158:161], v[230:233], v[10:13]
	v_mfma_f32_16x16x32_bf16 v[62:65], v[134:137], v[210:213], v[62:65]
	v_mfma_f32_16x16x32_bf16 v[58:61], v[186:189], v[210:213], v[58:61]
	v_mfma_f32_16x16x32_bf16 v[46:49], v[134:137], v[218:221], v[46:49]
	v_mfma_f32_16x16x32_bf16 v[42:45], v[186:189], v[218:221], v[42:45]
	v_mfma_f32_16x16x32_bf16 v[30:33], v[134:137], v[226:229], v[30:33]
	v_mfma_f32_16x16x32_bf16 v[26:29], v[186:189], v[226:229], v[26:29]
	v_mfma_f32_16x16x32_bf16 v[14:17], v[134:137], v[234:237], v[14:17]
	v_mfma_f32_16x16x32_bf16 v[10:13], v[186:189], v[234:237], v[10:13]
	s_waitcnt vmcnt(8)
	s_barrier
; #define PG8_STAGE(bufoff, gbase, voff) do { _Pragma("unroll") for (int _i = 0; _i < 2; ++_i) \
;         __builtin_amdgcn_global_load_lds((const unsigned*)((const char*)(gbase) + (voff)[_i]), (PG8_LAS unsigned*)(lds + (bufoff) + ldsw + _i * 8192), 16, 0, 0); } while (0)
; #define PG8_LDA(dst, b, h) do { _Pragma("unroll") for (int m = 0; m < 4; ++m) _Pragma("unroll") for (int k = 0; k < 2; ++k) dst[m][k] = *(const PG8_LAS bf16x8*)(lds + PG8_SA(b, h) + aoff + m * 2048 + k * 1024); } while (0)
; #define PG8_LDB(dst, b, h) do { _Pragma("unroll") for (int n = 0; n < 2; ++n) _Pragma("unroll") for (int k = 0; k < 2; ++k) dst[n][k] = *(const PG8_LAS bf16x8*)(lds + PG8_SB(b, h) + boff + n * 2048 + k * 1024); } while (0)
; #define PG8_MMA(ai, bj, At, Bt) do { __builtin_amdgcn_s_setprio(1); _Pragma("unroll") for (int m = 0; m < 4; ++m) _Pragma("unroll") for (int n = 0; n < 2; ++n) _Pragma("unroll") for (int k = 0; k < 2; ++k) \
;         acc[ai][bj][m][n] = __builtin_amdgcn_mfma_f32_16x16x32_bf16(Bt[n][k], At[m][k], acc[ai][bj][m][n], 0, 0, 0); __builtin_amdgcn_s_setprio(0); } while (0)
; #define PG8_WAIT_V(n) asm volatile("s_waitcnt vmcnt(" #n ")" ::: "memory")
; template <class Epi, class Sched, bool ALIGN_EPI = false, bool SP2 = false>
; __device__ __forceinline__ void gemm_phase(PG8_LAS unsigned char* lds, const Gemm g, const Sched& S, const Epi& E) {
;     ...
;             PG8_LDB(B0, 0, 0); PG8_LDB(B1, 0, 1); PG8_SCHED; PG8_LDA(At, 0, 0); PG8_STAGE(PG8_SA(1, 1), a1 + hstep, voffA);
;             PG8_WAIT_V(8); PG8_WAIT_L(0); PG8_BAR; PG8_MMA(0, 0, At, B0); PG8_MMA(0, 1, At, B1); PG8_BAR; PG8_SCHED;
;             PG8_LDA(At, 0, 1); PG8_STAGE(PG8_SB(0, 0), b2, voffB); PG8_STAGE(PG8_SB(0, 1), b2 + hstep, voffB); PG8_STAGE(PG8_SA(0, 0), a2, voffA);
;             PG8_WAIT_V(8); PG8_WAIT_L(0); PG8_BAR; PG8_MMA(1, 0, At, B0); PG8_MMA(1, 1, At, B1); PG8_BAR; PG8_SCHED;
;             PG8_LDB(B0, 1, 0); PG8_LDB(B1, 1, 1); PG8_SCHED; PG8_LDA(At, 1, 0); PG8_STAGE(PG8_SA(0, 1), a2 + hstep, voffA);
;             PG8_WAIT_V(8); PG8_WAIT_L(0); PG8_BAR; PG8_MMA(0, 0, At, B0); PG8_MMA(0, 1, At, B1); PG8_BAR; PG8_SCHED;
;             PG8_LDA(At, 1, 1); PG8_STAGE(PG8_SB(1, 0), b3, voffB); PG8_STAGE(PG8_SB(1, 1), b3 + hstep, voffB); PG8_STAGE(PG8_SA(1, 0), a3, voffA);
;             PG8_WAIT_V(8); PG8_WAIT_L(0); PG8_BAR; PG8_MMA(1, 0, At, B0); PG8_MMA(1, 1, At, B1); PG8_BAR; PG8_SCHED;
	ds_read_b128 v[130:133], v181
	ds_read_b128 v[134:137], v181 offset:1024
	ds_read_b128 v[158:161], v181 offset:2048
	ds_read_b128 v[186:189], v181 offset:3072
	ds_read_b128 v[206:209], v182
	ds_read_b128 v[210:213], v182 offset:1024
	ds_read_b128 v[214:217], v182 offset:2048
	ds_read_b128 v[218:221], v182 offset:3072
	ds_read_b128 v[222:225], v182 offset:4096
	ds_read_b128 v[226:229], v182 offset:5120
	ds_read_b128 v[230:233], v182 offset:6144
	ds_read_b128 v[234:237], v182 offset:7168
	s_add_u32 s34, s34, 0x80
	s_addc_u32 s35, s35, 0
	s_add_u32 s38, s38, 0x80
	s_addc_u32 s39, s39, 0
	s_add_i32 m0, s42, 0xc000
	s_nop 0
	global_load_lds_dwordx4 v140, s[34:35]
	s_add_i32 m0, s42, 0xe000
	s_nop 0
	global_load_lds_dwordx4 v144, s[34:35]
	s_add_i32 m0, s42, 0x18000
	s_nop 0
	global_load_lds_dwordx4 v142, s[38:39]
	s_add_i32 m0, s42, 0x1a000
	s_nop 0
	global_load_lds_dwordx4 v146, s[38:39]
	s_waitcnt lgkmcnt(0)
	v_mfma_f32_16x16x32_bf16 v[62:65], v[130:133], v[206:209], v[62:65]
	v_mfma_f32_16x16x32_bf16 v[58:61], v[158:161], v[206:209], v[58:61]
	v_mfma_f32_16x16x32_bf16 v[46:49], v[130:133], v[214:217], v[46:49]
	v_mfma_f32_16x16x32_bf16 v[42:45], v[158:161], v[214:217], v[42:45]
	v_mfma_f32_16x16x32_bf16 v[30:33], v[130:133], v[222:225], v[30:33]
	v_mfma_f32_16x16x32_bf16 v[26:29], v[158:161], v[222:225], v[26:29]
	v_mfma_f32_16x16x32_bf16 v[14:17], v[130:133], v[230:233], v[14:17]
	v_mfma_f32_16x16x32_bf16 v[10:13], v[158:161], v[230:233], v[10:13]
	v_mfma_f32_16x16x32_bf16 v[62:65], v[134:137], v[210:213], v[62:65]
	v_mfma_f32_16x16x32_bf16 v[58:61], v[186:189], v[210:213], v[58:61]
	v_mfma_f32_16x16x32_bf16 v[46:49], v[134:137], v[218:221], v[46:49]
	v_mfma_f32_16x16x32_bf16 v[42:45], v[186:189], v[218:221], v[42:45]
	v_mfma_f32_16x16x32_bf16 v[30:33], v[134:137], v[226:229], v[30:33]
	v_mfma_f32_16x16x32_bf16 v[26:29], v[186:189], v[226:229], v[26:29]
	v_mfma_f32_16x16x32_bf16 v[14:17], v[134:137], v[234:237], v[14:17]
	v_mfma_f32_16x16x32_bf16 v[10:13], v[186:189], v[234:237], v[10:13]
	s_waitcnt vmcnt(8)
	s_barrier
	ds_read_b128 v[130:133], v184
	ds_read_b128 v[134:137], v184 offset:1024
	ds_read_b128 v[158:161], v184 offset:2048
	ds_read_b128 v[186:189], v184 offset:3072
	ds_read_b128 v[206:209], v182 offset:32768
	ds_read_b128 v[210:213], v182 offset:33792
	ds_read_b128 v[214:217], v182 offset:34816
	ds_read_b128 v[218:221], v182 offset:35840
	ds_read_b128 v[222:225], v182 offset:36864
	ds_read_b128 v[226:229], v182 offset:37888
	ds_read_b128 v[230:233], v182 offset:38912
	ds_read_b128 v[234:237], v182 offset:39936
	s_add_u32 s34, s34, 0x80
	s_addc_u32 s35, s35, 0
	s_add_u32 s38, s38, 0x80
	s_addc_u32 s39, s39, 0
	s_mov_b32 m0, s42
	s_nop 0
	global_load_lds_dwordx4 v140, s[34:35]
	s_add_i32 m0, s42, 0x2000
	s_nop 0
	global_load_lds_dwordx4 v144, s[34:35]
	s_add_i32 m0, s42, 0x14000
	s_nop 0
	global_load_lds_dwordx4 v142, s[38:39]
	s_add_i32 m0, s42, 0x16000
	s_nop 0
	global_load_lds_dwordx4 v146, s[38:39]
	s_waitcnt lgkmcnt(0)
	v_mfma_f32_16x16x32_bf16 v[62:65], v[130:133], v[206:209], v[62:65]
	v_mfma_f32_16x16x32_bf16 v[58:61], v[158:161], v[206:209], v[58:61]
	v_mfma_f32_16x16x32_bf16 v[46:49], v[130:133], v[214:217], v[46:49]
	v_mfma_f32_16x16x32_bf16 v[42:45], v[158:161], v[214:217], v[42:45]
	v_mfma_f32_16x16x32_bf16 v[30:33], v[130:133], v[222:225], v[30:33]
	v_mfma_f32_16x16x32_bf16 v[26:29], v[158:161], v[222:225], v[26:29]
	v_mfma_f32_16x16x32_bf16 v[14:17], v[130:133], v[230:233], v[14:17]
	v_mfma_f32_16x16x32_bf16 v[10:13], v[158:161], v[230:233], v[10:13]
	v_mfma_f32_16x16x32_bf16 v[62:65], v[134:137], v[210:213], v[62:65]
	v_mfma_f32_16x16x32_bf16 v[58:61], v[186:189], v[210:213], v[58:61]
	v_mfma_f32_16x16x32_bf16 v[46:49], v[134:137], v[218:221], v[46:49]
	v_mfma_f32_16x16x32_bf16 v[42:45], v[186:189], v[218:221], v[42:45]
	v_mfma_f32_16x16x32_bf16 v[30:33], v[134:137], v[226:229], v[30:33]
	v_mfma_f32_16x16x32_bf16 v[26:29], v[186:189], v[226:229], v[26:29]
	v_mfma_f32_16x16x32_bf16 v[14:17], v[134:137], v[234:237], v[14:17]
	v_mfma_f32_16x16x32_bf16 v[10:13], v[186:189], v[234:237], v[10:13]
	s_waitcnt vmcnt(8)
	s_barrier
	ds_read_b128 v[130:133], v180
	ds_read_b128 v[134:137], v180 offset:1024
	ds_read_b128 v[158:161], v180 offset:2048
	ds_read_b128 v[186:189], v180 offset:3072
	ds_read_b128 v[206:209], v182 offset:16384
	ds_read_b128 v[210:213], v182 offset:17408
	ds_read_b128 v[214:217], v182 offset:18432
	ds_read_b128 v[218:221], v182 offset:19456
	ds_read_b128 v[222:225], v182 offset:20480
	ds_read_b128 v[226:229], v182 offset:21504
	ds_read_b128 v[230:233], v182 offset:22528
	ds_read_b128 v[234:237], v182 offset:23552
	s_add_u32 s34, s34, 0x80
	s_addc_u32 s35, s35, 0
	s_add_u32 s38, s38, 0x80
	s_addc_u32 s39, s39, 0
	s_add_i32 m0, s42, 0x8000
	s_nop 0
	global_load_lds_dwordx4 v140, s[34:35]
	s_add_i32 m0, s42, 0xa000
	s_nop 0
	global_load_lds_dwordx4 v144, s[34:35]
	s_add_i32 m0, s42, 0x1c000
	s_nop 0
	global_load_lds_dwordx4 v142, s[38:39]
	s_add_i32 m0, s42, 0x1e000
	s_nop 0
	global_load_lds_dwordx4 v146, s[38:39]
	s_waitcnt lgkmcnt(0)
	v_mfma_f32_16x16x32_bf16 v[62:65], v[130:133], v[206:209], v[62:65]
	v_mfma_f32_16x16x32_bf16 v[58:61], v[158:161], v[206:209], v[58:61]
	v_mfma_f32_16x16x32_bf16 v[46:49], v[130:133], v[214:217], v[46:49]
	v_mfma_f32_16x16x32_bf16 v[42:45], v[158:161], v[214:217], v[42:45]
	v_mfma_f32_16x16x32_bf16 v[30:33], v[130:133], v[222:225], v[30:33]
	v_mfma_f32_16x16x32_bf16 v[26:29], v[158:161], v[222:225], v[26:29]
	v_mfma_f32_16x16x32_bf16 v[14:17], v[130:133], v[230:233], v[14:17]
	v_mfma_f32_16x16x32_bf16 v[10:13], v[158:161], v[230:233], v[10:13]
	v_mfma_f32_16x16x32_bf16 v[62:65], v[134:137], v[210:213], v[62:65]
	v_mfma_f32_16x16x32_bf16 v[58:61], v[186:189], v[210:213], v[58:61]
	v_mfma_f32_16x16x32_bf16 v[46:49], v[134:137], v[218:221], v[46:49]
	v_mfma_f32_16x16x32_bf16 v[42:45], v[186:189], v[218:221], v[42:45]
	v_mfma_f32_16x16x32_bf16 v[30:33], v[134:137], v[226:229], v[30:33]
	v_mfma_f32_16x16x32_bf16 v[26:29], v[186:189], v[226:229], v[26:29]
	v_mfma_f32_16x16x32_bf16 v[14:17], v[134:137], v[234:237], v[14:17]
	v_mfma_f32_16x16x32_bf16 v[10:13], v[186:189], v[234:237], v[10:13]
	s_waitcnt vmcnt(8)
	s_barrier
; #define PG8_STAGE(bufoff, gbase, voff) do { _Pragma("unroll") for (int _i = 0; _i < 2; ++_i) \
;         __builtin_amdgcn_global_load_lds((const unsigned*)((const char*)(gbase) + (voff)[_i]), (PG8_LAS unsigned*)(lds + (bufoff) + ldsw + _i * 8192), 16, 0, 0); } while (0)
; #define PG8_LDA(dst, b, h) do { _Pragma("unroll") for (int m = 0; m < 4; ++m) _Pragma("unroll") for (int k = 0; k < 2; ++k) dst[m][k] = *(const PG8_LAS bf16x8*)(lds + PG8_SA(b, h) + aoff + m * 2048 + k * 1024); } while (0)
; #define PG8_LDB(dst, b, h) do { _Pragma("unroll") for (int n = 0; n < 2; ++n) _Pragma("unroll") for (int k = 0; k < 2; ++k) dst[n][k] = *(const PG8_LAS bf16x8*)(lds + PG8_SB(b, h) + boff + n * 2048 + k * 1024); } while (0)
; #define PG8_MMA(ai, bj, At, Bt) do { __builtin_amdgcn_s_setprio(1); _Pragma("unroll") for (int m = 0; m < 4; ++m) _Pragma("unroll") for (int n = 0; n < 2; ++n) _Pragma("unroll") for (int k = 0; k < 2; ++k) \
;         acc[ai][bj][m][n] = __builtin_amdgcn_mfma_f32_16x16x32_bf16(Bt[n][k], At[m][k], acc[ai][bj][m][n], 0, 0, 0); __builtin_amdgcn_s_setprio(0); } while (0)
; #define PG8_WAIT_V(n) asm volatile("s_waitcnt vmcnt(" #n ")" ::: "memory")
; template <class Epi, class Sched, bool ALIGN_EPI = false, bool SP2 = false>
; __device__ __forceinline__ void gemm_phase(PG8_LAS unsigned char* lds, const Gemm g, const Sched& S, const Epi& E) {
;     ...
;             PG8_LDB(B0, 0, 0); PG8_LDB(B1, 0, 1); PG8_SCHED; PG8_LDA(At, 0, 0); PG8_STAGE(PG8_SA(1, 1), a1 + hstep, voffA);
;             PG8_WAIT_V(8); PG8_WAIT_L(0); PG8_BAR; PG8_MMA(0, 0, At, B0); PG8_MMA(0, 1, At, B1); PG8_BAR; PG8_SCHED;
;             PG8_LDA(At, 0, 1); PG8_STAGE(PG8_SB(0, 0), b2, voffB); PG8_STAGE(PG8_SB(0, 1), b2 + hstep, voffB); PG8_STAGE(PG8_SA(0, 0), a2, voffA);
;             PG8_WAIT_V(8); PG8_WAIT_L(0); PG8_BAR; PG8_MMA(1, 0, At, B0); PG8_MMA(1, 1, At, B1); PG8_BAR; PG8_SCHED;
;             PG8_LDB(B0, 1, 0); PG8_LDB(B1, 1, 1); PG8_SCHED; PG8_LDA(At, 1, 0); PG8_STAGE(PG8_SA(0, 1), a2 + hstep, voffA);
;             PG8_WAIT_V(8); PG8_WAIT_L(0); PG8_BAR; PG8_MMA(0, 0, At, B0); PG8_MMA(0, 1, At, B1); PG8_BAR; PG8_SCHED;
;             PG8_LDA(At, 1, 1); PG8_STAGE(PG8_SB(1, 0), b3, voffB); PG8_STAGE(PG8_SB(1, 1), b3 + hstep, voffB); PG8_STAGE(PG8_SA(1, 0), a3, voffA);
;             PG8_WAIT_V(8); PG8_WAIT_L(0); PG8_BAR; PG8_MMA(1, 0, At, B0); PG8_MMA(1, 1, At, B1); PG8_BAR; PG8_SCHED;
	ds_read_b128 v[130:133], v183
	ds_read_b128 v[134:137], v183 offset:1024
	ds_read_b128 v[158:161], v183 offset:2048
	ds_read_b128 v[186:189], v183 offset:3072
	ds_read_b128 v[206:209], v182 offset:49152
	ds_read_b128 v[210:213], v182 offset:50176
	ds_read_b128 v[214:217], v182 offset:51200
	ds_read_b128 v[218:221], v182 offset:52224
	ds_read_b128 v[222:225], v182 offset:53248
	ds_read_b128 v[226:229], v182 offset:54272
	ds_read_b128 v[230:233], v182 offset:55296
	ds_read_b128 v[234:237], v182 offset:56320
	s_add_u32 s34, s34, 0x80
	s_addc_u32 s35, s35, 0
	s_add_u32 s38, s38, 0x80
	s_addc_u32 s39, s39, 0
	s_add_i32 m0, s42, 0x4000
	s_nop 0
	global_load_lds_dwordx4 v140, s[34:35]
	s_add_i32 m0, s42, 0x6000
	s_nop 0
	global_load_lds_dwordx4 v144, s[34:35]
	s_add_i32 m0, s42, 0x10000
	s_nop 0
	global_load_lds_dwordx4 v142, s[38:39]
	s_add_i32 m0, s42, 0x12000
	s_nop 0
	global_load_lds_dwordx4 v146, s[38:39]
	s_waitcnt lgkmcnt(0)
	v_mfma_f32_16x16x32_bf16 v[62:65], v[130:133], v[206:209], v[62:65]
	v_mfma_f32_16x16x32_bf16 v[58:61], v[158:161], v[206:209], v[58:61]
	v_mfma_f32_16x16x32_bf16 v[46:49], v[130:133], v[214:217], v[46:49]
	v_mfma_f32_16x16x32_bf16 v[42:45], v[158:161], v[214:217], v[42:45]
	v_mfma_f32_16x16x32_bf16 v[30:33], v[130:133], v[222:225], v[30:33]
	v_mfma_f32_16x16x32_bf16 v[26:29], v[158:161], v[222:225], v[26:29]
	v_mfma_f32_16x16x32_bf16 v[14:17], v[130:133], v[230:233], v[14:17]
	v_mfma_f32_16x16x32_bf16 v[10:13], v[158:161], v[230:233], v[10:13]
	v_mfma_f32_16x16x32_bf16 v[62:65], v[134:137], v[210:213], v[62:65]
	v_mfma_f32_16x16x32_bf16 v[58:61], v[186:189], v[210:213], v[58:61]
	v_mfma_f32_16x16x32_bf16 v[46:49], v[134:137], v[218:221], v[46:49]
	v_mfma_f32_16x16x32_bf16 v[42:45], v[186:189], v[218:221], v[42:45]
	v_mfma_f32_16x16x32_bf16 v[30:33], v[134:137], v[226:229], v[30:33]
	v_mfma_f32_16x16x32_bf16 v[26:29], v[186:189], v[226:229], v[26:29]
	v_mfma_f32_16x16x32_bf16 v[14:17], v[134:137], v[234:237], v[14:17]
	v_mfma_f32_16x16x32_bf16 v[10:13], v[186:189], v[234:237], v[10:13]
	s_waitcnt vmcnt(8)
	s_barrier
	ds_read_b128 v[130:133], v181
	ds_read_b128 v[134:137], v181 offset:1024
	ds_read_b128 v[158:161], v181 offset:2048
	ds_read_b128 v[186:189], v181 offset:3072
	ds_read_b128 v[206:209], v182
	ds_read_b128 v[210:213], v182 offset:1024
	ds_read_b128 v[214:217], v182 offset:2048
	ds_read_b128 v[218:221], v182 offset:3072
	ds_read_b128 v[222:225], v182 offset:4096
	ds_read_b128 v[226:229], v182 offset:5120
	ds_read_b128 v[230:233], v182 offset:6144
	ds_read_b128 v[234:237], v182 offset:7168
	s_add_u32 s34, s34, 0x80
	s_addc_u32 s35, s35, 0
	s_add_u32 s38, s38, 0x80
	s_addc_u32 s39, s39, 0
	s_add_i32 m0, s42, 0xc000
	s_nop 0
	global_load_lds_dwordx4 v140, s[34:35]
	s_add_i32 m0, s42, 0xe000
	s_nop 0
	global_load_lds_dwordx4 v144, s[34:35]
	s_add_i32 m0, s42, 0x18000
	s_nop 0
	global_load_lds_dwordx4 v142, s[38:39]
	s_add_i32 m0, s42, 0x1a000
	s_nop 0
	global_load_lds_dwordx4 v146, s[38:39]
	s_waitcnt lgkmcnt(0)
	v_mfma_f32_16x16x32_bf16 v[62:65], v[130:133], v[206:209], v[62:65]
	v_mfma_f32_16x16x32_bf16 v[58:61], v[158:161], v[206:209], v[58:61]
	v_mfma_f32_16x16x32_bf16 v[46:49], v[130:133], v[214:217], v[46:49]
	v_mfma_f32_16x16x32_bf16 v[42:45], v[158:161], v[214:217], v[42:45]
	v_mfma_f32_16x16x32_bf16 v[30:33], v[130:133], v[222:225], v[30:33]
	v_mfma_f32_16x16x32_bf16 v[26:29], v[158:161], v[222:225], v[26:29]
	v_mfma_f32_16x16x32_bf16 v[14:17], v[130:133], v[230:233], v[14:17]
	v_mfma_f32_16x16x32_bf16 v[10:13], v[158:161], v[230:233], v[10:13]
	v_mfma_f32_16x16x32_bf16 v[62:65], v[134:137], v[210:213], v[62:65]
	v_mfma_f32_16x16x32_bf16 v[58:61], v[186:189], v[210:213], v[58:61]
	v_mfma_f32_16x16x32_bf16 v[46:49], v[134:137], v[218:221], v[46:49]
	v_mfma_f32_16x16x32_bf16 v[42:45], v[186:189], v[218:221], v[42:45]
	v_mfma_f32_16x16x32_bf16 v[30:33], v[134:137], v[226:229], v[30:33]
	v_mfma_f32_16x16x32_bf16 v[26:29], v[186:189], v[226:229], v[26:29]
	v_mfma_f32_16x16x32_bf16 v[14:17], v[134:137], v[234:237], v[14:17]
	v_mfma_f32_16x16x32_bf16 v[10:13], v[186:189], v[234:237], v[10:13]
	s_waitcnt vmcnt(8)
	s_barrier
	ds_read_b128 v[130:133], v184
	ds_read_b128 v[134:137], v184 offset:1024
	ds_read_b128 v[158:161], v184 offset:2048
	ds_read_b128 v[186:189], v184 offset:3072
	ds_read_b128 v[206:209], v182 offset:32768
	ds_read_b128 v[210:213], v182 offset:33792
	ds_read_b128 v[214:217], v182 offset:34816
	ds_read_b128 v[218:221], v182 offset:35840
	ds_read_b128 v[222:225], v182 offset:36864
	ds_read_b128 v[226:229], v182 offset:37888
	ds_read_b128 v[230:233], v182 offset:38912
	ds_read_b128 v[234:237], v182 offset:39936
	s_add_u32 s34, s34, 0x80
	s_addc_u32 s35, s35, 0
	s_add_u32 s38, s38, 0x80
	s_addc_u32 s39, s39, 0
	s_mov_b32 m0, s42
	s_nop 0
	global_load_lds_dwordx4 v140, s[34:35]
	s_add_i32 m0, s42, 0x2000
	s_nop 0
	global_load_lds_dwordx4 v144, s[34:35]
	s_add_i32 m0, s42, 0x14000
	s_nop 0
	global_load_lds_dwordx4 v142, s[38:39]
	s_add_i32 m0, s42, 0x16000
	s_nop 0
	global_load_lds_dwordx4 v146, s[38:39]
	s_waitcnt lgkmcnt(0)
	v_mfma_f32_16x16x32_bf16 v[62:65], v[130:133], v[206:209], v[62:65]
	v_mfma_f32_16x16x32_bf16 v[58:61], v[158:161], v[206:209], v[58:61]
	v_mfma_f32_16x16x32_bf16 v[46:49], v[130:133], v[214:217], v[46:49]
	v_mfma_f32_16x16x32_bf16 v[42:45], v[158:161], v[214:217], v[42:45]
	v_mfma_f32_16x16x32_bf16 v[30:33], v[130:133], v[222:225], v[30:33]
	v_mfma_f32_16x16x32_bf16 v[26:29], v[158:161], v[222:225], v[26:29]
	v_mfma_f32_16x16x32_bf16 v[14:17], v[130:133], v[230:233], v[14:17]
	v_mfma_f32_16x16x32_bf16 v[10:13], v[158:161], v[230:233], v[10:13]
	v_mfma_f32_16x16x32_bf16 v[62:65], v[134:137], v[210:213], v[62:65]
	v_mfma_f32_16x16x32_bf16 v[58:61], v[186:189], v[210:213], v[58:61]
	v_mfma_f32_16x16x32_bf16 v[46:49], v[134:137], v[218:221], v[46:49]
	v_mfma_f32_16x16x32_bf16 v[42:45], v[186:189], v[218:221], v[42:45]
	v_mfma_f32_16x16x32_bf16 v[30:33], v[134:137], v[226:229], v[30:33]
	v_mfma_f32_16x16x32_bf16 v[26:29], v[186:189], v[226:229], v[26:29]
	v_mfma_f32_16x16x32_bf16 v[14:17], v[134:137], v[234:237], v[14:17]
	v_mfma_f32_16x16x32_bf16 v[10:13], v[186:189], v[234:237], v[10:13]
	s_waitcnt vmcnt(8)
	s_barrier
; #define PG8_STAGE(bufoff, gbase, voff) do { _Pragma("unroll") for (int _i = 0; _i < 2; ++_i) \
;         __builtin_amdgcn_global_load_lds((const unsigned*)((const char*)(gbase) + (voff)[_i]), (PG8_LAS unsigned*)(lds + (bufoff) + ldsw + _i * 8192), 16, 0, 0); } while (0)
; #define PG8_LDA(dst, b, h) do { _Pragma("unroll") for (int m = 0; m < 4; ++m) _Pragma("unroll") for (int k = 0; k < 2; ++k) dst[m][k] = *(const PG8_LAS bf16x8*)(lds + PG8_SA(b, h) + aoff + m * 2048 + k * 1024); } while (0)
; #define PG8_LDB(dst, b, h) do { _Pragma("unroll") for (int n = 0; n < 2; ++n) _Pragma("unroll") for (int k = 0; k < 2; ++k) dst[n][k] = *(const PG8_LAS bf16x8*)(lds + PG8_SB(b, h) + boff + n * 2048 + k * 1024); } while (0)
; #define PG8_MMA(ai, bj, At, Bt) do { __builtin_amdgcn_s_setprio(1); _Pragma("unroll") for (int m = 0; m < 4; ++m) _Pragma("unroll") for (int n = 0; n < 2; ++n) _Pragma("unroll") for (int k = 0; k < 2; ++k) \
;         acc[ai][bj][m][n] = __builtin_amdgcn_mfma_f32_16x16x32_bf16(Bt[n][k], At[m][k], acc[ai][bj][m][n], 0, 0, 0); __builtin_amdgcn_s_setprio(0); } while (0)
; #define PG8_WAIT_V(n) asm volatile("s_waitcnt vmcnt(" #n ")" ::: "memory")
; template <class Epi, class Sched, bool ALIGN_EPI = false, bool SP2 = false>
; __device__ __forceinline__ void gemm_phase(PG8_LAS unsigned char* lds, const Gemm g, const Sched& S, const Epi& E) {
;     ...
;             PG8_LDB(B0, 0, 0); PG8_LDB(B1, 0, 1); PG8_SCHED; PG8_LDA(At, 0, 0); PG8_STAGE(PG8_SA(1, 1), a1 + hstep, voffA);
;             PG8_WAIT_V(8); PG8_WAIT_L(0); PG8_BAR; PG8_MMA(0, 0, At, B0); PG8_MMA(0, 1, At, B1); PG8_BAR; PG8_SCHED;
;             PG8_LDA(At, 0, 1); PG8_STAGE(PG8_SB(0, 0), b2, voffB); PG8_STAGE(PG8_SB(0, 1), b2 + hstep, voffB); PG8_STAGE(PG8_SA(0, 0), a2, voffA);
;             PG8_WAIT_V(8); PG8_WAIT_L(0); PG8_BAR; PG8_MMA(1, 0, At, B0); PG8_MMA(1, 1, At, B1); PG8_BAR; PG8_SCHED;
;             PG8_LDB(B0, 1, 0); PG8_LDB(B1, 1, 1); PG8_SCHED; PG8_LDA(At, 1, 0); PG8_STAGE(PG8_SA(0, 1), a2 + hstep, voffA);
;             PG8_WAIT_V(8); PG8_WAIT_L(0); PG8_BAR; PG8_MMA(0, 0, At, B0); PG8_MMA(0, 1, At, B1); PG8_BAR; PG8_SCHED;
;             PG8_LDA(At, 1, 1); PG8_STAGE(PG8_SB(1, 0), b3, voffB); PG8_STAGE(PG8_SB(1, 1), b3 + hstep, voffB); PG8_STAGE(PG8_SA(1, 0), a3, voffA);
;             PG8_WAIT_V(8); PG8_WAIT_L(0); PG8_BAR; PG8_MMA(1, 0, At, B0); PG8_MMA(1, 1, At, B1); PG8_BAR; PG8_SCHED;
	ds_read_b128 v[130:133], v180
	ds_read_b128 v[134:137], v180 offset:1024
	ds_read_b128 v[158:161], v180 offset:2048
	ds_read_b128 v[186:189], v180 offset:3072
	ds_read_b128 v[206:209], v182 offset:16384
	ds_read_b128 v[210:213], v182 offset:17408
	ds_read_b128 v[214:217], v182 offset:18432
	ds_read_b128 v[218:221], v182 offset:19456
	ds_read_b128 v[222:225], v182 offset:20480
	ds_read_b128 v[226:229], v182 offset:21504
	ds_read_b128 v[230:233], v182 offset:22528
	ds_read_b128 v[234:237], v182 offset:23552
	s_add_u32 s34, s34, 0x80
	s_addc_u32 s35, s35, 0
	s_add_u32 s38, s38, 0x80
	s_addc_u32 s39, s39, 0
	s_add_i32 m0, s42, 0x8000
	s_nop 0
	global_load_lds_dwordx4 v140, s[34:35]
	s_add_i32 m0, s42, 0xa000
	s_nop 0
	global_load_lds_dwordx4 v144, s[34:35]
	s_add_i32 m0, s42, 0x1c000
	s_nop 0
	global_load_lds_dwordx4 v142, s[38:39]
	s_add_i32 m0, s42, 0x1e000
	s_nop 0
	global_load_lds_dwordx4 v146, s[38:39]
	s_waitcnt lgkmcnt(0)
	v_mfma_f32_16x16x32_bf16 v[62:65], v[130:133], v[206:209], v[62:65]
	v_mfma_f32_16x16x32_bf16 v[58:61], v[158:161], v[206:209], v[58:61]
	v_mfma_f32_16x16x32_bf16 v[46:49], v[130:133], v[214:217], v[46:49]
	v_mfma_f32_16x16x32_bf16 v[42:45], v[158:161], v[214:217], v[42:45]
	v_mfma_f32_16x16x32_bf16 v[30:33], v[130:133], v[222:225], v[30:33]
	v_mfma_f32_16x16x32_bf16 v[26:29], v[158:161], v[222:225], v[26:29]
	v_mfma_f32_16x16x32_bf16 v[14:17], v[130:133], v[230:233], v[14:17]
	v_mfma_f32_16x16x32_bf16 v[10:13], v[158:161], v[230:233], v[10:13]
	v_mfma_f32_16x16x32_bf16 v[62:65], v[134:137], v[210:213], v[62:65]
	v_mfma_f32_16x16x32_bf16 v[58:61], v[186:189], v[210:213], v[58:61]
	v_mfma_f32_16x16x32_bf16 v[46:49], v[134:137], v[218:221], v[46:49]
	v_mfma_f32_16x16x32_bf16 v[42:45], v[186:189], v[218:221], v[42:45]
	v_mfma_f32_16x16x32_bf16 v[30:33], v[134:137], v[226:229], v[30:33]
	v_mfma_f32_16x16x32_bf16 v[26:29], v[186:189], v[226:229], v[26:29]
	v_mfma_f32_16x16x32_bf16 v[14:17], v[134:137], v[234:237], v[14:17]
	v_mfma_f32_16x16x32_bf16 v[10:13], v[186:189], v[234:237], v[10:13]
	s_waitcnt vmcnt(8)
	s_barrier
	ds_read_b128 v[130:133], v183
	ds_read_b128 v[134:137], v183 offset:1024
	ds_read_b128 v[158:161], v183 offset:2048
	ds_read_b128 v[186:189], v183 offset:3072
	ds_read_b128 v[206:209], v182 offset:49152
	ds_read_b128 v[210:213], v182 offset:50176
	ds_read_b128 v[214:217], v182 offset:51200
	ds_read_b128 v[218:221], v182 offset:52224
	ds_read_b128 v[222:225], v182 offset:53248
	ds_read_b128 v[226:229], v182 offset:54272
	ds_read_b128 v[230:233], v182 offset:55296
	ds_read_b128 v[234:237], v182 offset:56320
	s_add_u32 s34, s34, 0x80
	s_addc_u32 s35, s35, 0
	s_add_u32 s38, s38, 0x80
	s_addc_u32 s39, s39, 0
	s_add_i32 m0, s42, 0x4000
	s_nop 0
	global_load_lds_dwordx4 v140, s[34:35]
	s_add_i32 m0, s42, 0x6000
	s_nop 0
	global_load_lds_dwordx4 v144, s[34:35]
	s_add_i32 m0, s42, 0x10000
	s_nop 0
	global_load_lds_dwordx4 v142, s[38:39]
	s_add_i32 m0, s42, 0x12000
	s_nop 0
	global_load_lds_dwordx4 v146, s[38:39]
	s_waitcnt lgkmcnt(0)
	v_mfma_f32_16x16x32_bf16 v[62:65], v[130:133], v[206:209], v[62:65]
	v_mfma_f32_16x16x32_bf16 v[58:61], v[158:161], v[206:209], v[58:61]
	v_mfma_f32_16x16x32_bf16 v[46:49], v[130:133], v[214:217], v[46:49]
	v_mfma_f32_16x16x32_bf16 v[42:45], v[158:161], v[214:217], v[42:45]
	v_mfma_f32_16x16x32_bf16 v[30:33], v[130:133], v[222:225], v[30:33]
	v_mfma_f32_16x16x32_bf16 v[26:29], v[158:161], v[222:225], v[26:29]
	v_mfma_f32_16x16x32_bf16 v[14:17], v[130:133], v[230:233], v[14:17]
	v_mfma_f32_16x16x32_bf16 v[10:13], v[158:161], v[230:233], v[10:13]
	v_mfma_f32_16x16x32_bf16 v[62:65], v[134:137], v[210:213], v[62:65]
	v_mfma_f32_16x16x32_bf16 v[58:61], v[186:189], v[210:213], v[58:61]
	v_mfma_f32_16x16x32_bf16 v[46:49], v[134:137], v[218:221], v[46:49]
	v_mfma_f32_16x16x32_bf16 v[42:45], v[186:189], v[218:221], v[42:45]
	v_mfma_f32_16x16x32_bf16 v[30:33], v[134:137], v[226:229], v[30:33]
	v_mfma_f32_16x16x32_bf16 v[26:29], v[186:189], v[226:229], v[26:29]
	v_mfma_f32_16x16x32_bf16 v[14:17], v[134:137], v[234:237], v[14:17]
	v_mfma_f32_16x16x32_bf16 v[10:13], v[186:189], v[234:237], v[10:13]
	s_waitcnt vmcnt(8)
	s_barrier
	ds_read_b128 v[130:133], v181
	ds_read_b128 v[134:137], v181 offset:1024
	ds_read_b128 v[158:161], v181 offset:2048
	ds_read_b128 v[186:189], v181 offset:3072
	ds_read_b128 v[206:209], v182
	ds_read_b128 v[210:213], v182 offset:1024
	ds_read_b128 v[214:217], v182 offset:2048
	ds_read_b128 v[218:221], v182 offset:3072
	ds_read_b128 v[222:225], v182 offset:4096
	ds_read_b128 v[226:229], v182 offset:5120
	ds_read_b128 v[230:233], v182 offset:6144
	ds_read_b128 v[234:237], v182 offset:7168
	s_add_u32 s34, s34, 0x80
	s_addc_u32 s35, s35, 0
	s_add_u32 s38, s38, 0x80
	s_addc_u32 s39, s39, 0
	s_add_i32 m0, s42, 0xc000
	s_nop 0
	global_load_lds_dwordx4 v140, s[34:35]
	s_add_i32 m0, s42, 0xe000
	s_nop 0
	global_load_lds_dwordx4 v144, s[34:35]
	s_add_i32 m0, s42, 0x18000
	s_nop 0
	global_load_lds_dwordx4 v142, s[38:39]
	s_add_i32 m0, s42, 0x1a000
	s_nop 0
	global_load_lds_dwordx4 v146, s[38:39]
	s_waitcnt lgkmcnt(0)
	v_mfma_f32_16x16x32_bf16 v[62:65], v[130:133], v[206:209], v[62:65]
	v_mfma_f32_16x16x32_bf16 v[58:61], v[158:161], v[206:209], v[58:61]
	v_mfma_f32_16x16x32_bf16 v[46:49], v[130:133], v[214:217], v[46:49]
	v_mfma_f32_16x16x32_bf16 v[42:45], v[158:161], v[214:217], v[42:45]
	v_mfma_f32_16x16x32_bf16 v[30:33], v[130:133], v[222:225], v[30:33]
	v_mfma_f32_16x16x32_bf16 v[26:29], v[158:161], v[222:225], v[26:29]
	v_mfma_f32_16x16x32_bf16 v[14:17], v[130:133], v[230:233], v[14:17]
	v_mfma_f32_16x16x32_bf16 v[10:13], v[158:161], v[230:233], v[10:13]
	v_mfma_f32_16x16x32_bf16 v[62:65], v[134:137], v[210:213], v[62:65]
	v_mfma_f32_16x16x32_bf16 v[58:61], v[186:189], v[210:213], v[58:61]
	v_mfma_f32_16x16x32_bf16 v[46:49], v[134:137], v[218:221], v[46:49]
	v_mfma_f32_16x16x32_bf16 v[42:45], v[186:189], v[218:221], v[42:45]
	v_mfma_f32_16x16x32_bf16 v[30:33], v[134:137], v[226:229], v[30:33]
	v_mfma_f32_16x16x32_bf16 v[26:29], v[186:189], v[226:229], v[26:29]
	v_mfma_f32_16x16x32_bf16 v[14:17], v[134:137], v[234:237], v[14:17]
	v_mfma_f32_16x16x32_bf16 v[10:13], v[186:189], v[234:237], v[10:13]
	s_waitcnt vmcnt(8)
	s_barrier
; #define PG8_STAGE(bufoff, gbase, voff) do { _Pragma("unroll") for (int _i = 0; _i < 2; ++_i) \
;         __builtin_amdgcn_global_load_lds((const unsigned*)((const char*)(gbase) + (voff)[_i]), (PG8_LAS unsigned*)(lds + (bufoff) + ldsw + _i * 8192), 16, 0, 0); } while (0)
; #define PG8_LDA(dst, b, h) do { _Pragma("unroll") for (int m = 0; m < 4; ++m) _Pragma("unroll") for (int k = 0; k < 2; ++k) dst[m][k] = *(const PG8_LAS bf16x8*)(lds + PG8_SA(b, h) + aoff + m * 2048 + k * 1024); } while (0)
; #define PG8_LDB(dst, b, h) do { _Pragma("unroll") for (int n = 0; n < 2; ++n) _Pragma("unroll") for (int k = 0; k < 2; ++k) dst[n][k] = *(const PG8_LAS bf16x8*)(lds + PG8_SB(b, h) + boff + n * 2048 + k * 1024); } while (0)
; template <class Epi, class Sched, bool ALIGN_EPI = false, bool SP2 = false>
; __device__ __forceinline__ void gemm_phase(PG8_LAS unsigned char* lds, const Gemm g, const Sched& S, const Epi& E) {
;     ...
;         for (int t = 0; t < nt; t += 2) {
;             const bool last = (t == nt - 2);
;             const char* a1 = cA + (size_t)(t + 1) * kstep;
;             const char* a2 = last ? nA : cA + (size_t)(t + 2) * kstep; const char* b2 = last ? nB : cB + (size_t)(t + 2) * kstep;
;             const char* a3 = a2 + kstep; const char* b3 = b2 + kstep;
;             if (last && has_next) S.a_ready(nxt);
;             if constexpr (SP2) {
;             PG8_LDB(B0, 0, 0); PG8_LDB(B1, 0, 1); PG8_SCHED; PG8_LDA(At, 0, 0); PG8_STAGE(PG8_SA(1, 1), a1 + hstep, voffA);
;             PG8_WAIT_V(8); PG8_WAIT_L(0); PG8_BAR; PG8_MMA(0, 0, At, B0); PG8_MMA(0, 1, At, B1); PG8_BAR; PG8_SCHED;
;             PG8_LDA(At, 0, 1); PG8_STAGE(PG8_SB(0, 0), b2, voffB); PG8_STAGE(PG8_SB(0, 1), b2 + hstep, voffB); PG8_STAGE(PG8_SA(0, 0), a2, voffA);
;             PG8_WAIT_V(8); PG8_WAIT_L(0); PG8_BAR; PG8_MMA(1, 0, At, B0); PG8_MMA(1, 1, At, B1); PG8_BAR; PG8_SCHED;
;             PG8_LDB(B0, 1, 0); PG8_LDB(B1, 1, 1); PG8_SCHED; PG8_LDA(At, 1, 0); PG8_STAGE(PG8_SA(0, 1), a2 + hstep, voffA);
;             PG8_WAIT_V(8); PG8_WAIT_L(0); PG8_BAR; PG8_MMA(0, 0, At, B0); PG8_MMA(0, 1, At, B1); PG8_BAR; PG8_SCHED;
;             PG8_LDA(At, 1, 1); PG8_STAGE(PG8_SB(1, 0), b3, voffB); PG8_STAGE(PG8_SB(1, 1), b3 + hstep, voffB); PG8_STAGE(PG8_SA(1, 0), a3, voffA);
;             PG8_WAIT_V(8); PG8_WAIT_L(0); PG8_BAR; PG8_MMA(1, 0, At, B0); PG8_MMA(1, 1, At, B1); PG8_BAR; PG8_SCHED;
	ds_read_b128 v[130:133], v184
	ds_read_b128 v[134:137], v184 offset:1024
	ds_read_b128 v[158:161], v184 offset:2048
	ds_read_b128 v[186:189], v184 offset:3072
	ds_read_b128 v[206:209], v182 offset:32768
	ds_read_b128 v[210:213], v182 offset:33792
	ds_read_b128 v[214:217], v182 offset:34816
	ds_read_b128 v[218:221], v182 offset:35840
	ds_read_b128 v[222:225], v182 offset:36864
	ds_read_b128 v[226:229], v182 offset:37888
	ds_read_b128 v[230:233], v182 offset:38912
	ds_read_b128 v[234:237], v182 offset:39936
	s_add_u32 s34, s34, 0x80
	s_addc_u32 s35, s35, 0
	s_add_u32 s38, s38, 0x80
	s_addc_u32 s39, s39, 0
	s_mov_b32 m0, s42
	s_nop 0
	global_load_lds_dwordx4 v140, s[34:35]
	s_add_i32 m0, s42, 0x2000
	s_nop 0
	global_load_lds_dwordx4 v144, s[34:35]
	s_add_i32 m0, s42, 0x14000
	s_nop 0
	global_load_lds_dwordx4 v142, s[38:39]
	s_add_i32 m0, s42, 0x16000
	s_nop 0
	global_load_lds_dwordx4 v146, s[38:39]
	s_waitcnt lgkmcnt(0)
	v_mfma_f32_16x16x32_bf16 v[62:65], v[130:133], v[206:209], v[62:65]
	v_mfma_f32_16x16x32_bf16 v[58:61], v[158:161], v[206:209], v[58:61]
	v_mfma_f32_16x16x32_bf16 v[46:49], v[130:133], v[214:217], v[46:49]
	v_mfma_f32_16x16x32_bf16 v[42:45], v[158:161], v[214:217], v[42:45]
	v_mfma_f32_16x16x32_bf16 v[30:33], v[130:133], v[222:225], v[30:33]
	v_mfma_f32_16x16x32_bf16 v[26:29], v[158:161], v[222:225], v[26:29]
	v_mfma_f32_16x16x32_bf16 v[14:17], v[130:133], v[230:233], v[14:17]
	v_mfma_f32_16x16x32_bf16 v[10:13], v[158:161], v[230:233], v[10:13]
	v_mfma_f32_16x16x32_bf16 v[62:65], v[134:137], v[210:213], v[62:65]
	v_mfma_f32_16x16x32_bf16 v[58:61], v[186:189], v[210:213], v[58:61]
	v_mfma_f32_16x16x32_bf16 v[46:49], v[134:137], v[218:221], v[46:49]
	v_mfma_f32_16x16x32_bf16 v[42:45], v[186:189], v[218:221], v[42:45]
	v_mfma_f32_16x16x32_bf16 v[30:33], v[134:137], v[226:229], v[30:33]
	v_mfma_f32_16x16x32_bf16 v[26:29], v[186:189], v[226:229], v[26:29]
	v_mfma_f32_16x16x32_bf16 v[14:17], v[134:137], v[234:237], v[14:17]
	v_mfma_f32_16x16x32_bf16 v[10:13], v[186:189], v[234:237], v[10:13]
	s_waitcnt vmcnt(8)
	s_barrier
	ds_read_b128 v[130:133], v180
	ds_read_b128 v[134:137], v180 offset:1024
	ds_read_b128 v[158:161], v180 offset:2048
	ds_read_b128 v[186:189], v180 offset:3072
	ds_read_b128 v[206:209], v182 offset:16384
	ds_read_b128 v[210:213], v182 offset:17408
	ds_read_b128 v[214:217], v182 offset:18432
	ds_read_b128 v[218:221], v182 offset:19456
	ds_read_b128 v[222:225], v182 offset:20480
	ds_read_b128 v[226:229], v182 offset:21504
	ds_read_b128 v[230:233], v182 offset:22528
	ds_read_b128 v[234:237], v182 offset:23552
	s_add_u32 s34, s34, 0x80
	s_addc_u32 s35, s35, 0
	s_add_u32 s38, s38, 0x80
	s_addc_u32 s39, s39, 0
	s_add_i32 m0, s42, 0x8000
	s_nop 0
	global_load_lds_dwordx4 v140, s[34:35]
	s_add_i32 m0, s42, 0xa000
	s_nop 0
	global_load_lds_dwordx4 v144, s[34:35]
	s_add_i32 m0, s42, 0x1c000
	s_nop 0
	global_load_lds_dwordx4 v142, s[38:39]
	s_add_i32 m0, s42, 0x1e000
	s_nop 0
	global_load_lds_dwordx4 v146, s[38:39]
	s_waitcnt lgkmcnt(0)
	v_mfma_f32_16x16x32_bf16 v[62:65], v[130:133], v[206:209], v[62:65]
	v_mfma_f32_16x16x32_bf16 v[58:61], v[158:161], v[206:209], v[58:61]
	v_mfma_f32_16x16x32_bf16 v[46:49], v[130:133], v[214:217], v[46:49]
	v_mfma_f32_16x16x32_bf16 v[42:45], v[158:161], v[214:217], v[42:45]
	v_mfma_f32_16x16x32_bf16 v[30:33], v[130:133], v[222:225], v[30:33]
	v_mfma_f32_16x16x32_bf16 v[26:29], v[158:161], v[222:225], v[26:29]
	v_mfma_f32_16x16x32_bf16 v[14:17], v[130:133], v[230:233], v[14:17]
	v_mfma_f32_16x16x32_bf16 v[10:13], v[158:161], v[230:233], v[10:13]
	v_mfma_f32_16x16x32_bf16 v[62:65], v[134:137], v[210:213], v[62:65]
	v_mfma_f32_16x16x32_bf16 v[58:61], v[186:189], v[210:213], v[58:61]
	v_mfma_f32_16x16x32_bf16 v[46:49], v[134:137], v[218:221], v[46:49]
	v_mfma_f32_16x16x32_bf16 v[42:45], v[186:189], v[218:221], v[42:45]
	v_mfma_f32_16x16x32_bf16 v[30:33], v[134:137], v[226:229], v[30:33]
	v_mfma_f32_16x16x32_bf16 v[26:29], v[186:189], v[226:229], v[26:29]
	v_mfma_f32_16x16x32_bf16 v[14:17], v[134:137], v[234:237], v[14:17]
	v_mfma_f32_16x16x32_bf16 v[10:13], v[186:189], v[234:237], v[10:13]
	s_waitcnt vmcnt(8)
	s_barrier
	ds_read_b128 v[130:133], v183
	ds_read_b128 v[134:137], v183 offset:1024
	ds_read_b128 v[158:161], v183 offset:2048
	ds_read_b128 v[186:189], v183 offset:3072
	ds_read_b128 v[206:209], v182 offset:49152
	ds_read_b128 v[210:213], v182 offset:50176
	ds_read_b128 v[214:217], v182 offset:51200
	ds_read_b128 v[218:221], v182 offset:52224
	ds_read_b128 v[222:225], v182 offset:53248
	ds_read_b128 v[226:229], v182 offset:54272
	ds_read_b128 v[230:233], v182 offset:55296
	ds_read_b128 v[234:237], v182 offset:56320
	s_waitcnt lgkmcnt(0)
	v_mfma_f32_16x16x32_bf16 v[62:65], v[130:133], v[206:209], v[62:65]
	v_mfma_f32_16x16x32_bf16 v[58:61], v[158:161], v[206:209], v[58:61]
	v_mfma_f32_16x16x32_bf16 v[46:49], v[130:133], v[214:217], v[46:49]
	v_mfma_f32_16x16x32_bf16 v[42:45], v[158:161], v[214:217], v[42:45]
	v_mfma_f32_16x16x32_bf16 v[30:33], v[130:133], v[222:225], v[30:33]
	v_mfma_f32_16x16x32_bf16 v[26:29], v[158:161], v[222:225], v[26:29]
	v_mfma_f32_16x16x32_bf16 v[14:17], v[130:133], v[230:233], v[14:17]
	v_mfma_f32_16x16x32_bf16 v[10:13], v[158:161], v[230:233], v[10:13]
	v_mfma_f32_16x16x32_bf16 v[62:65], v[134:137], v[210:213], v[62:65]
	v_mfma_f32_16x16x32_bf16 v[58:61], v[186:189], v[210:213], v[58:61]
	v_mfma_f32_16x16x32_bf16 v[46:49], v[134:137], v[218:221], v[46:49]
	v_mfma_f32_16x16x32_bf16 v[42:45], v[186:189], v[218:221], v[42:45]
	v_mfma_f32_16x16x32_bf16 v[30:33], v[134:137], v[226:229], v[30:33]
	v_mfma_f32_16x16x32_bf16 v[26:29], v[186:189], v[226:229], v[26:29]
	v_mfma_f32_16x16x32_bf16 v[14:17], v[134:137], v[234:237], v[14:17]
	v_mfma_f32_16x16x32_bf16 v[10:13], v[186:189], v[234:237], v[10:13]
	s_waitcnt vmcnt(4)
	s_barrier
; #define PG8_WAIT_V(n) asm volatile("s_waitcnt vmcnt(" #n ")" ::: "memory")
; template <class Epi, class Sched, bool ALIGN_EPI = false, bool SP2 = false>
; __device__ __forceinline__ void gemm_phase(PG8_LAS unsigned char* lds, const Gemm g, const Sched& S, const Epi& E) {
;     ...
;     const char* cA = (const char*)g.A + (size_t)cur.pm * tstep; const char* cB = (const char*)g.Bt + (size_t)cur.pn * tstep;
;     S.a_ready(cur);
;     if constexpr (SP2) {
;         PG8_STAGE(PG8_SB(0, 0), cB, voffB); PG8_STAGE(PG8_SB(0, 1), cB + hstep, voffB); PG8_STAGE(PG8_SA(0, 0), cA, voffA); PG8_STAGE(PG8_SA(0, 1), cA + hstep, voffA);
;         if (wr == 1) PG8_BAR;
;         PG8_WAIT_V(2); PG8_BAR;
;         PG8_STAGE(PG8_SB(1, 0), cB + kstep, voffB); PG8_STAGE(PG8_SA(1, 0), cA + kstep, voffA); PG8_STAGE(PG8_SB(1, 1), cB + hstep + kstep, voffB);
;         PG8_WAIT_V(6); PG8_BAR;
;     } else {
;     ...
;         for (int t = 0; t < nt; t += 2) {
;             const bool last = (t == nt - 2);
;             const char* a1 = cA + (size_t)(t + 1) * kstep;
;             const char* a2 = last ? nA : cA + (size_t)(t + 2) * kstep; const char* b2 = last ? nB : cB + (size_t)(t + 2) * kstep;
;             const char* a3 = a2 + kstep; const char* b3 = b2 + kstep;
;             if (last && has_next) S.a_ready(nxt);
;             if constexpr (SP2) {
;             PG8_LDB(B0, 0, 0); PG8_LDB(B1, 0, 1); PG8_SCHED; PG8_LDA(At, 0, 0); PG8_STAGE(PG8_SA(1, 1), a1 + hstep, voffA);
;             PG8_WAIT_V(8); PG8_WAIT_L(0); PG8_BAR; PG8_MMA(0, 0, At, B0); PG8_MMA(0, 1, At, B1); PG8_BAR; PG8_SCHED;
;             PG8_LDA(At, 0, 1); PG8_STAGE(PG8_SB(0, 0), b2, voffB); PG8_STAGE(PG8_SB(0, 1), b2 + hstep, voffB); PG8_STAGE(PG8_SA(0, 0), a2, voffA);
;             PG8_WAIT_V(8); PG8_WAIT_L(0); PG8_BAR; PG8_MMA(1, 0, At, B0); PG8_MMA(1, 1, At, B1); PG8_BAR; PG8_SCHED;
;             PG8_LDB(B0, 1, 0); PG8_LDB(B1, 1, 1); PG8_SCHED; PG8_LDA(At, 1, 0); PG8_STAGE(PG8_SA(0, 1), a2 + hstep, voffA);
;             PG8_WAIT_V(8); PG8_WAIT_L(0); PG8_BAR; PG8_MMA(0, 0, At, B0); PG8_MMA(0, 1, At, B1); PG8_BAR; PG8_SCHED;
;             PG8_LDA(At, 1, 1); PG8_STAGE(PG8_SB(1, 0), b3, voffB); PG8_STAGE(PG8_SB(1, 1), b3 + hstep, voffB); PG8_STAGE(PG8_SA(1, 0), a3, voffA);
;             PG8_WAIT_V(8); PG8_WAIT_L(0); PG8_BAR; PG8_MMA(1, 0, At, B0); PG8_MMA(1, 1, At, B1); PG8_BAR; PG8_SCHED;
	ds_read_b128 v[130:133], v181
	ds_read_b128 v[134:137], v181 offset:1024
	ds_read_b128 v[158:161], v181 offset:2048
	ds_read_b128 v[186:189], v181 offset:3072
	ds_read_b128 v[206:209], v182
	ds_read_b128 v[210:213], v182 offset:1024
	ds_read_b128 v[214:217], v182 offset:2048
	ds_read_b128 v[218:221], v182 offset:3072
	ds_read_b128 v[222:225], v182 offset:4096
	ds_read_b128 v[226:229], v182 offset:5120
	ds_read_b128 v[230:233], v182 offset:6144
	ds_read_b128 v[234:237], v182 offset:7168
	s_waitcnt lgkmcnt(0)
	v_mfma_f32_16x16x32_bf16 v[62:65], v[130:133], v[206:209], v[62:65]
	v_mfma_f32_16x16x32_bf16 v[58:61], v[158:161], v[206:209], v[58:61]
	v_mfma_f32_16x16x32_bf16 v[46:49], v[130:133], v[214:217], v[46:49]
	v_mfma_f32_16x16x32_bf16 v[42:45], v[158:161], v[214:217], v[42:45]
	v_mfma_f32_16x16x32_bf16 v[30:33], v[130:133], v[222:225], v[30:33]
	v_mfma_f32_16x16x32_bf16 v[26:29], v[158:161], v[222:225], v[26:29]
	v_mfma_f32_16x16x32_bf16 v[14:17], v[130:133], v[230:233], v[14:17]
	v_mfma_f32_16x16x32_bf16 v[10:13], v[158:161], v[230:233], v[10:13]
	v_mfma_f32_16x16x32_bf16 v[62:65], v[134:137], v[210:213], v[62:65]
	v_mfma_f32_16x16x32_bf16 v[58:61], v[186:189], v[210:213], v[58:61]
	v_mfma_f32_16x16x32_bf16 v[46:49], v[134:137], v[218:221], v[46:49]
	v_mfma_f32_16x16x32_bf16 v[42:45], v[186:189], v[218:221], v[42:45]
	v_mfma_f32_16x16x32_bf16 v[30:33], v[134:137], v[226:229], v[30:33]
	v_mfma_f32_16x16x32_bf16 v[26:29], v[186:189], v[226:229], v[26:29]
	v_mfma_f32_16x16x32_bf16 v[14:17], v[134:137], v[234:237], v[14:17]
	v_mfma_f32_16x16x32_bf16 v[10:13], v[186:189], v[234:237], v[10:13]
	s_waitcnt vmcnt(0)
	s_barrier
	ds_read_b128 v[130:133], v184
	ds_read_b128 v[134:137], v184 offset:1024
	ds_read_b128 v[158:161], v184 offset:2048
	ds_read_b128 v[186:189], v184 offset:3072
	ds_read_b128 v[206:209], v182 offset:32768
	ds_read_b128 v[210:213], v182 offset:33792
	ds_read_b128 v[214:217], v182 offset:34816
	ds_read_b128 v[218:221], v182 offset:35840
	ds_read_b128 v[222:225], v182 offset:36864
	ds_read_b128 v[226:229], v182 offset:37888
	ds_read_b128 v[230:233], v182 offset:38912
	ds_read_b128 v[234:237], v182 offset:39936
	s_waitcnt lgkmcnt(0)
	v_mfma_f32_16x16x32_bf16 v[62:65], v[130:133], v[206:209], v[62:65]
	v_mfma_f32_16x16x32_bf16 v[58:61], v[158:161], v[206:209], v[58:61]
	v_mfma_f32_16x16x32_bf16 v[46:49], v[130:133], v[214:217], v[46:49]
	v_mfma_f32_16x16x32_bf16 v[42:45], v[158:161], v[214:217], v[42:45]
	v_mfma_f32_16x16x32_bf16 v[30:33], v[130:133], v[222:225], v[30:33]
	v_mfma_f32_16x16x32_bf16 v[26:29], v[158:161], v[222:225], v[26:29]
	v_mfma_f32_16x16x32_bf16 v[14:17], v[130:133], v[230:233], v[14:17]
	v_mfma_f32_16x16x32_bf16 v[10:13], v[158:161], v[230:233], v[10:13]
	v_mfma_f32_16x16x32_bf16 v[62:65], v[134:137], v[210:213], v[62:65]
	v_mfma_f32_16x16x32_bf16 v[58:61], v[186:189], v[210:213], v[58:61]
	v_mfma_f32_16x16x32_bf16 v[46:49], v[134:137], v[218:221], v[46:49]
	v_mfma_f32_16x16x32_bf16 v[42:45], v[186:189], v[218:221], v[42:45]
	v_mfma_f32_16x16x32_bf16 v[30:33], v[134:137], v[226:229], v[30:33]
	v_mfma_f32_16x16x32_bf16 v[26:29], v[186:189], v[226:229], v[26:29]
	v_mfma_f32_16x16x32_bf16 v[14:17], v[134:137], v[234:237], v[14:17]
	v_mfma_f32_16x16x32_bf16 v[10:13], v[186:189], v[234:237], v[10:13]
	s_branch .LBB0_141
.Lp1q_lean_q3:
	s_mov_b32 s34, s6
	s_mov_b32 s35, 0
	s_lshl_b64 s[34:35], s[34:35], 19
	s_add_u32 s34, s34, s66
	s_addc_u32 s35, s35, s67
	s_add_u32 s34, s34, 0x80
	s_addc_u32 s35, s35, 0
	s_add_u32 s34, s34, 0x40000
	s_addc_u32 s35, s35, 0
	s_mov_b32 s38, s0
	s_mov_b32 s39, 0
	s_lshl_b64 s[38:39], s[38:39], 19
	s_add_u32 s38, s38, s62
	s_addc_u32 s39, s39, s63
	s_add_u32 s38, s38, 0x80
	s_addc_u32 s39, s39, 0
	s_add_u32 s38, s38, 0x40000
	s_addc_u32 s39, s39, 0
	s_waitcnt vmcnt(0) lgkmcnt(0)
	s_barrier
	s_add_i32 m0, s42, 0xc000
	s_nop 0
	global_load_lds_dwordx4 v140, s[34:35]
	s_add_i32 m0, s42, 0xe000
	s_nop 0
	global_load_lds_dwordx4 v144, s[34:35]
	s_add_u32 s34, s34, 0x80
	s_addc_u32 s35, s35, 0
	s_add_u32 s38, s38, 0x80
	s_addc_u32 s39, s39, 0
	s_mov_b32 m0, s42
	s_nop 0
	global_load_lds_dwordx4 v140, s[34:35]
	s_add_i32 m0, s42, 0x2000
	s_nop 0
	global_load_lds_dwordx4 v144, s[34:35]
	s_add_i32 m0, s42, 0x10000
	s_nop 0
	global_load_lds_dwordx4 v142, s[38:39]
	s_add_i32 m0, s42, 0x12000
	s_nop 0
	global_load_lds_dwordx4 v146, s[38:39]
	s_add_u32 s34, s34, 0x80
	s_addc_u32 s35, s35, 0
	s_add_u32 s38, s38, 0x80
	s_addc_u32 s39, s39, 0
	s_add_i32 m0, s42, 0x8000
	s_nop 0
	global_load_lds_dwordx4 v140, s[34:35]
	s_add_i32 m0, s42, 0xa000
	s_nop 0
	global_load_lds_dwordx4 v144, s[34:35]
	s_add_i32 m0, s42, 0x18000
	s_nop 0
	global_load_lds_dwordx4 v142, s[38:39]
	s_add_i32 m0, s42, 0x1a000
	s_nop 0
	global_load_lds_dwordx4 v146, s[38:39]
	ds_read_b128 v[190:193], v181
	ds_read_b128 v[194:197], v181 offset:1024
	ds_read_b128 v[198:201], v181 offset:2048
	ds_read_b128 v[202:205], v181 offset:3072
	ds_read_b128 v[206:209], v182 offset:16384
	ds_read_b128 v[210:213], v182 offset:17408
	ds_read_b128 v[214:217], v182 offset:18432
	ds_read_b128 v[218:221], v182 offset:19456
	ds_read_b128 v[222:225], v182 offset:20480
	ds_read_b128 v[226:229], v182 offset:21504
	ds_read_b128 v[230:233], v182 offset:22528
	ds_read_b128 v[234:237], v182 offset:23552
	s_waitcnt lgkmcnt(0)
	v_mfma_f32_16x16x32_bf16 v[54:57], v[190:193], v[206:209], v[54:57]
	v_mfma_f32_16x16x32_bf16 v[50:53], v[198:201], v[206:209], v[50:53]
	v_mfma_f32_16x16x32_bf16 v[38:41], v[190:193], v[214:217], v[38:41]
	v_mfma_f32_16x16x32_bf16 v[34:37], v[198:201], v[214:217], v[34:37]
	v_mfma_f32_16x16x32_bf16 v[22:25], v[190:193], v[222:225], v[22:25]
	v_mfma_f32_16x16x32_bf16 v[18:21], v[198:201], v[222:225], v[18:21]
	v_mfma_f32_16x16x32_bf16 v[6:9], v[190:193], v[230:233], v[6:9]
	v_mfma_f32_16x16x32_bf16 v[2:5], v[198:201], v[230:233], v[2:5]
	v_mfma_f32_16x16x32_bf16 v[54:57], v[194:197], v[210:213], v[54:57]
	v_mfma_f32_16x16x32_bf16 v[50:53], v[202:205], v[210:213], v[50:53]
	v_mfma_f32_16x16x32_bf16 v[38:41], v[194:197], v[218:221], v[38:41]
	v_mfma_f32_16x16x32_bf16 v[34:37], v[202:205], v[218:221], v[34:37]
	v_mfma_f32_16x16x32_bf16 v[22:25], v[194:197], v[226:229], v[22:25]
	v_mfma_f32_16x16x32_bf16 v[18:21], v[202:205], v[226:229], v[18:21]
	v_mfma_f32_16x16x32_bf16 v[6:9], v[194:197], v[234:237], v[6:9]
	v_mfma_f32_16x16x32_bf16 v[2:5], v[202:205], v[234:237], v[2:5]
	s_waitcnt vmcnt(8)
	s_barrier
; #define PG8_STAGE(bufoff, gbase, voff) do { _Pragma("unroll") for (int _i = 0; _i < 2; ++_i) \
;         __builtin_amdgcn_global_load_lds((const unsigned*)((const char*)(gbase) + (voff)[_i]), (PG8_LAS unsigned*)(lds + (bufoff) + ldsw + _i * 8192), 16, 0, 0); } while (0)
; #define PG8_LDA(dst, b, h) do { _Pragma("unroll") for (int m = 0; m < 4; ++m) _Pragma("unroll") for (int k = 0; k < 2; ++k) dst[m][k] = *(const PG8_LAS bf16x8*)(lds + PG8_SA(b, h) + aoff + m * 2048 + k * 1024); } while (0)
; #define PG8_LDB(dst, b, h) do { _Pragma("unroll") for (int n = 0; n < 2; ++n) _Pragma("unroll") for (int k = 0; k < 2; ++k) dst[n][k] = *(const PG8_LAS bf16x8*)(lds + PG8_SB(b, h) + boff + n * 2048 + k * 1024); } while (0)
; template <class Epi, class Sched, bool ALIGN_EPI = false, bool SP2 = false>
; __device__ __forceinline__ void gemm_phase(PG8_LAS unsigned char* lds, const Gemm g, const Sched& S, const Epi& E) {
;     ...
;         for (int t = 0; t < nt; t += 2) {
;             const bool last = (t == nt - 2);
;             const char* a1 = cA + (size_t)(t + 1) * kstep;
;             const char* a2 = last ? nA : cA + (size_t)(t + 2) * kstep; const char* b2 = last ? nB : cB + (size_t)(t + 2) * kstep;
;             const char* a3 = a2 + kstep; const char* b3 = b2 + kstep;
;             if (last && has_next) S.a_ready(nxt);
;             if constexpr (SP2) {
;             PG8_LDB(B0, 0, 0); PG8_LDB(B1, 0, 1); PG8_SCHED; PG8_LDA(At, 0, 0); PG8_STAGE(PG8_SA(1, 1), a1 + hstep, voffA);
;             PG8_WAIT_V(8); PG8_WAIT_L(0); PG8_BAR; PG8_MMA(0, 0, At, B0); PG8_MMA(0, 1, At, B1); PG8_BAR; PG8_SCHED;
;             PG8_LDA(At, 0, 1); PG8_STAGE(PG8_SB(0, 0), b2, voffB); PG8_STAGE(PG8_SB(0, 1), b2 + hstep, voffB); PG8_STAGE(PG8_SA(0, 0), a2, voffA);
;             PG8_WAIT_V(8); PG8_WAIT_L(0); PG8_BAR; PG8_MMA(1, 0, At, B0); PG8_MMA(1, 1, At, B1); PG8_BAR; PG8_SCHED;
;             PG8_LDB(B0, 1, 0); PG8_LDB(B1, 1, 1); PG8_SCHED; PG8_LDA(At, 1, 0); PG8_STAGE(PG8_SA(0, 1), a2 + hstep, voffA);
;             PG8_WAIT_V(8); PG8_WAIT_L(0); PG8_BAR; PG8_MMA(0, 0, At, B0); PG8_MMA(0, 1, At, B1); PG8_BAR; PG8_SCHED;
;             PG8_LDA(At, 1, 1); PG8_STAGE(PG8_SB(1, 0), b3, voffB); PG8_STAGE(PG8_SB(1, 1), b3 + hstep, voffB); PG8_STAGE(PG8_SA(1, 0), a3, voffA);
;             PG8_WAIT_V(8); PG8_WAIT_L(0); PG8_BAR; PG8_MMA(1, 0, At, B0); PG8_MMA(1, 1, At, B1); PG8_BAR; PG8_SCHED;
	ds_read_b128 v[190:193], v184
	ds_read_b128 v[194:197], v184 offset:1024
	ds_read_b128 v[198:201], v184 offset:2048
	ds_read_b128 v[202:205], v184 offset:3072
	ds_read_b128 v[206:209], v182 offset:49152
	ds_read_b128 v[210:213], v182 offset:50176
	ds_read_b128 v[214:217], v182 offset:51200
	ds_read_b128 v[218:221], v182 offset:52224
	ds_read_b128 v[222:225], v182 offset:53248
	ds_read_b128 v[226:229], v182 offset:54272
	ds_read_b128 v[230:233], v182 offset:55296
	ds_read_b128 v[234:237], v182 offset:56320
	s_add_u32 s34, s34, 0x80
	s_addc_u32 s35, s35, 0
	s_add_u32 s38, s38, 0x80
	s_addc_u32 s39, s39, 0
	s_add_i32 m0, s42, 0x4000
	s_nop 0
	global_load_lds_dwordx4 v140, s[34:35]
	s_add_i32 m0, s42, 0x6000
	s_nop 0
	global_load_lds_dwordx4 v144, s[34:35]
	s_add_i32 m0, s42, 0x14000
	s_nop 0
	global_load_lds_dwordx4 v142, s[38:39]
	s_add_i32 m0, s42, 0x16000
	s_nop 0
	global_load_lds_dwordx4 v146, s[38:39]
	s_waitcnt lgkmcnt(0)
	v_mfma_f32_16x16x32_bf16 v[54:57], v[190:193], v[206:209], v[54:57]
	v_mfma_f32_16x16x32_bf16 v[50:53], v[198:201], v[206:209], v[50:53]
	v_mfma_f32_16x16x32_bf16 v[38:41], v[190:193], v[214:217], v[38:41]
	v_mfma_f32_16x16x32_bf16 v[34:37], v[198:201], v[214:217], v[34:37]
	v_mfma_f32_16x16x32_bf16 v[22:25], v[190:193], v[222:225], v[22:25]
	v_mfma_f32_16x16x32_bf16 v[18:21], v[198:201], v[222:225], v[18:21]
	v_mfma_f32_16x16x32_bf16 v[6:9], v[190:193], v[230:233], v[6:9]
	v_mfma_f32_16x16x32_bf16 v[2:5], v[198:201], v[230:233], v[2:5]
	v_mfma_f32_16x16x32_bf16 v[54:57], v[194:197], v[210:213], v[54:57]
	v_mfma_f32_16x16x32_bf16 v[50:53], v[202:205], v[210:213], v[50:53]
	v_mfma_f32_16x16x32_bf16 v[38:41], v[194:197], v[218:221], v[38:41]
	v_mfma_f32_16x16x32_bf16 v[34:37], v[202:205], v[218:221], v[34:37]
	v_mfma_f32_16x16x32_bf16 v[22:25], v[194:197], v[226:229], v[22:25]
	v_mfma_f32_16x16x32_bf16 v[18:21], v[202:205], v[226:229], v[18:21]
	v_mfma_f32_16x16x32_bf16 v[6:9], v[194:197], v[234:237], v[6:9]
	v_mfma_f32_16x16x32_bf16 v[2:5], v[202:205], v[234:237], v[2:5]
	s_waitcnt vmcnt(8)
	s_barrier
	ds_read_b128 v[190:193], v180
	ds_read_b128 v[194:197], v180 offset:1024
	ds_read_b128 v[198:201], v180 offset:2048
	ds_read_b128 v[202:205], v180 offset:3072
	ds_read_b128 v[206:209], v182
	ds_read_b128 v[210:213], v182 offset:1024
	ds_read_b128 v[214:217], v182 offset:2048
	ds_read_b128 v[218:221], v182 offset:3072
	ds_read_b128 v[222:225], v182 offset:4096
	ds_read_b128 v[226:229], v182 offset:5120
	ds_read_b128 v[230:233], v182 offset:6144
	ds_read_b128 v[234:237], v182 offset:7168
	s_add_u32 s34, s34, 0x80
	s_addc_u32 s35, s35, 0
	s_add_u32 s38, s38, 0x80
	s_addc_u32 s39, s39, 0
	s_add_i32 m0, s42, 0xc000
	s_nop 0
	global_load_lds_dwordx4 v140, s[34:35]
	s_add_i32 m0, s42, 0xe000
	s_nop 0
	global_load_lds_dwordx4 v144, s[34:35]
	s_add_i32 m0, s42, 0x1c000
	s_nop 0
	global_load_lds_dwordx4 v142, s[38:39]
	s_add_i32 m0, s42, 0x1e000
	s_nop 0
	global_load_lds_dwordx4 v146, s[38:39]
	s_waitcnt lgkmcnt(0)
	v_mfma_f32_16x16x32_bf16 v[54:57], v[190:193], v[206:209], v[54:57]
	v_mfma_f32_16x16x32_bf16 v[50:53], v[198:201], v[206:209], v[50:53]
	v_mfma_f32_16x16x32_bf16 v[38:41], v[190:193], v[214:217], v[38:41]
	v_mfma_f32_16x16x32_bf16 v[34:37], v[198:201], v[214:217], v[34:37]
	v_mfma_f32_16x16x32_bf16 v[22:25], v[190:193], v[222:225], v[22:25]
	v_mfma_f32_16x16x32_bf16 v[18:21], v[198:201], v[222:225], v[18:21]
	v_mfma_f32_16x16x32_bf16 v[6:9], v[190:193], v[230:233], v[6:9]
	v_mfma_f32_16x16x32_bf16 v[2:5], v[198:201], v[230:233], v[2:5]
	v_mfma_f32_16x16x32_bf16 v[54:57], v[194:197], v[210:213], v[54:57]
	v_mfma_f32_16x16x32_bf16 v[50:53], v[202:205], v[210:213], v[50:53]
	v_mfma_f32_16x16x32_bf16 v[38:41], v[194:197], v[218:221], v[38:41]
	v_mfma_f32_16x16x32_bf16 v[34:37], v[202:205], v[218:221], v[34:37]
	v_mfma_f32_16x16x32_bf16 v[22:25], v[194:197], v[226:229], v[22:25]
	v_mfma_f32_16x16x32_bf16 v[18:21], v[202:205], v[226:229], v[18:21]
	v_mfma_f32_16x16x32_bf16 v[6:9], v[194:197], v[234:237], v[6:9]
	v_mfma_f32_16x16x32_bf16 v[2:5], v[202:205], v[234:237], v[2:5]
	s_waitcnt vmcnt(8)
	s_barrier
	ds_read_b128 v[190:193], v183
	ds_read_b128 v[194:197], v183 offset:1024
	ds_read_b128 v[198:201], v183 offset:2048
	ds_read_b128 v[202:205], v183 offset:3072
	ds_read_b128 v[206:209], v182 offset:32768
	ds_read_b128 v[210:213], v182 offset:33792
	ds_read_b128 v[214:217], v182 offset:34816
	ds_read_b128 v[218:221], v182 offset:35840
	ds_read_b128 v[222:225], v182 offset:36864
	ds_read_b128 v[226:229], v182 offset:37888
	ds_read_b128 v[230:233], v182 offset:38912
	ds_read_b128 v[234:237], v182 offset:39936
	s_add_u32 s34, s34, 0x80
	s_addc_u32 s35, s35, 0
	s_add_u32 s38, s38, 0x80
	s_addc_u32 s39, s39, 0
	s_mov_b32 m0, s42
	s_nop 0
	global_load_lds_dwordx4 v140, s[34:35]
	s_add_i32 m0, s42, 0x2000
	s_nop 0
	global_load_lds_dwordx4 v144, s[34:35]
	s_add_i32 m0, s42, 0x10000
	s_nop 0
	global_load_lds_dwordx4 v142, s[38:39]
	s_add_i32 m0, s42, 0x12000
	s_nop 0
	global_load_lds_dwordx4 v146, s[38:39]
	s_waitcnt lgkmcnt(0)
	v_mfma_f32_16x16x32_bf16 v[54:57], v[190:193], v[206:209], v[54:57]
	v_mfma_f32_16x16x32_bf16 v[50:53], v[198:201], v[206:209], v[50:53]
	v_mfma_f32_16x16x32_bf16 v[38:41], v[190:193], v[214:217], v[38:41]
	v_mfma_f32_16x16x32_bf16 v[34:37], v[198:201], v[214:217], v[34:37]
	v_mfma_f32_16x16x32_bf16 v[22:25], v[190:193], v[222:225], v[22:25]
	v_mfma_f32_16x16x32_bf16 v[18:21], v[198:201], v[222:225], v[18:21]
	v_mfma_f32_16x16x32_bf16 v[6:9], v[190:193], v[230:233], v[6:9]
	v_mfma_f32_16x16x32_bf16 v[2:5], v[198:201], v[230:233], v[2:5]
	v_mfma_f32_16x16x32_bf16 v[54:57], v[194:197], v[210:213], v[54:57]
	v_mfma_f32_16x16x32_bf16 v[50:53], v[202:205], v[210:213], v[50:53]
	v_mfma_f32_16x16x32_bf16 v[38:41], v[194:197], v[218:221], v[38:41]
	v_mfma_f32_16x16x32_bf16 v[34:37], v[202:205], v[218:221], v[34:37]
	v_mfma_f32_16x16x32_bf16 v[22:25], v[194:197], v[226:229], v[22:25]
	v_mfma_f32_16x16x32_bf16 v[18:21], v[202:205], v[226:229], v[18:21]
	v_mfma_f32_16x16x32_bf16 v[6:9], v[194:197], v[234:237], v[6:9]
	v_mfma_f32_16x16x32_bf16 v[2:5], v[202:205], v[234:237], v[2:5]
	s_waitcnt vmcnt(8)
	s_barrier
; #define PG8_STAGE(bufoff, gbase, voff) do { _Pragma("unroll") for (int _i = 0; _i < 2; ++_i) \
;         __builtin_amdgcn_global_load_lds((const unsigned*)((const char*)(gbase) + (voff)[_i]), (PG8_LAS unsigned*)(lds + (bufoff) + ldsw + _i * 8192), 16, 0, 0); } while (0)
; #define PG8_LDA(dst, b, h) do { _Pragma("unroll") for (int m = 0; m < 4; ++m) _Pragma("unroll") for (int k = 0; k < 2; ++k) dst[m][k] = *(const PG8_LAS bf16x8*)(lds + PG8_SA(b, h) + aoff + m * 2048 + k * 1024); } while (0)
; #define PG8_LDB(dst, b, h) do { _Pragma("unroll") for (int n = 0; n < 2; ++n) _Pragma("unroll") for (int k = 0; k < 2; ++k) dst[n][k] = *(const PG8_LAS bf16x8*)(lds + PG8_SB(b, h) + boff + n * 2048 + k * 1024); } while (0)
; template <class Epi, class Sched, bool ALIGN_EPI = false, bool SP2 = false>
; __device__ __forceinline__ void gemm_phase(PG8_LAS unsigned char* lds, const Gemm g, const Sched& S, const Epi& E) {
;     ...
;         for (int t = 0; t < nt; t += 2) {
;             const bool last = (t == nt - 2);
;             const char* a1 = cA + (size_t)(t + 1) * kstep;
;             const char* a2 = last ? nA : cA + (size_t)(t + 2) * kstep; const char* b2 = last ? nB : cB + (size_t)(t + 2) * kstep;
;             const char* a3 = a2 + kstep; const char* b3 = b2 + kstep;
;             if (last && has_next) S.a_ready(nxt);
;             if constexpr (SP2) {
;             PG8_LDB(B0, 0, 0); PG8_LDB(B1, 0, 1); PG8_SCHED; PG8_LDA(At, 0, 0); PG8_STAGE(PG8_SA(1, 1), a1 + hstep, voffA);
;             PG8_WAIT_V(8); PG8_WAIT_L(0); PG8_BAR; PG8_MMA(0, 0, At, B0); PG8_MMA(0, 1, At, B1); PG8_BAR; PG8_SCHED;
;             PG8_LDA(At, 0, 1); PG8_STAGE(PG8_SB(0, 0), b2, voffB); PG8_STAGE(PG8_SB(0, 1), b2 + hstep, voffB); PG8_STAGE(PG8_SA(0, 0), a2, voffA);
;             PG8_WAIT_V(8); PG8_WAIT_L(0); PG8_BAR; PG8_MMA(1, 0, At, B0); PG8_MMA(1, 1, At, B1); PG8_BAR; PG8_SCHED;
;             PG8_LDB(B0, 1, 0); PG8_LDB(B1, 1, 1); PG8_SCHED; PG8_LDA(At, 1, 0); PG8_STAGE(PG8_SA(0, 1), a2 + hstep, voffA);
;             PG8_WAIT_V(8); PG8_WAIT_L(0); PG8_BAR; PG8_MMA(0, 0, At, B0); PG8_MMA(0, 1, At, B1); PG8_BAR; PG8_SCHED;
;             PG8_LDA(At, 1, 1); PG8_STAGE(PG8_SB(1, 0), b3, voffB); PG8_STAGE(PG8_SB(1, 1), b3 + hstep, voffB); PG8_STAGE(PG8_SA(1, 0), a3, voffA);
;             PG8_WAIT_V(8); PG8_WAIT_L(0); PG8_BAR; PG8_MMA(1, 0, At, B0); PG8_MMA(1, 1, At, B1); PG8_BAR; PG8_SCHED;
	ds_read_b128 v[190:193], v181
	ds_read_b128 v[194:197], v181 offset:1024
	ds_read_b128 v[198:201], v181 offset:2048
	ds_read_b128 v[202:205], v181 offset:3072
	ds_read_b128 v[206:209], v182 offset:16384
	ds_read_b128 v[210:213], v182 offset:17408
	ds_read_b128 v[214:217], v182 offset:18432
	ds_read_b128 v[218:221], v182 offset:19456
	ds_read_b128 v[222:225], v182 offset:20480
	ds_read_b128 v[226:229], v182 offset:21504
	ds_read_b128 v[230:233], v182 offset:22528
	ds_read_b128 v[234:237], v182 offset:23552
	s_add_u32 s34, s34, 0x80
	s_addc_u32 s35, s35, 0
	s_add_u32 s38, s38, 0x80
	s_addc_u32 s39, s39, 0
	s_add_i32 m0, s42, 0x8000
	s_nop 0
	global_load_lds_dwordx4 v140, s[34:35]
	s_add_i32 m0, s42, 0xa000
	s_nop 0
	global_load_lds_dwordx4 v144, s[34:35]
	s_add_i32 m0, s42, 0x18000
	s_nop 0
	global_load_lds_dwordx4 v142, s[38:39]
	s_add_i32 m0, s42, 0x1a000
	s_nop 0
	global_load_lds_dwordx4 v146, s[38:39]
	s_waitcnt lgkmcnt(0)
	v_mfma_f32_16x16x32_bf16 v[54:57], v[190:193], v[206:209], v[54:57]
	v_mfma_f32_16x16x32_bf16 v[50:53], v[198:201], v[206:209], v[50:53]
	v_mfma_f32_16x16x32_bf16 v[38:41], v[190:193], v[214:217], v[38:41]
	v_mfma_f32_16x16x32_bf16 v[34:37], v[198:201], v[214:217], v[34:37]
	v_mfma_f32_16x16x32_bf16 v[22:25], v[190:193], v[222:225], v[22:25]
	v_mfma_f32_16x16x32_bf16 v[18:21], v[198:201], v[222:225], v[18:21]
	v_mfma_f32_16x16x32_bf16 v[6:9], v[190:193], v[230:233], v[6:9]
	v_mfma_f32_16x16x32_bf16 v[2:5], v[198:201], v[230:233], v[2:5]
	v_mfma_f32_16x16x32_bf16 v[54:57], v[194:197], v[210:213], v[54:57]
	v_mfma_f32_16x16x32_bf16 v[50:53], v[202:205], v[210:213], v[50:53]
	v_mfma_f32_16x16x32_bf16 v[38:41], v[194:197], v[218:221], v[38:41]
	v_mfma_f32_16x16x32_bf16 v[34:37], v[202:205], v[218:221], v[34:37]
	v_mfma_f32_16x16x32_bf16 v[22:25], v[194:197], v[226:229], v[22:25]
	v_mfma_f32_16x16x32_bf16 v[18:21], v[202:205], v[226:229], v[18:21]
	v_mfma_f32_16x16x32_bf16 v[6:9], v[194:197], v[234:237], v[6:9]
	v_mfma_f32_16x16x32_bf16 v[2:5], v[202:205], v[234:237], v[2:5]
	s_waitcnt vmcnt(8)
	s_barrier
	ds_read_b128 v[190:193], v184
	ds_read_b128 v[194:197], v184 offset:1024
	ds_read_b128 v[198:201], v184 offset:2048
	ds_read_b128 v[202:205], v184 offset:3072
	ds_read_b128 v[206:209], v182 offset:49152
	ds_read_b128 v[210:213], v182 offset:50176
	ds_read_b128 v[214:217], v182 offset:51200
	ds_read_b128 v[218:221], v182 offset:52224
	ds_read_b128 v[222:225], v182 offset:53248
	ds_read_b128 v[226:229], v182 offset:54272
	ds_read_b128 v[230:233], v182 offset:55296
	ds_read_b128 v[234:237], v182 offset:56320
	s_add_u32 s34, s34, 0x80
	s_addc_u32 s35, s35, 0
	s_add_u32 s38, s38, 0x80
	s_addc_u32 s39, s39, 0
	s_add_i32 m0, s42, 0x4000
	s_nop 0
	global_load_lds_dwordx4 v140, s[34:35]
	s_add_i32 m0, s42, 0x6000
	s_nop 0
	global_load_lds_dwordx4 v144, s[34:35]
	s_add_i32 m0, s42, 0x14000
	s_nop 0
	global_load_lds_dwordx4 v142, s[38:39]
	s_add_i32 m0, s42, 0x16000
	s_nop 0
	global_load_lds_dwordx4 v146, s[38:39]
	s_waitcnt lgkmcnt(0)
	v_mfma_f32_16x16x32_bf16 v[54:57], v[190:193], v[206:209], v[54:57]
	v_mfma_f32_16x16x32_bf16 v[50:53], v[198:201], v[206:209], v[50:53]
	v_mfma_f32_16x16x32_bf16 v[38:41], v[190:193], v[214:217], v[38:41]
	v_mfma_f32_16x16x32_bf16 v[34:37], v[198:201], v[214:217], v[34:37]
	v_mfma_f32_16x16x32_bf16 v[22:25], v[190:193], v[222:225], v[22:25]
	v_mfma_f32_16x16x32_bf16 v[18:21], v[198:201], v[222:225], v[18:21]
	v_mfma_f32_16x16x32_bf16 v[6:9], v[190:193], v[230:233], v[6:9]
	v_mfma_f32_16x16x32_bf16 v[2:5], v[198:201], v[230:233], v[2:5]
	v_mfma_f32_16x16x32_bf16 v[54:57], v[194:197], v[210:213], v[54:57]
	v_mfma_f32_16x16x32_bf16 v[50:53], v[202:205], v[210:213], v[50:53]
	v_mfma_f32_16x16x32_bf16 v[38:41], v[194:197], v[218:221], v[38:41]
	v_mfma_f32_16x16x32_bf16 v[34:37], v[202:205], v[218:221], v[34:37]
	v_mfma_f32_16x16x32_bf16 v[22:25], v[194:197], v[226:229], v[22:25]
	v_mfma_f32_16x16x32_bf16 v[18:21], v[202:205], v[226:229], v[18:21]
	v_mfma_f32_16x16x32_bf16 v[6:9], v[194:197], v[234:237], v[6:9]
	v_mfma_f32_16x16x32_bf16 v[2:5], v[202:205], v[234:237], v[2:5]
	s_waitcnt vmcnt(8)
	s_barrier
	ds_read_b128 v[190:193], v180
	ds_read_b128 v[194:197], v180 offset:1024
	ds_read_b128 v[198:201], v180 offset:2048
	ds_read_b128 v[202:205], v180 offset:3072
	ds_read_b128 v[206:209], v182
	ds_read_b128 v[210:213], v182 offset:1024
	ds_read_b128 v[214:217], v182 offset:2048
	ds_read_b128 v[218:221], v182 offset:3072
	ds_read_b128 v[222:225], v182 offset:4096
	ds_read_b128 v[226:229], v182 offset:5120
	ds_read_b128 v[230:233], v182 offset:6144
	ds_read_b128 v[234:237], v182 offset:7168
	s_add_u32 s34, s34, 0x80
	s_addc_u32 s35, s35, 0
	s_add_u32 s38, s38, 0x80
	s_addc_u32 s39, s39, 0
	s_add_i32 m0, s42, 0xc000
	s_nop 0
	global_load_lds_dwordx4 v140, s[34:35]
	s_add_i32 m0, s42, 0xe000
	s_nop 0
	global_load_lds_dwordx4 v144, s[34:35]
	s_add_i32 m0, s42, 0x1c000
	s_nop 0
	global_load_lds_dwordx4 v142, s[38:39]
	s_add_i32 m0, s42, 0x1e000
	s_nop 0
	global_load_lds_dwordx4 v146, s[38:39]
	s_waitcnt lgkmcnt(0)
	v_mfma_f32_16x16x32_bf16 v[54:57], v[190:193], v[206:209], v[54:57]
	v_mfma_f32_16x16x32_bf16 v[50:53], v[198:201], v[206:209], v[50:53]
	v_mfma_f32_16x16x32_bf16 v[38:41], v[190:193], v[214:217], v[38:41]
	v_mfma_f32_16x16x32_bf16 v[34:37], v[198:201], v[214:217], v[34:37]
	v_mfma_f32_16x16x32_bf16 v[22:25], v[190:193], v[222:225], v[22:25]
	v_mfma_f32_16x16x32_bf16 v[18:21], v[198:201], v[222:225], v[18:21]
	v_mfma_f32_16x16x32_bf16 v[6:9], v[190:193], v[230:233], v[6:9]
	v_mfma_f32_16x16x32_bf16 v[2:5], v[198:201], v[230:233], v[2:5]
	v_mfma_f32_16x16x32_bf16 v[54:57], v[194:197], v[210:213], v[54:57]
	v_mfma_f32_16x16x32_bf16 v[50:53], v[202:205], v[210:213], v[50:53]
	v_mfma_f32_16x16x32_bf16 v[38:41], v[194:197], v[218:221], v[38:41]
	v_mfma_f32_16x16x32_bf16 v[34:37], v[202:205], v[218:221], v[34:37]
	v_mfma_f32_16x16x32_bf16 v[22:25], v[194:197], v[226:229], v[22:25]
	v_mfma_f32_16x16x32_bf16 v[18:21], v[202:205], v[226:229], v[18:21]
	v_mfma_f32_16x16x32_bf16 v[6:9], v[194:197], v[234:237], v[6:9]
	v_mfma_f32_16x16x32_bf16 v[2:5], v[202:205], v[234:237], v[2:5]
	s_waitcnt vmcnt(8)
	s_barrier
; #define PG8_STAGE(bufoff, gbase, voff) do { _Pragma("unroll") for (int _i = 0; _i < 2; ++_i) \
;         __builtin_amdgcn_global_load_lds((const unsigned*)((const char*)(gbase) + (voff)[_i]), (PG8_LAS unsigned*)(lds + (bufoff) + ldsw + _i * 8192), 16, 0, 0); } while (0)
; #define PG8_LDA(dst, b, h) do { _Pragma("unroll") for (int m = 0; m < 4; ++m) _Pragma("unroll") for (int k = 0; k < 2; ++k) dst[m][k] = *(const PG8_LAS bf16x8*)(lds + PG8_SA(b, h) + aoff + m * 2048 + k * 1024); } while (0)
; #define PG8_LDB(dst, b, h) do { _Pragma("unroll") for (int n = 0; n < 2; ++n) _Pragma("unroll") for (int k = 0; k < 2; ++k) dst[n][k] = *(const PG8_LAS bf16x8*)(lds + PG8_SB(b, h) + boff + n * 2048 + k * 1024); } while (0)
; template <class Epi, class Sched, bool ALIGN_EPI = false, bool SP2 = false>
; __device__ __forceinline__ void gemm_phase(PG8_LAS unsigned char* lds, const Gemm g, const Sched& S, const Epi& E) {
;     ...
;         for (int t = 0; t < nt; t += 2) {
;             const bool last = (t == nt - 2);
;             const char* a1 = cA + (size_t)(t + 1) * kstep;
;             const char* a2 = last ? nA : cA + (size_t)(t + 2) * kstep; const char* b2 = last ? nB : cB + (size_t)(t + 2) * kstep;
;             const char* a3 = a2 + kstep; const char* b3 = b2 + kstep;
;             if (last && has_next) S.a_ready(nxt);
;             if constexpr (SP2) {
;             PG8_LDB(B0, 0, 0); PG8_LDB(B1, 0, 1); PG8_SCHED; PG8_LDA(At, 0, 0); PG8_STAGE(PG8_SA(1, 1), a1 + hstep, voffA);
;             PG8_WAIT_V(8); PG8_WAIT_L(0); PG8_BAR; PG8_MMA(0, 0, At, B0); PG8_MMA(0, 1, At, B1); PG8_BAR; PG8_SCHED;
;             PG8_LDA(At, 0, 1); PG8_STAGE(PG8_SB(0, 0), b2, voffB); PG8_STAGE(PG8_SB(0, 1), b2 + hstep, voffB); PG8_STAGE(PG8_SA(0, 0), a2, voffA);
;             PG8_WAIT_V(8); PG8_WAIT_L(0); PG8_BAR; PG8_MMA(1, 0, At, B0); PG8_MMA(1, 1, At, B1); PG8_BAR; PG8_SCHED;
;             PG8_LDB(B0, 1, 0); PG8_LDB(B1, 1, 1); PG8_SCHED; PG8_LDA(At, 1, 0); PG8_STAGE(PG8_SA(0, 1), a2 + hstep, voffA);
;             PG8_WAIT_V(8); PG8_WAIT_L(0); PG8_BAR; PG8_MMA(0, 0, At, B0); PG8_MMA(0, 1, At, B1); PG8_BAR; PG8_SCHED;
;             PG8_LDA(At, 1, 1); PG8_STAGE(PG8_SB(1, 0), b3, voffB); PG8_STAGE(PG8_SB(1, 1), b3 + hstep, voffB); PG8_STAGE(PG8_SA(1, 0), a3, voffA);
;             PG8_WAIT_V(8); PG8_WAIT_L(0); PG8_BAR; PG8_MMA(1, 0, At, B0); PG8_MMA(1, 1, At, B1); PG8_BAR; PG8_SCHED;
	ds_read_b128 v[190:193], v183
	ds_read_b128 v[194:197], v183 offset:1024
	ds_read_b128 v[198:201], v183 offset:2048
	ds_read_b128 v[202:205], v183 offset:3072
	ds_read_b128 v[206:209], v182 offset:32768
	ds_read_b128 v[210:213], v182 offset:33792
	ds_read_b128 v[214:217], v182 offset:34816
	ds_read_b128 v[218:221], v182 offset:35840
	ds_read_b128 v[222:225], v182 offset:36864
	ds_read_b128 v[226:229], v182 offset:37888
	ds_read_b128 v[230:233], v182 offset:38912
	ds_read_b128 v[234:237], v182 offset:39936
	s_add_u32 s34, s34, 0x80
	s_addc_u32 s35, s35, 0
	s_add_u32 s38, s38, 0x80
	s_addc_u32 s39, s39, 0
	s_mov_b32 m0, s42
	s_nop 0
	global_load_lds_dwordx4 v140, s[34:35]
	s_add_i32 m0, s42, 0x2000
	s_nop 0
	global_load_lds_dwordx4 v144, s[34:35]
	s_add_i32 m0, s42, 0x10000
	s_nop 0
	global_load_lds_dwordx4 v142, s[38:39]
	s_add_i32 m0, s42, 0x12000
	s_nop 0
	global_load_lds_dwordx4 v146, s[38:39]
	s_waitcnt lgkmcnt(0)
	v_mfma_f32_16x16x32_bf16 v[54:57], v[190:193], v[206:209], v[54:57]
	v_mfma_f32_16x16x32_bf16 v[50:53], v[198:201], v[206:209], v[50:53]
	v_mfma_f32_16x16x32_bf16 v[38:41], v[190:193], v[214:217], v[38:41]
	v_mfma_f32_16x16x32_bf16 v[34:37], v[198:201], v[214:217], v[34:37]
	v_mfma_f32_16x16x32_bf16 v[22:25], v[190:193], v[222:225], v[22:25]
	v_mfma_f32_16x16x32_bf16 v[18:21], v[198:201], v[222:225], v[18:21]
	v_mfma_f32_16x16x32_bf16 v[6:9], v[190:193], v[230:233], v[6:9]
	v_mfma_f32_16x16x32_bf16 v[2:5], v[198:201], v[230:233], v[2:5]
	v_mfma_f32_16x16x32_bf16 v[54:57], v[194:197], v[210:213], v[54:57]
	v_mfma_f32_16x16x32_bf16 v[50:53], v[202:205], v[210:213], v[50:53]
	v_mfma_f32_16x16x32_bf16 v[38:41], v[194:197], v[218:221], v[38:41]
	v_mfma_f32_16x16x32_bf16 v[34:37], v[202:205], v[218:221], v[34:37]
	v_mfma_f32_16x16x32_bf16 v[22:25], v[194:197], v[226:229], v[22:25]
	v_mfma_f32_16x16x32_bf16 v[18:21], v[202:205], v[226:229], v[18:21]
	v_mfma_f32_16x16x32_bf16 v[6:9], v[194:197], v[234:237], v[6:9]
	v_mfma_f32_16x16x32_bf16 v[2:5], v[202:205], v[234:237], v[2:5]
	s_waitcnt vmcnt(8)
	s_barrier
	ds_read_b128 v[190:193], v181
	ds_read_b128 v[194:197], v181 offset:1024
	ds_read_b128 v[198:201], v181 offset:2048
	ds_read_b128 v[202:205], v181 offset:3072
	ds_read_b128 v[206:209], v182 offset:16384
	ds_read_b128 v[210:213], v182 offset:17408
	ds_read_b128 v[214:217], v182 offset:18432
	ds_read_b128 v[218:221], v182 offset:19456
	ds_read_b128 v[222:225], v182 offset:20480
	ds_read_b128 v[226:229], v182 offset:21504
	ds_read_b128 v[230:233], v182 offset:22528
	ds_read_b128 v[234:237], v182 offset:23552
	s_add_u32 s34, s34, 0x80
	s_addc_u32 s35, s35, 0
	s_add_u32 s38, s38, 0x80
	s_addc_u32 s39, s39, 0
	s_add_i32 m0, s42, 0x8000
	s_nop 0
	global_load_lds_dwordx4 v140, s[34:35]
	s_add_i32 m0, s42, 0xa000
	s_nop 0
	global_load_lds_dwordx4 v144, s[34:35]
	s_add_i32 m0, s42, 0x18000
	s_nop 0
	global_load_lds_dwordx4 v142, s[38:39]
	s_add_i32 m0, s42, 0x1a000
	s_nop 0
	global_load_lds_dwordx4 v146, s[38:39]
	s_waitcnt lgkmcnt(0)
	v_mfma_f32_16x16x32_bf16 v[54:57], v[190:193], v[206:209], v[54:57]
	v_mfma_f32_16x16x32_bf16 v[50:53], v[198:201], v[206:209], v[50:53]
	v_mfma_f32_16x16x32_bf16 v[38:41], v[190:193], v[214:217], v[38:41]
	v_mfma_f32_16x16x32_bf16 v[34:37], v[198:201], v[214:217], v[34:37]
	v_mfma_f32_16x16x32_bf16 v[22:25], v[190:193], v[222:225], v[22:25]
	v_mfma_f32_16x16x32_bf16 v[18:21], v[198:201], v[222:225], v[18:21]
	v_mfma_f32_16x16x32_bf16 v[6:9], v[190:193], v[230:233], v[6:9]
	v_mfma_f32_16x16x32_bf16 v[2:5], v[198:201], v[230:233], v[2:5]
	v_mfma_f32_16x16x32_bf16 v[54:57], v[194:197], v[210:213], v[54:57]
	v_mfma_f32_16x16x32_bf16 v[50:53], v[202:205], v[210:213], v[50:53]
	v_mfma_f32_16x16x32_bf16 v[38:41], v[194:197], v[218:221], v[38:41]
	v_mfma_f32_16x16x32_bf16 v[34:37], v[202:205], v[218:221], v[34:37]
	v_mfma_f32_16x16x32_bf16 v[22:25], v[194:197], v[226:229], v[22:25]
	v_mfma_f32_16x16x32_bf16 v[18:21], v[202:205], v[226:229], v[18:21]
	v_mfma_f32_16x16x32_bf16 v[6:9], v[194:197], v[234:237], v[6:9]
	v_mfma_f32_16x16x32_bf16 v[2:5], v[202:205], v[234:237], v[2:5]
	s_waitcnt vmcnt(8)
	s_barrier
	ds_read_b128 v[190:193], v184
	ds_read_b128 v[194:197], v184 offset:1024
	ds_read_b128 v[198:201], v184 offset:2048
	ds_read_b128 v[202:205], v184 offset:3072
	ds_read_b128 v[206:209], v182 offset:49152
	ds_read_b128 v[210:213], v182 offset:50176
	ds_read_b128 v[214:217], v182 offset:51200
	ds_read_b128 v[218:221], v182 offset:52224
	ds_read_b128 v[222:225], v182 offset:53248
	ds_read_b128 v[226:229], v182 offset:54272
	ds_read_b128 v[230:233], v182 offset:55296
	ds_read_b128 v[234:237], v182 offset:56320
	s_add_u32 s34, s34, 0x80
	s_addc_u32 s35, s35, 0
	s_add_u32 s38, s38, 0x80
	s_addc_u32 s39, s39, 0
	s_add_i32 m0, s42, 0x4000
	s_nop 0
	global_load_lds_dwordx4 v140, s[34:35]
	s_add_i32 m0, s42, 0x6000
	s_nop 0
	global_load_lds_dwordx4 v144, s[34:35]
	s_add_i32 m0, s42, 0x14000
	s_nop 0
	global_load_lds_dwordx4 v142, s[38:39]
	s_add_i32 m0, s42, 0x16000
	s_nop 0
	global_load_lds_dwordx4 v146, s[38:39]
	s_waitcnt lgkmcnt(0)
	v_mfma_f32_16x16x32_bf16 v[54:57], v[190:193], v[206:209], v[54:57]
	v_mfma_f32_16x16x32_bf16 v[50:53], v[198:201], v[206:209], v[50:53]
	v_mfma_f32_16x16x32_bf16 v[38:41], v[190:193], v[214:217], v[38:41]
	v_mfma_f32_16x16x32_bf16 v[34:37], v[198:201], v[214:217], v[34:37]
	v_mfma_f32_16x16x32_bf16 v[22:25], v[190:193], v[222:225], v[22:25]
	v_mfma_f32_16x16x32_bf16 v[18:21], v[198:201], v[222:225], v[18:21]
	v_mfma_f32_16x16x32_bf16 v[6:9], v[190:193], v[230:233], v[6:9]
	v_mfma_f32_16x16x32_bf16 v[2:5], v[198:201], v[230:233], v[2:5]
	v_mfma_f32_16x16x32_bf16 v[54:57], v[194:197], v[210:213], v[54:57]
	v_mfma_f32_16x16x32_bf16 v[50:53], v[202:205], v[210:213], v[50:53]
	v_mfma_f32_16x16x32_bf16 v[38:41], v[194:197], v[218:221], v[38:41]
	v_mfma_f32_16x16x32_bf16 v[34:37], v[202:205], v[218:221], v[34:37]
	v_mfma_f32_16x16x32_bf16 v[22:25], v[194:197], v[226:229], v[22:25]
	v_mfma_f32_16x16x32_bf16 v[18:21], v[202:205], v[226:229], v[18:21]
	v_mfma_f32_16x16x32_bf16 v[6:9], v[194:197], v[234:237], v[6:9]
	v_mfma_f32_16x16x32_bf16 v[2:5], v[202:205], v[234:237], v[2:5]
	s_waitcnt vmcnt(8)
	s_barrier
; #define PG8_STAGE(bufoff, gbase, voff) do { _Pragma("unroll") for (int _i = 0; _i < 2; ++_i) \
;         __builtin_amdgcn_global_load_lds((const unsigned*)((const char*)(gbase) + (voff)[_i]), (PG8_LAS unsigned*)(lds + (bufoff) + ldsw + _i * 8192), 16, 0, 0); } while (0)
; #define PG8_LDA(dst, b, h) do { _Pragma("unroll") for (int m = 0; m < 4; ++m) _Pragma("unroll") for (int k = 0; k < 2; ++k) dst[m][k] = *(const PG8_LAS bf16x8*)(lds + PG8_SA(b, h) + aoff + m * 2048 + k * 1024); } while (0)
; #define PG8_LDB(dst, b, h) do { _Pragma("unroll") for (int n = 0; n < 2; ++n) _Pragma("unroll") for (int k = 0; k < 2; ++k) dst[n][k] = *(const PG8_LAS bf16x8*)(lds + PG8_SB(b, h) + boff + n * 2048 + k * 1024); } while (0)
; template <class Epi, class Sched, bool ALIGN_EPI = false, bool SP2 = false>
; __device__ __forceinline__ void gemm_phase(PG8_LAS unsigned char* lds, const Gemm g, const Sched& S, const Epi& E) {
;     ...
;         for (int t = 0; t < nt; t += 2) {
;             const bool last = (t == nt - 2);
;             const char* a1 = cA + (size_t)(t + 1) * kstep;
;             const char* a2 = last ? nA : cA + (size_t)(t + 2) * kstep; const char* b2 = last ? nB : cB + (size_t)(t + 2) * kstep;
;             const char* a3 = a2 + kstep; const char* b3 = b2 + kstep;
;             if (last && has_next) S.a_ready(nxt);
;             if constexpr (SP2) {
;             PG8_LDB(B0, 0, 0); PG8_LDB(B1, 0, 1); PG8_SCHED; PG8_LDA(At, 0, 0); PG8_STAGE(PG8_SA(1, 1), a1 + hstep, voffA);
;             PG8_WAIT_V(8); PG8_WAIT_L(0); PG8_BAR; PG8_MMA(0, 0, At, B0); PG8_MMA(0, 1, At, B1); PG8_BAR; PG8_SCHED;
;             PG8_LDA(At, 0, 1); PG8_STAGE(PG8_SB(0, 0), b2, voffB); PG8_STAGE(PG8_SB(0, 1), b2 + hstep, voffB); PG8_STAGE(PG8_SA(0, 0), a2, voffA);
;             PG8_WAIT_V(8); PG8_WAIT_L(0); PG8_BAR; PG8_MMA(1, 0, At, B0); PG8_MMA(1, 1, At, B1); PG8_BAR; PG8_SCHED;
;             PG8_LDB(B0, 1, 0); PG8_LDB(B1, 1, 1); PG8_SCHED; PG8_LDA(At, 1, 0); PG8_STAGE(PG8_SA(0, 1), a2 + hstep, voffA);
;             PG8_WAIT_V(8); PG8_WAIT_L(0); PG8_BAR; PG8_MMA(0, 0, At, B0); PG8_MMA(0, 1, At, B1); PG8_BAR; PG8_SCHED;
;             PG8_LDA(At, 1, 1); PG8_STAGE(PG8_SB(1, 0), b3, voffB); PG8_STAGE(PG8_SB(1, 1), b3 + hstep, voffB); PG8_STAGE(PG8_SA(1, 0), a3, voffA);
;             PG8_WAIT_V(8); PG8_WAIT_L(0); PG8_BAR; PG8_MMA(1, 0, At, B0); PG8_MMA(1, 1, At, B1); PG8_BAR; PG8_SCHED;
	ds_read_b128 v[190:193], v180
	ds_read_b128 v[194:197], v180 offset:1024
	ds_read_b128 v[198:201], v180 offset:2048
	ds_read_b128 v[202:205], v180 offset:3072
	ds_read_b128 v[206:209], v182
	ds_read_b128 v[210:213], v182 offset:1024
	ds_read_b128 v[214:217], v182 offset:2048
	ds_read_b128 v[218:221], v182 offset:3072
	ds_read_b128 v[222:225], v182 offset:4096
	ds_read_b128 v[226:229], v182 offset:5120
	ds_read_b128 v[230:233], v182 offset:6144
	ds_read_b128 v[234:237], v182 offset:7168
	s_add_u32 s34, s34, 0x80
	s_addc_u32 s35, s35, 0
	s_add_u32 s38, s38, 0x80
	s_addc_u32 s39, s39, 0
	s_add_i32 m0, s42, 0xc000
	s_nop 0
	global_load_lds_dwordx4 v140, s[34:35]
	s_add_i32 m0, s42, 0xe000
	s_nop 0
	global_load_lds_dwordx4 v144, s[34:35]
	s_add_i32 m0, s42, 0x1c000
	s_nop 0
	global_load_lds_dwordx4 v142, s[38:39]
	s_add_i32 m0, s42, 0x1e000
	s_nop 0
	global_load_lds_dwordx4 v146, s[38:39]
	s_waitcnt lgkmcnt(0)
	v_mfma_f32_16x16x32_bf16 v[54:57], v[190:193], v[206:209], v[54:57]
	v_mfma_f32_16x16x32_bf16 v[50:53], v[198:201], v[206:209], v[50:53]
	v_mfma_f32_16x16x32_bf16 v[38:41], v[190:193], v[214:217], v[38:41]
	v_mfma_f32_16x16x32_bf16 v[34:37], v[198:201], v[214:217], v[34:37]
	v_mfma_f32_16x16x32_bf16 v[22:25], v[190:193], v[222:225], v[22:25]
	v_mfma_f32_16x16x32_bf16 v[18:21], v[198:201], v[222:225], v[18:21]
	v_mfma_f32_16x16x32_bf16 v[6:9], v[190:193], v[230:233], v[6:9]
	v_mfma_f32_16x16x32_bf16 v[2:5], v[198:201], v[230:233], v[2:5]
	v_mfma_f32_16x16x32_bf16 v[54:57], v[194:197], v[210:213], v[54:57]
	v_mfma_f32_16x16x32_bf16 v[50:53], v[202:205], v[210:213], v[50:53]
	v_mfma_f32_16x16x32_bf16 v[38:41], v[194:197], v[218:221], v[38:41]
	v_mfma_f32_16x16x32_bf16 v[34:37], v[202:205], v[218:221], v[34:37]
	v_mfma_f32_16x16x32_bf16 v[22:25], v[194:197], v[226:229], v[22:25]
	v_mfma_f32_16x16x32_bf16 v[18:21], v[202:205], v[226:229], v[18:21]
	v_mfma_f32_16x16x32_bf16 v[6:9], v[194:197], v[234:237], v[6:9]
	v_mfma_f32_16x16x32_bf16 v[2:5], v[202:205], v[234:237], v[2:5]
	s_waitcnt vmcnt(8)
	s_barrier
	ds_read_b128 v[190:193], v183
	ds_read_b128 v[194:197], v183 offset:1024
	ds_read_b128 v[198:201], v183 offset:2048
	ds_read_b128 v[202:205], v183 offset:3072
	ds_read_b128 v[206:209], v182 offset:32768
	ds_read_b128 v[210:213], v182 offset:33792
	ds_read_b128 v[214:217], v182 offset:34816
	ds_read_b128 v[218:221], v182 offset:35840
	ds_read_b128 v[222:225], v182 offset:36864
	ds_read_b128 v[226:229], v182 offset:37888
	ds_read_b128 v[230:233], v182 offset:38912
	ds_read_b128 v[234:237], v182 offset:39936
	s_add_u32 s34, s34, 0x80
	s_addc_u32 s35, s35, 0
	s_add_u32 s38, s38, 0x80
	s_addc_u32 s39, s39, 0
	s_mov_b32 m0, s42
	s_nop 0
	global_load_lds_dwordx4 v140, s[34:35]
	s_add_i32 m0, s42, 0x2000
	s_nop 0
	global_load_lds_dwordx4 v144, s[34:35]
	s_add_i32 m0, s42, 0x10000
	s_nop 0
	global_load_lds_dwordx4 v142, s[38:39]
	s_add_i32 m0, s42, 0x12000
	s_nop 0
	global_load_lds_dwordx4 v146, s[38:39]
	s_waitcnt lgkmcnt(0)
	v_mfma_f32_16x16x32_bf16 v[54:57], v[190:193], v[206:209], v[54:57]
	v_mfma_f32_16x16x32_bf16 v[50:53], v[198:201], v[206:209], v[50:53]
	v_mfma_f32_16x16x32_bf16 v[38:41], v[190:193], v[214:217], v[38:41]
	v_mfma_f32_16x16x32_bf16 v[34:37], v[198:201], v[214:217], v[34:37]
	v_mfma_f32_16x16x32_bf16 v[22:25], v[190:193], v[222:225], v[22:25]
	v_mfma_f32_16x16x32_bf16 v[18:21], v[198:201], v[222:225], v[18:21]
	v_mfma_f32_16x16x32_bf16 v[6:9], v[190:193], v[230:233], v[6:9]
	v_mfma_f32_16x16x32_bf16 v[2:5], v[198:201], v[230:233], v[2:5]
	v_mfma_f32_16x16x32_bf16 v[54:57], v[194:197], v[210:213], v[54:57]
	v_mfma_f32_16x16x32_bf16 v[50:53], v[202:205], v[210:213], v[50:53]
	v_mfma_f32_16x16x32_bf16 v[38:41], v[194:197], v[218:221], v[38:41]
	v_mfma_f32_16x16x32_bf16 v[34:37], v[202:205], v[218:221], v[34:37]
	v_mfma_f32_16x16x32_bf16 v[22:25], v[194:197], v[226:229], v[22:25]
	v_mfma_f32_16x16x32_bf16 v[18:21], v[202:205], v[226:229], v[18:21]
	v_mfma_f32_16x16x32_bf16 v[6:9], v[194:197], v[234:237], v[6:9]
	v_mfma_f32_16x16x32_bf16 v[2:5], v[202:205], v[234:237], v[2:5]
	s_waitcnt vmcnt(8)
	s_barrier
	ds_read_b128 v[190:193], v181
	ds_read_b128 v[194:197], v181 offset:1024
	ds_read_b128 v[198:201], v181 offset:2048
	ds_read_b128 v[202:205], v181 offset:3072
	ds_read_b128 v[206:209], v182 offset:16384
	ds_read_b128 v[210:213], v182 offset:17408
	ds_read_b128 v[214:217], v182 offset:18432
	ds_read_b128 v[218:221], v182 offset:19456
	ds_read_b128 v[222:225], v182 offset:20480
	ds_read_b128 v[226:229], v182 offset:21504
	ds_read_b128 v[230:233], v182 offset:22528
	ds_read_b128 v[234:237], v182 offset:23552
	s_add_u32 s34, s34, 0x80
	s_addc_u32 s35, s35, 0
	s_add_u32 s38, s38, 0x80
	s_addc_u32 s39, s39, 0
	s_add_i32 m0, s42, 0x8000
	s_nop 0
	global_load_lds_dwordx4 v140, s[34:35]
	s_add_i32 m0, s42, 0xa000
	s_nop 0
	global_load_lds_dwordx4 v144, s[34:35]
	s_add_i32 m0, s42, 0x18000
	s_nop 0
	global_load_lds_dwordx4 v142, s[38:39]
	s_add_i32 m0, s42, 0x1a000
	s_nop 0
	global_load_lds_dwordx4 v146, s[38:39]
	s_waitcnt lgkmcnt(0)
	v_mfma_f32_16x16x32_bf16 v[54:57], v[190:193], v[206:209], v[54:57]
	v_mfma_f32_16x16x32_bf16 v[50:53], v[198:201], v[206:209], v[50:53]
	v_mfma_f32_16x16x32_bf16 v[38:41], v[190:193], v[214:217], v[38:41]
	v_mfma_f32_16x16x32_bf16 v[34:37], v[198:201], v[214:217], v[34:37]
	v_mfma_f32_16x16x32_bf16 v[22:25], v[190:193], v[222:225], v[22:25]
	v_mfma_f32_16x16x32_bf16 v[18:21], v[198:201], v[222:225], v[18:21]
	v_mfma_f32_16x16x32_bf16 v[6:9], v[190:193], v[230:233], v[6:9]
	v_mfma_f32_16x16x32_bf16 v[2:5], v[198:201], v[230:233], v[2:5]
	v_mfma_f32_16x16x32_bf16 v[54:57], v[194:197], v[210:213], v[54:57]
	v_mfma_f32_16x16x32_bf16 v[50:53], v[202:205], v[210:213], v[50:53]
	v_mfma_f32_16x16x32_bf16 v[38:41], v[194:197], v[218:221], v[38:41]
	v_mfma_f32_16x16x32_bf16 v[34:37], v[202:205], v[218:221], v[34:37]
	v_mfma_f32_16x16x32_bf16 v[22:25], v[194:197], v[226:229], v[22:25]
	v_mfma_f32_16x16x32_bf16 v[18:21], v[202:205], v[226:229], v[18:21]
	v_mfma_f32_16x16x32_bf16 v[6:9], v[194:197], v[234:237], v[6:9]
	v_mfma_f32_16x16x32_bf16 v[2:5], v[202:205], v[234:237], v[2:5]
	s_waitcnt vmcnt(8)
	s_barrier
; #define PG8_STAGE(bufoff, gbase, voff) do { _Pragma("unroll") for (int _i = 0; _i < 2; ++_i) \
;         __builtin_amdgcn_global_load_lds((const unsigned*)((const char*)(gbase) + (voff)[_i]), (PG8_LAS unsigned*)(lds + (bufoff) + ldsw + _i * 8192), 16, 0, 0); } while (0)
; #define PG8_LDA(dst, b, h) do { _Pragma("unroll") for (int m = 0; m < 4; ++m) _Pragma("unroll") for (int k = 0; k < 2; ++k) dst[m][k] = *(const PG8_LAS bf16x8*)(lds + PG8_SA(b, h) + aoff + m * 2048 + k * 1024); } while (0)
; #define PG8_LDB(dst, b, h) do { _Pragma("unroll") for (int n = 0; n < 2; ++n) _Pragma("unroll") for (int k = 0; k < 2; ++k) dst[n][k] = *(const PG8_LAS bf16x8*)(lds + PG8_SB(b, h) + boff + n * 2048 + k * 1024); } while (0)
; template <class Epi, class Sched, bool ALIGN_EPI = false, bool SP2 = false>
; __device__ __forceinline__ void gemm_phase(PG8_LAS unsigned char* lds, const Gemm g, const Sched& S, const Epi& E) {
;     ...
;         for (int t = 0; t < nt; t += 2) {
;             const bool last = (t == nt - 2);
;             const char* a1 = cA + (size_t)(t + 1) * kstep;
;             const char* a2 = last ? nA : cA + (size_t)(t + 2) * kstep; const char* b2 = last ? nB : cB + (size_t)(t + 2) * kstep;
;             const char* a3 = a2 + kstep; const char* b3 = b2 + kstep;
;             if (last && has_next) S.a_ready(nxt);
;             if constexpr (SP2) {
;             PG8_LDB(B0, 0, 0); PG8_LDB(B1, 0, 1); PG8_SCHED; PG8_LDA(At, 0, 0); PG8_STAGE(PG8_SA(1, 1), a1 + hstep, voffA);
;             PG8_WAIT_V(8); PG8_WAIT_L(0); PG8_BAR; PG8_MMA(0, 0, At, B0); PG8_MMA(0, 1, At, B1); PG8_BAR; PG8_SCHED;
;             PG8_LDA(At, 0, 1); PG8_STAGE(PG8_SB(0, 0), b2, voffB); PG8_STAGE(PG8_SB(0, 1), b2 + hstep, voffB); PG8_STAGE(PG8_SA(0, 0), a2, voffA);
;             PG8_WAIT_V(8); PG8_WAIT_L(0); PG8_BAR; PG8_MMA(1, 0, At, B0); PG8_MMA(1, 1, At, B1); PG8_BAR; PG8_SCHED;
;             PG8_LDB(B0, 1, 0); PG8_LDB(B1, 1, 1); PG8_SCHED; PG8_LDA(At, 1, 0); PG8_STAGE(PG8_SA(0, 1), a2 + hstep, voffA);
;             PG8_WAIT_V(8); PG8_WAIT_L(0); PG8_BAR; PG8_MMA(0, 0, At, B0); PG8_MMA(0, 1, At, B1); PG8_BAR; PG8_SCHED;
;             PG8_LDA(At, 1, 1); PG8_STAGE(PG8_SB(1, 0), b3, voffB); PG8_STAGE(PG8_SB(1, 1), b3 + hstep, voffB); PG8_STAGE(PG8_SA(1, 0), a3, voffA);
;             PG8_WAIT_V(8); PG8_WAIT_L(0); PG8_BAR; PG8_MMA(1, 0, At, B0); PG8_MMA(1, 1, At, B1); PG8_BAR; PG8_SCHED;
	ds_read_b128 v[190:193], v184
	ds_read_b128 v[194:197], v184 offset:1024
	ds_read_b128 v[198:201], v184 offset:2048
	ds_read_b128 v[202:205], v184 offset:3072
	ds_read_b128 v[206:209], v182 offset:49152
	ds_read_b128 v[210:213], v182 offset:50176
	ds_read_b128 v[214:217], v182 offset:51200
	ds_read_b128 v[218:221], v182 offset:52224
	ds_read_b128 v[222:225], v182 offset:53248
	ds_read_b128 v[226:229], v182 offset:54272
	ds_read_b128 v[230:233], v182 offset:55296
	ds_read_b128 v[234:237], v182 offset:56320
	s_waitcnt lgkmcnt(0)
	v_mfma_f32_16x16x32_bf16 v[54:57], v[190:193], v[206:209], v[54:57]
	v_mfma_f32_16x16x32_bf16 v[50:53], v[198:201], v[206:209], v[50:53]
	v_mfma_f32_16x16x32_bf16 v[38:41], v[190:193], v[214:217], v[38:41]
	v_mfma_f32_16x16x32_bf16 v[34:37], v[198:201], v[214:217], v[34:37]
	v_mfma_f32_16x16x32_bf16 v[22:25], v[190:193], v[222:225], v[22:25]
	v_mfma_f32_16x16x32_bf16 v[18:21], v[198:201], v[222:225], v[18:21]
	v_mfma_f32_16x16x32_bf16 v[6:9], v[190:193], v[230:233], v[6:9]
	v_mfma_f32_16x16x32_bf16 v[2:5], v[198:201], v[230:233], v[2:5]
	v_mfma_f32_16x16x32_bf16 v[54:57], v[194:197], v[210:213], v[54:57]
	v_mfma_f32_16x16x32_bf16 v[50:53], v[202:205], v[210:213], v[50:53]
	v_mfma_f32_16x16x32_bf16 v[38:41], v[194:197], v[218:221], v[38:41]
	v_mfma_f32_16x16x32_bf16 v[34:37], v[202:205], v[218:221], v[34:37]
	v_mfma_f32_16x16x32_bf16 v[22:25], v[194:197], v[226:229], v[22:25]
	v_mfma_f32_16x16x32_bf16 v[18:21], v[202:205], v[226:229], v[18:21]
	v_mfma_f32_16x16x32_bf16 v[6:9], v[194:197], v[234:237], v[6:9]
	v_mfma_f32_16x16x32_bf16 v[2:5], v[202:205], v[234:237], v[2:5]
	s_waitcnt vmcnt(4)
	s_barrier
	ds_read_b128 v[190:193], v180
	ds_read_b128 v[194:197], v180 offset:1024
	ds_read_b128 v[198:201], v180 offset:2048
	ds_read_b128 v[202:205], v180 offset:3072
	ds_read_b128 v[206:209], v182
	ds_read_b128 v[210:213], v182 offset:1024
	ds_read_b128 v[214:217], v182 offset:2048
	ds_read_b128 v[218:221], v182 offset:3072
	ds_read_b128 v[222:225], v182 offset:4096
	ds_read_b128 v[226:229], v182 offset:5120
	ds_read_b128 v[230:233], v182 offset:6144
	ds_read_b128 v[234:237], v182 offset:7168
	s_waitcnt lgkmcnt(0)
	v_mfma_f32_16x16x32_bf16 v[54:57], v[190:193], v[206:209], v[54:57]
	v_mfma_f32_16x16x32_bf16 v[50:53], v[198:201], v[206:209], v[50:53]
	v_mfma_f32_16x16x32_bf16 v[38:41], v[190:193], v[214:217], v[38:41]
	v_mfma_f32_16x16x32_bf16 v[34:37], v[198:201], v[214:217], v[34:37]
	v_mfma_f32_16x16x32_bf16 v[22:25], v[190:193], v[222:225], v[22:25]
	v_mfma_f32_16x16x32_bf16 v[18:21], v[198:201], v[222:225], v[18:21]
	v_mfma_f32_16x16x32_bf16 v[6:9], v[190:193], v[230:233], v[6:9]
	v_mfma_f32_16x16x32_bf16 v[2:5], v[198:201], v[230:233], v[2:5]
	v_mfma_f32_16x16x32_bf16 v[54:57], v[194:197], v[210:213], v[54:57]
	v_mfma_f32_16x16x32_bf16 v[50:53], v[202:205], v[210:213], v[50:53]
	v_mfma_f32_16x16x32_bf16 v[38:41], v[194:197], v[218:221], v[38:41]
	v_mfma_f32_16x16x32_bf16 v[34:37], v[202:205], v[218:221], v[34:37]
	v_mfma_f32_16x16x32_bf16 v[22:25], v[194:197], v[226:229], v[22:25]
	v_mfma_f32_16x16x32_bf16 v[18:21], v[202:205], v[226:229], v[18:21]
	v_mfma_f32_16x16x32_bf16 v[6:9], v[194:197], v[234:237], v[6:9]
	v_mfma_f32_16x16x32_bf16 v[2:5], v[202:205], v[234:237], v[2:5]
	s_waitcnt vmcnt(0)
	s_barrier
	ds_read_b128 v[190:193], v183
	ds_read_b128 v[194:197], v183 offset:1024
	ds_read_b128 v[198:201], v183 offset:2048
	ds_read_b128 v[202:205], v183 offset:3072
	ds_read_b128 v[206:209], v182 offset:32768
	ds_read_b128 v[210:213], v182 offset:33792
	ds_read_b128 v[214:217], v182 offset:34816
	ds_read_b128 v[218:221], v182 offset:35840
	ds_read_b128 v[222:225], v182 offset:36864
	ds_read_b128 v[226:229], v182 offset:37888
	ds_read_b128 v[230:233], v182 offset:38912
	ds_read_b128 v[234:237], v182 offset:39936
	s_waitcnt lgkmcnt(0)
	v_mfma_f32_16x16x32_bf16 v[54:57], v[190:193], v[206:209], v[54:57]
	v_mfma_f32_16x16x32_bf16 v[50:53], v[198:201], v[206:209], v[50:53]
	v_mfma_f32_16x16x32_bf16 v[38:41], v[190:193], v[214:217], v[38:41]
	v_mfma_f32_16x16x32_bf16 v[34:37], v[198:201], v[214:217], v[34:37]
	v_mfma_f32_16x16x32_bf16 v[22:25], v[190:193], v[222:225], v[22:25]
	v_mfma_f32_16x16x32_bf16 v[18:21], v[198:201], v[222:225], v[18:21]
	v_mfma_f32_16x16x32_bf16 v[6:9], v[190:193], v[230:233], v[6:9]
	v_mfma_f32_16x16x32_bf16 v[2:5], v[198:201], v[230:233], v[2:5]
	v_mfma_f32_16x16x32_bf16 v[54:57], v[194:197], v[210:213], v[54:57]
	v_mfma_f32_16x16x32_bf16 v[50:53], v[202:205], v[210:213], v[50:53]
	v_mfma_f32_16x16x32_bf16 v[38:41], v[194:197], v[218:221], v[38:41]
	v_mfma_f32_16x16x32_bf16 v[34:37], v[202:205], v[218:221], v[34:37]
	v_mfma_f32_16x16x32_bf16 v[22:25], v[194:197], v[226:229], v[22:25]
	v_mfma_f32_16x16x32_bf16 v[18:21], v[202:205], v[226:229], v[18:21]
	v_mfma_f32_16x16x32_bf16 v[6:9], v[194:197], v[234:237], v[6:9]
	v_mfma_f32_16x16x32_bf16 v[2:5], v[202:205], v[234:237], v[2:5]
	s_branch .LBB0_141
